# removed all s_setprio flips from the 12 GEMM K-loops (A/B: faster without, static per-half raise slower)
# speedup vs baseline: 1.0067x; 1.0025x over previous
; #define PG8_STAGE(bufoff, gbase, voff) do { _Pragma("unroll") for (int _i = 0; _i < 2; ++_i) \
;         __builtin_amdgcn_global_load_lds((const unsigned*)((const char*)(gbase) + (voff)[_i]), (PG8_LAS unsigned*)(lds + (bufoff) + ldsw + _i * 8192), 16, 0, 0); } while (0)
; #define PG8_LDA(dst, b, h) do { _Pragma("unroll") for (int m = 0; m < 4; ++m) _Pragma("unroll") for (int k = 0; k < 2; ++k) dst[m][k] = *(const PG8_LAS bf16x8*)(lds + PG8_SA(b, h) + aoff + m * 2048 + k * 1024); } while (0)
; #define PG8_LDB(dst, b, h) do { _Pragma("unroll") for (int n = 0; n < 2; ++n) _Pragma("unroll") for (int k = 0; k < 2; ++k) dst[n][k] = *(const PG8_LAS bf16x8*)(lds + PG8_SB(b, h) + boff + n * 2048 + k * 1024); } while (0)
; #define PG8_MMA(ai, bj, At, Bt) do { __builtin_amdgcn_s_setprio(1); _Pragma("unroll") for (int m = 0; m < 4; ++m) _Pragma("unroll") for (int n = 0; n < 2; ++n) _Pragma("unroll") for (int k = 0; k < 2; ++k) \
;         acc[ai][bj][m][n] = __builtin_amdgcn_mfma_f32_16x16x32_bf16(Bt[n][k], At[m][k], acc[ai][bj][m][n], 0, 0, 0); __builtin_amdgcn_s_setprio(0); } while (0)
; #define PG8_WAIT_V(n) asm volatile("s_waitcnt vmcnt(" #n ")" ::: "memory")
; #define PG8_WAIT_L(n) asm volatile("s_waitcnt lgkmcnt(" #n ")" ::: "memory")
; template <class Epi, class Sched, bool ALIGN_EPI = false, bool SP2 = false>
; __device__ __forceinline__ void gemm_phase(PG8_LAS unsigned char* lds, const Gemm g, const Sched& S, const Epi& E) {
;     ...
;             const bool last = (t == nt - 2);
;             const char* a1 = cA + (size_t)(t + 1) * kstep;
;             const char* a2 = last ? nA : cA + (size_t)(t + 2) * kstep; const char* b2 = last ? nB : cB + (size_t)(t + 2) * kstep;
;             const char* a3 = a2 + kstep; const char* b3 = b2 + kstep;
;             if (last && has_next) S.a_ready(nxt);
;             if constexpr (SP2) {
;             PG8_LDB(B0, 0, 0); PG8_LDB(B1, 0, 1); PG8_SCHED; PG8_LDA(At, 0, 0); PG8_STAGE(PG8_SA(1, 1), a1 + hstep, voffA);
;             PG8_WAIT_V(8); PG8_WAIT_L(0); PG8_BAR; PG8_MMA(0, 0, At, B0); PG8_MMA(0, 1, At, B1); PG8_BAR; PG8_SCHED;
;             PG8_LDA(At, 0, 1); PG8_STAGE(PG8_SB(0, 0), b2, voffB); PG8_STAGE(PG8_SB(0, 1), b2 + hstep, voffB); PG8_STAGE(PG8_SA(0, 0), a2, voffA);
;             PG8_WAIT_V(8); PG8_WAIT_L(0); PG8_BAR; PG8_MMA(1, 0, At, B0); PG8_MMA(1, 1, At, B1); PG8_BAR; PG8_SCHED;
.LBB0_163:
	ds_read_b128 v[128:131], v188
	ds_read_b128 v[132:135], v189
	ds_read_b128 v[136:139], v190
	ds_read_b128 v[140:143], v191
	ds_read_b128 v[144:147], v192
	ds_read_b128 v[148:151], v193
	ds_read_b128 v[172:175], v194
	ds_read_b128 v[176:179], v195
	s_add_u32 s44, s42, 0xfffc0080
	s_addc_u32 s45, s43, -1
	s_cmp_eq_u32 s74, 12
	s_cselect_b32 s47, s9, s45
	s_cselect_b32 s46, s11, s44
	s_cselect_b32 s45, s29, s73
	s_cselect_b32 s44, s31, s72
	s_mov_b32 m0, s68
	v_lshl_add_u64 v[236:237], s[42:43], 0, v[166:167]
	ds_read_b128 v[180:183], v186
	ds_read_b128 v[208:211], v186 offset:1024
	ds_read_b128 v[212:215], v186 offset:2048
	ds_read_b128 v[216:219], v186 offset:3072
	ds_read_b128 v[220:223], v186 offset:4096
	ds_read_b128 v[224:227], v186 offset:5120
	ds_read_b128 v[228:231], v186 offset:6144
	ds_read_b128 v[232:235], v186 offset:7168
	global_load_lds_dwordx4 v[236:237], off
	v_lshl_add_u64 v[236:237], s[42:43], 0, v[164:165]
	s_mov_b32 m0, s69
	s_nop 0
	global_load_lds_dwordx4 v[236:237], off
	s_waitcnt vmcnt(8)
	s_waitcnt lgkmcnt(0)
	s_barrier
	s_waitcnt lgkmcnt(0)
	v_mfma_f32_16x16x32_bf16 v[124:127], v[128:131], v[180:183], v[124:127]
	v_mfma_f32_16x16x32_bf16 v[120:123], v[136:139], v[180:183], v[120:123]
	v_mfma_f32_16x16x32_bf16 v[108:111], v[128:131], v[212:215], v[108:111]
	v_mfma_f32_16x16x32_bf16 v[104:107], v[136:139], v[212:215], v[104:107]
	v_mfma_f32_16x16x32_bf16 v[92:95], v[128:131], v[220:223], v[92:95]
	v_mfma_f32_16x16x32_bf16 v[88:91], v[136:139], v[220:223], v[88:91]
	v_mfma_f32_16x16x32_bf16 v[76:79], v[128:131], v[228:231], v[76:79]
	v_mfma_f32_16x16x32_bf16 v[72:75], v[136:139], v[228:231], v[72:75]
	v_mfma_f32_16x16x32_bf16 v[124:127], v[132:135], v[208:211], v[124:127]
	v_mfma_f32_16x16x32_bf16 v[120:123], v[140:143], v[208:211], v[120:123]
	v_mfma_f32_16x16x32_bf16 v[108:111], v[132:135], v[216:219], v[108:111]
	v_mfma_f32_16x16x32_bf16 v[104:107], v[140:143], v[216:219], v[104:107]
	v_mfma_f32_16x16x32_bf16 v[92:95], v[132:135], v[224:227], v[92:95]
	v_mfma_f32_16x16x32_bf16 v[88:91], v[140:143], v[224:227], v[88:91]
	v_mfma_f32_16x16x32_bf16 v[76:79], v[132:135], v[232:235], v[76:79]
	v_mfma_f32_16x16x32_bf16 v[72:75], v[140:143], v[232:235], v[72:75]
	v_mfma_f32_16x16x32_bf16 v[116:119], v[144:147], v[180:183], v[116:119]
	v_mfma_f32_16x16x32_bf16 v[112:115], v[172:175], v[180:183], v[112:115]
	v_mfma_f32_16x16x32_bf16 v[100:103], v[144:147], v[212:215], v[100:103]
	v_mfma_f32_16x16x32_bf16 v[96:99], v[172:175], v[212:215], v[96:99]
	v_mfma_f32_16x16x32_bf16 v[84:87], v[144:147], v[220:223], v[84:87]
	v_mfma_f32_16x16x32_bf16 v[80:83], v[172:175], v[220:223], v[80:83]
	v_mfma_f32_16x16x32_bf16 v[68:71], v[144:147], v[228:231], v[68:71]
	v_mfma_f32_16x16x32_bf16 v[64:67], v[172:175], v[228:231], v[64:67]
	v_mfma_f32_16x16x32_bf16 v[116:119], v[148:151], v[208:211], v[116:119]
	v_mfma_f32_16x16x32_bf16 v[112:115], v[176:179], v[208:211], v[112:115]
	v_mfma_f32_16x16x32_bf16 v[100:103], v[148:151], v[216:219], v[100:103]
	v_mfma_f32_16x16x32_bf16 v[96:99], v[176:179], v[216:219], v[96:99]
	v_mfma_f32_16x16x32_bf16 v[84:87], v[148:151], v[224:227], v[84:87]
	v_mfma_f32_16x16x32_bf16 v[80:83], v[176:179], v[224:227], v[80:83]
	v_mfma_f32_16x16x32_bf16 v[68:71], v[148:151], v[232:235], v[68:71]
	v_mfma_f32_16x16x32_bf16 v[64:67], v[176:179], v[232:235], v[64:67]
	s_barrier
	s_mov_b32 m0, s51
	v_lshl_add_u64 v[236:237], s[44:45], 0, v[154:155]
	s_add_u32 s76, s44, 0x40000
	ds_read_b128 v[180:183], v186 offset:16384
	ds_read_b128 v[208:211], v186 offset:17408
	ds_read_b128 v[212:215], v186 offset:18432
	ds_read_b128 v[216:219], v186 offset:19456
	ds_read_b128 v[220:223], v186 offset:20480
	ds_read_b128 v[224:227], v186 offset:21504
	ds_read_b128 v[228:231], v186 offset:22528
	ds_read_b128 v[232:235], v186 offset:23552
	global_load_lds_dwordx4 v[236:237], off
	v_lshl_add_u64 v[238:239], s[44:45], 0, v[158:159]
	s_mov_b32 m0, s52
	s_addc_u32 s77, s45, 0
	global_load_lds_dwordx4 v[238:239], off
	v_lshl_add_u64 v[240:241], s[76:77], 0, v[154:155]
	s_mov_b32 m0, s53
	v_lshl_add_u64 v[242:243], s[46:47], 0, v[156:157]
	global_load_lds_dwordx4 v[240:241], off
	v_lshl_add_u64 v[240:241], s[76:77], 0, v[158:159]
	s_mov_b32 m0, s54
	s_nop 0
	global_load_lds_dwordx4 v[240:241], off
	v_lshl_add_u64 v[240:241], s[46:47], 0, v[152:153]
	s_mov_b32 m0, s50
	s_nop 0
	global_load_lds_dwordx4 v[240:241], off
	s_mov_b32 m0, s55
	s_nop 0
	global_load_lds_dwordx4 v[242:243], off
	s_waitcnt vmcnt(8)
	s_waitcnt lgkmcnt(0)
	s_barrier
	s_waitcnt lgkmcnt(0)
	v_mfma_f32_16x16x32_bf16 v[60:63], v[128:131], v[180:183], v[60:63]
	v_mfma_f32_16x16x32_bf16 v[56:59], v[136:139], v[180:183], v[56:59]
	v_mfma_f32_16x16x32_bf16 v[44:47], v[128:131], v[212:215], v[44:47]
	v_mfma_f32_16x16x32_bf16 v[40:43], v[136:139], v[212:215], v[40:43]
	v_mfma_f32_16x16x32_bf16 v[28:31], v[128:131], v[220:223], v[28:31]
	v_mfma_f32_16x16x32_bf16 v[24:27], v[136:139], v[220:223], v[24:27]
	v_mfma_f32_16x16x32_bf16 v[12:15], v[128:131], v[228:231], v[12:15]
	v_mfma_f32_16x16x32_bf16 v[8:11], v[136:139], v[228:231], v[8:11]
	v_mfma_f32_16x16x32_bf16 v[60:63], v[132:135], v[208:211], v[60:63]
	v_mfma_f32_16x16x32_bf16 v[56:59], v[140:143], v[208:211], v[56:59]
	v_mfma_f32_16x16x32_bf16 v[44:47], v[132:135], v[216:219], v[44:47]
	v_mfma_f32_16x16x32_bf16 v[40:43], v[140:143], v[216:219], v[40:43]
	v_mfma_f32_16x16x32_bf16 v[28:31], v[132:135], v[224:227], v[28:31]
	v_mfma_f32_16x16x32_bf16 v[24:27], v[140:143], v[224:227], v[24:27]
	v_mfma_f32_16x16x32_bf16 v[12:15], v[132:135], v[232:235], v[12:15]
	v_mfma_f32_16x16x32_bf16 v[8:11], v[140:143], v[232:235], v[8:11]
	v_mfma_f32_16x16x32_bf16 v[52:55], v[144:147], v[180:183], v[52:55]
	v_mfma_f32_16x16x32_bf16 v[48:51], v[172:175], v[180:183], v[48:51]
	v_mfma_f32_16x16x32_bf16 v[36:39], v[144:147], v[212:215], v[36:39]
	v_mfma_f32_16x16x32_bf16 v[32:35], v[172:175], v[212:215], v[32:35]
	v_mfma_f32_16x16x32_bf16 v[20:23], v[144:147], v[220:223], v[20:23]
	v_mfma_f32_16x16x32_bf16 v[16:19], v[172:175], v[220:223], v[16:19]
	v_mfma_f32_16x16x32_bf16 v[4:7], v[144:147], v[228:231], v[4:7]
	v_mfma_f32_16x16x32_bf16 v[0:3], v[172:175], v[228:231], v[0:3]
	v_mfma_f32_16x16x32_bf16 v[52:55], v[148:151], v[208:211], v[52:55]
	v_mfma_f32_16x16x32_bf16 v[48:51], v[176:179], v[208:211], v[48:51]
	v_mfma_f32_16x16x32_bf16 v[36:39], v[148:151], v[216:219], v[36:39]
	v_mfma_f32_16x16x32_bf16 v[32:35], v[176:179], v[216:219], v[32:35]
	v_mfma_f32_16x16x32_bf16 v[20:23], v[148:151], v[224:227], v[20:23]
	v_mfma_f32_16x16x32_bf16 v[16:19], v[176:179], v[224:227], v[16:19]
	v_mfma_f32_16x16x32_bf16 v[4:7], v[148:151], v[232:235], v[4:7]
	v_mfma_f32_16x16x32_bf16 v[0:3], v[176:179], v[232:235], v[0:3]
	s_barrier
; #define PG8_STAGE(bufoff, gbase, voff) do { _Pragma("unroll") for (int _i = 0; _i < 2; ++_i) \
;         __builtin_amdgcn_global_load_lds((const unsigned*)((const char*)(gbase) + (voff)[_i]), (PG8_LAS unsigned*)(lds + (bufoff) + ldsw + _i * 8192), 16, 0, 0); } while (0)
; #define PG8_LDA(dst, b, h) do { _Pragma("unroll") for (int m = 0; m < 4; ++m) _Pragma("unroll") for (int k = 0; k < 2; ++k) dst[m][k] = *(const PG8_LAS bf16x8*)(lds + PG8_SA(b, h) + aoff + m * 2048 + k * 1024); } while (0)
; #define PG8_LDB(dst, b, h) do { _Pragma("unroll") for (int n = 0; n < 2; ++n) _Pragma("unroll") for (int k = 0; k < 2; ++k) dst[n][k] = *(const PG8_LAS bf16x8*)(lds + PG8_SB(b, h) + boff + n * 2048 + k * 1024); } while (0)
; #define PG8_MMA(ai, bj, At, Bt) do { __builtin_amdgcn_s_setprio(1); _Pragma("unroll") for (int m = 0; m < 4; ++m) _Pragma("unroll") for (int n = 0; n < 2; ++n) _Pragma("unroll") for (int k = 0; k < 2; ++k) \
;         acc[ai][bj][m][n] = __builtin_amdgcn_mfma_f32_16x16x32_bf16(Bt[n][k], At[m][k], acc[ai][bj][m][n], 0, 0, 0); __builtin_amdgcn_s_setprio(0); } while (0)
; #define PG8_WAIT_V(n) asm volatile("s_waitcnt vmcnt(" #n ")" ::: "memory")
; #define PG8_WAIT_L(n) asm volatile("s_waitcnt lgkmcnt(" #n ")" ::: "memory")
; #define PG8_BAR __builtin_amdgcn_s_barrier()
; #define PG8_SCHED __builtin_amdgcn_sched_barrier(0)
; template <class Epi, class Sched, bool ALIGN_EPI = false, bool SP2 = false>
; __device__ __forceinline__ void gemm_phase(PG8_LAS unsigned char* lds, const Gemm g, const Sched& S, const Epi& E) {
;     ...
;         for (int t = 0; t < nt; t += 2) {
;     ...
;             PG8_LDB(B0, 1, 0); PG8_LDB(B1, 1, 1); PG8_SCHED; PG8_LDA(At, 1, 0); PG8_STAGE(PG8_SA(0, 1), a2 + hstep, voffA);
;             PG8_WAIT_V(8); PG8_WAIT_L(0); PG8_BAR; PG8_MMA(0, 0, At, B0); PG8_MMA(0, 1, At, B1); PG8_BAR; PG8_SCHED;
;             PG8_LDA(At, 1, 1); PG8_STAGE(PG8_SB(1, 0), b3, voffB); PG8_STAGE(PG8_SB(1, 1), b3 + hstep, voffB); PG8_STAGE(PG8_SA(1, 0), a3, voffA);
;             PG8_WAIT_V(8); PG8_WAIT_L(0); PG8_BAR; PG8_MMA(1, 0, At, B0); PG8_MMA(1, 1, At, B1); PG8_BAR; PG8_SCHED;
	ds_read_b128 v[128:131], v196
	ds_read_b128 v[132:135], v197
	ds_read_b128 v[136:139], v198
	ds_read_b128 v[140:143], v199
	ds_read_b128 v[144:147], v200
	ds_read_b128 v[148:151], v201
	ds_read_b128 v[172:175], v202
	ds_read_b128 v[176:179], v203
	s_add_u32 s46, s46, 0x40000
	s_addc_u32 s47, s47, 0
	s_mov_b32 m0, s56
	v_lshl_add_u64 v[244:245], s[46:47], 0, v[152:153]
	ds_read_b128 v[180:183], v186 offset:32768
	ds_read_b128 v[208:211], v186 offset:33792
	ds_read_b128 v[212:215], v186 offset:34816
	ds_read_b128 v[216:219], v186 offset:35840
	ds_read_b128 v[220:223], v186 offset:36864
	ds_read_b128 v[224:227], v186 offset:37888
	ds_read_b128 v[228:231], v186 offset:38912
	ds_read_b128 v[232:235], v186 offset:39936
	global_load_lds_dwordx4 v[244:245], off
	v_lshl_add_u64 v[244:245], s[46:47], 0, v[156:157]
	s_mov_b32 m0, s57
	s_nop 0
	global_load_lds_dwordx4 v[244:245], off
	s_waitcnt vmcnt(8)
	s_waitcnt lgkmcnt(0)
	s_barrier
	s_waitcnt lgkmcnt(0)
	v_mfma_f32_16x16x32_bf16 v[124:127], v[128:131], v[180:183], v[124:127]
	v_mfma_f32_16x16x32_bf16 v[120:123], v[136:139], v[180:183], v[120:123]
	v_mfma_f32_16x16x32_bf16 v[108:111], v[128:131], v[212:215], v[108:111]
	v_mfma_f32_16x16x32_bf16 v[104:107], v[136:139], v[212:215], v[104:107]
	v_mfma_f32_16x16x32_bf16 v[92:95], v[128:131], v[220:223], v[92:95]
	v_mfma_f32_16x16x32_bf16 v[88:91], v[136:139], v[220:223], v[88:91]
	v_mfma_f32_16x16x32_bf16 v[76:79], v[128:131], v[228:231], v[76:79]
	v_mfma_f32_16x16x32_bf16 v[72:75], v[136:139], v[228:231], v[72:75]
	v_mfma_f32_16x16x32_bf16 v[124:127], v[132:135], v[208:211], v[124:127]
	v_mfma_f32_16x16x32_bf16 v[120:123], v[140:143], v[208:211], v[120:123]
	v_mfma_f32_16x16x32_bf16 v[108:111], v[132:135], v[216:219], v[108:111]
	v_mfma_f32_16x16x32_bf16 v[104:107], v[140:143], v[216:219], v[104:107]
	v_mfma_f32_16x16x32_bf16 v[92:95], v[132:135], v[224:227], v[92:95]
	v_mfma_f32_16x16x32_bf16 v[88:91], v[140:143], v[224:227], v[88:91]
	v_mfma_f32_16x16x32_bf16 v[76:79], v[132:135], v[232:235], v[76:79]
	v_mfma_f32_16x16x32_bf16 v[72:75], v[140:143], v[232:235], v[72:75]
	v_mfma_f32_16x16x32_bf16 v[116:119], v[144:147], v[180:183], v[116:119]
	v_mfma_f32_16x16x32_bf16 v[112:115], v[172:175], v[180:183], v[112:115]
	v_mfma_f32_16x16x32_bf16 v[100:103], v[144:147], v[212:215], v[100:103]
	v_mfma_f32_16x16x32_bf16 v[96:99], v[172:175], v[212:215], v[96:99]
	v_mfma_f32_16x16x32_bf16 v[84:87], v[144:147], v[220:223], v[84:87]
	v_mfma_f32_16x16x32_bf16 v[80:83], v[172:175], v[220:223], v[80:83]
	v_mfma_f32_16x16x32_bf16 v[68:71], v[144:147], v[228:231], v[68:71]
	v_mfma_f32_16x16x32_bf16 v[64:67], v[172:175], v[228:231], v[64:67]
	v_mfma_f32_16x16x32_bf16 v[116:119], v[148:151], v[208:211], v[116:119]
	v_mfma_f32_16x16x32_bf16 v[112:115], v[176:179], v[208:211], v[112:115]
	v_mfma_f32_16x16x32_bf16 v[100:103], v[148:151], v[216:219], v[100:103]
	v_mfma_f32_16x16x32_bf16 v[96:99], v[176:179], v[216:219], v[96:99]
	v_mfma_f32_16x16x32_bf16 v[84:87], v[148:151], v[224:227], v[84:87]
	v_mfma_f32_16x16x32_bf16 v[80:83], v[176:179], v[224:227], v[80:83]
	v_mfma_f32_16x16x32_bf16 v[68:71], v[148:151], v[232:235], v[68:71]
	v_mfma_f32_16x16x32_bf16 v[64:67], v[176:179], v[232:235], v[64:67]
	s_barrier
	s_mov_b32 m0, s59
	v_lshl_add_u64 v[236:237], v[236:237], 0, s[22:23]
	s_add_u32 s44, s44, 0x40080
	ds_read_b128 v[180:183], v186 offset:49152
	ds_read_b128 v[208:211], v186 offset:50176
	ds_read_b128 v[212:215], v186 offset:51200
	ds_read_b128 v[216:219], v186 offset:52224
	ds_read_b128 v[220:223], v186 offset:53248
	ds_read_b128 v[224:227], v186 offset:54272
	ds_read_b128 v[228:231], v186 offset:55296
	ds_read_b128 v[232:235], v186 offset:56320
	global_load_lds_dwordx4 v[236:237], off
	v_lshl_add_u64 v[236:237], v[238:239], 0, s[22:23]
	s_mov_b32 m0, s60
	s_addc_u32 s45, s45, 0
	global_load_lds_dwordx4 v[236:237], off
	v_lshl_add_u64 v[236:237], s[44:45], 0, v[154:155]
	s_mov_b32 m0, s63
	s_nop 0
	global_load_lds_dwordx4 v[236:237], off
	v_lshl_add_u64 v[236:237], s[44:45], 0, v[158:159]
	s_mov_b32 m0, s64
	s_nop 0
	global_load_lds_dwordx4 v[236:237], off
	v_lshl_add_u64 v[236:237], v[240:241], 0, s[22:23]
	s_mov_b32 m0, s61
	s_nop 0
	global_load_lds_dwordx4 v[236:237], off
	v_lshl_add_u64 v[236:237], v[242:243], 0, s[22:23]
	s_mov_b32 m0, s62
	s_nop 0
	global_load_lds_dwordx4 v[236:237], off
	s_waitcnt vmcnt(8)
	s_waitcnt lgkmcnt(0)
	s_barrier
	s_waitcnt lgkmcnt(0)
	v_mfma_f32_16x16x32_bf16 v[60:63], v[128:131], v[180:183], v[60:63]
	v_mfma_f32_16x16x32_bf16 v[56:59], v[136:139], v[180:183], v[56:59]
	v_mfma_f32_16x16x32_bf16 v[44:47], v[128:131], v[212:215], v[44:47]
	v_mfma_f32_16x16x32_bf16 v[40:43], v[136:139], v[212:215], v[40:43]
	v_mfma_f32_16x16x32_bf16 v[28:31], v[128:131], v[220:223], v[28:31]
	v_mfma_f32_16x16x32_bf16 v[24:27], v[136:139], v[220:223], v[24:27]
	v_mfma_f32_16x16x32_bf16 v[12:15], v[128:131], v[228:231], v[12:15]
	v_mfma_f32_16x16x32_bf16 v[8:11], v[136:139], v[228:231], v[8:11]
	v_mfma_f32_16x16x32_bf16 v[60:63], v[132:135], v[208:211], v[60:63]
	v_mfma_f32_16x16x32_bf16 v[56:59], v[140:143], v[208:211], v[56:59]
	v_mfma_f32_16x16x32_bf16 v[44:47], v[132:135], v[216:219], v[44:47]
	v_mfma_f32_16x16x32_bf16 v[40:43], v[140:143], v[216:219], v[40:43]
	v_mfma_f32_16x16x32_bf16 v[28:31], v[132:135], v[224:227], v[28:31]
	v_mfma_f32_16x16x32_bf16 v[24:27], v[140:143], v[224:227], v[24:27]
	v_mfma_f32_16x16x32_bf16 v[12:15], v[132:135], v[232:235], v[12:15]
	v_mfma_f32_16x16x32_bf16 v[8:11], v[140:143], v[232:235], v[8:11]
	v_mfma_f32_16x16x32_bf16 v[52:55], v[144:147], v[180:183], v[52:55]
	v_mfma_f32_16x16x32_bf16 v[48:51], v[172:175], v[180:183], v[48:51]
	v_mfma_f32_16x16x32_bf16 v[36:39], v[144:147], v[212:215], v[36:39]
	v_mfma_f32_16x16x32_bf16 v[32:35], v[172:175], v[212:215], v[32:35]
	v_mfma_f32_16x16x32_bf16 v[20:23], v[144:147], v[220:223], v[20:23]
	v_mfma_f32_16x16x32_bf16 v[16:19], v[172:175], v[220:223], v[16:19]
	v_mfma_f32_16x16x32_bf16 v[4:7], v[144:147], v[228:231], v[4:7]
	v_mfma_f32_16x16x32_bf16 v[0:3], v[172:175], v[228:231], v[0:3]
	v_mfma_f32_16x16x32_bf16 v[52:55], v[148:151], v[208:211], v[52:55]
	v_mfma_f32_16x16x32_bf16 v[48:51], v[176:179], v[208:211], v[48:51]
	v_mfma_f32_16x16x32_bf16 v[36:39], v[148:151], v[216:219], v[36:39]
	v_mfma_f32_16x16x32_bf16 v[32:35], v[176:179], v[216:219], v[32:35]
	v_mfma_f32_16x16x32_bf16 v[20:23], v[148:151], v[224:227], v[20:23]
	v_mfma_f32_16x16x32_bf16 v[16:19], v[176:179], v[224:227], v[16:19]
	v_mfma_f32_16x16x32_bf16 v[4:7], v[148:151], v[232:235], v[4:7]
	v_mfma_f32_16x16x32_bf16 v[0:3], v[176:179], v[232:235], v[0:3]
	s_barrier
	s_add_i32 s74, s74, 2
	s_add_u32 s72, s72, 0x100
	s_addc_u32 s73, s73, 0
	s_add_u32 s42, s42, 0x100
	s_addc_u32 s43, s43, 0
	s_cmp_gt_u32 s74, 13
	s_cbranch_scc0 .LBB0_163
	s_and_b64 vcc, exec, s[24:25]
	s_cbranch_vccz .LBB0_166
	s_barrier

; #define PG8_STAGE(bufoff, gbase, voff) do { _Pragma("unroll") for (int _i = 0; _i < 2; ++_i) \
;         __builtin_amdgcn_global_load_lds((const unsigned*)((const char*)(gbase) + (voff)[_i]), (PG8_LAS unsigned*)(lds + (bufoff) + ldsw + _i * 8192), 16, 0, 0); } while (0)
; #define PG8_LDA(dst, b, h) do { _Pragma("unroll") for (int m = 0; m < 4; ++m) _Pragma("unroll") for (int k = 0; k < 2; ++k) dst[m][k] = *(const PG8_LAS bf16x8*)(lds + PG8_SA(b, h) + aoff + m * 2048 + k * 1024); } while (0)
; #define PG8_LDB(dst, b, h) do { _Pragma("unroll") for (int n = 0; n < 2; ++n) _Pragma("unroll") for (int k = 0; k < 2; ++k) dst[n][k] = *(const PG8_LAS bf16x8*)(lds + PG8_SB(b, h) + boff + n * 2048 + k * 1024); } while (0)
; #define PG8_MMA(ai, bj, At, Bt) do { __builtin_amdgcn_s_setprio(1); _Pragma("unroll") for (int m = 0; m < 4; ++m) _Pragma("unroll") for (int n = 0; n < 2; ++n) _Pragma("unroll") for (int k = 0; k < 2; ++k) \
;         acc[ai][bj][m][n] = __builtin_amdgcn_mfma_f32_16x16x32_bf16(Bt[n][k], At[m][k], acc[ai][bj][m][n], 0, 0, 0); __builtin_amdgcn_s_setprio(0); } while (0)
; #define PG8_WAIT_V(n) asm volatile("s_waitcnt vmcnt(" #n ")" ::: "memory")
; #define PG8_WAIT_L(n) asm volatile("s_waitcnt lgkmcnt(" #n ")" ::: "memory")
; template <class Epi, class Sched, bool ALIGN_EPI = false, bool SP2 = false>
; __device__ __forceinline__ void gemm_phase(PG8_LAS unsigned char* lds, const Gemm g, const Sched& S, const Epi& E) {
;     ...
;             const bool last = (t == nt - 2);
;             const char* a1 = cA + (size_t)(t + 1) * kstep;
;             const char* a2 = last ? nA : cA + (size_t)(t + 2) * kstep; const char* b2 = last ? nB : cB + (size_t)(t + 2) * kstep;
;             const char* a3 = a2 + kstep; const char* b3 = b2 + kstep;
;             if (last && has_next) S.a_ready(nxt);
;             if constexpr (SP2) {
;             PG8_LDB(B0, 0, 0); PG8_LDB(B1, 0, 1); PG8_SCHED; PG8_LDA(At, 0, 0); PG8_STAGE(PG8_SA(1, 1), a1 + hstep, voffA);
;             PG8_WAIT_V(8); PG8_WAIT_L(0); PG8_BAR; PG8_MMA(0, 0, At, B0); PG8_MMA(0, 1, At, B1); PG8_BAR; PG8_SCHED;
;             PG8_LDA(At, 0, 1); PG8_STAGE(PG8_SB(0, 0), b2, voffB); PG8_STAGE(PG8_SB(0, 1), b2 + hstep, voffB); PG8_STAGE(PG8_SA(0, 0), a2, voffA);
;             PG8_WAIT_V(8); PG8_WAIT_L(0); PG8_BAR; PG8_MMA(1, 0, At, B0); PG8_MMA(1, 1, At, B1); PG8_BAR; PG8_SCHED;
.LBB0_390:
	ds_read_b128 v[144:147], v151
	ds_read_b128 v[168:171], v152
	ds_read_b128 v[172:175], v153
	ds_read_b128 v[176:179], v154
	ds_read_b128 v[180:183], v155
	ds_read_b128 v[186:189], v156
	ds_read_b128 v[190:193], v157
	ds_read_b128 v[194:197], v158
	s_add_u32 s36, s34, 0xfffc0080
	s_addc_u32 s37, s35, -1
	s_cmp_eq_u32 s70, 12
	s_cselect_b32 s43, s25, s37
	s_cselect_b32 s42, s31, s36
	s_cselect_b32 s37, s23, s69
	s_cselect_b32 s36, s67, s68
	s_mov_b32 m0, s64
	v_lshl_add_u64 v[230:231], s[34:35], 0, v[138:139]
	ds_read_b128 v[198:201], v149
	ds_read_b128 v[202:205], v149 offset:1024
	ds_read_b128 v[206:209], v149 offset:2048
	ds_read_b128 v[210:213], v149 offset:3072
	ds_read_b128 v[214:217], v149 offset:4096
	ds_read_b128 v[218:221], v149 offset:5120
	ds_read_b128 v[222:225], v149 offset:6144
	ds_read_b128 v[226:229], v149 offset:7168
	global_load_lds_dwordx4 v[230:231], off
	v_lshl_add_u64 v[230:231], s[34:35], 0, v[136:137]
	s_mov_b32 m0, s65
	s_nop 0
	global_load_lds_dwordx4 v[230:231], off
	s_waitcnt vmcnt(8)
	s_waitcnt lgkmcnt(0)
	s_barrier
	s_waitcnt lgkmcnt(0)
	v_mfma_f32_16x16x32_bf16 v[124:127], v[144:147], v[198:201], v[124:127]
	v_mfma_f32_16x16x32_bf16 v[120:123], v[172:175], v[198:201], v[120:123]
	v_mfma_f32_16x16x32_bf16 v[108:111], v[144:147], v[206:209], v[108:111]
	v_mfma_f32_16x16x32_bf16 v[104:107], v[172:175], v[206:209], v[104:107]
	v_mfma_f32_16x16x32_bf16 v[92:95], v[144:147], v[214:217], v[92:95]
	v_mfma_f32_16x16x32_bf16 v[88:91], v[172:175], v[214:217], v[88:91]
	v_mfma_f32_16x16x32_bf16 v[76:79], v[144:147], v[222:225], v[76:79]
	v_mfma_f32_16x16x32_bf16 v[72:75], v[172:175], v[222:225], v[72:75]
	v_mfma_f32_16x16x32_bf16 v[124:127], v[168:171], v[202:205], v[124:127]
	v_mfma_f32_16x16x32_bf16 v[120:123], v[176:179], v[202:205], v[120:123]
	v_mfma_f32_16x16x32_bf16 v[108:111], v[168:171], v[210:213], v[108:111]
	v_mfma_f32_16x16x32_bf16 v[104:107], v[176:179], v[210:213], v[104:107]
	v_mfma_f32_16x16x32_bf16 v[92:95], v[168:171], v[218:221], v[92:95]
	v_mfma_f32_16x16x32_bf16 v[88:91], v[176:179], v[218:221], v[88:91]
	v_mfma_f32_16x16x32_bf16 v[76:79], v[168:171], v[226:229], v[76:79]
	v_mfma_f32_16x16x32_bf16 v[72:75], v[176:179], v[226:229], v[72:75]
	v_mfma_f32_16x16x32_bf16 v[116:119], v[180:183], v[198:201], v[116:119]
	v_mfma_f32_16x16x32_bf16 v[112:115], v[190:193], v[198:201], v[112:115]
	v_mfma_f32_16x16x32_bf16 v[100:103], v[180:183], v[206:209], v[100:103]
	v_mfma_f32_16x16x32_bf16 v[96:99], v[190:193], v[206:209], v[96:99]
	v_mfma_f32_16x16x32_bf16 v[84:87], v[180:183], v[214:217], v[84:87]
	v_mfma_f32_16x16x32_bf16 v[80:83], v[190:193], v[214:217], v[80:83]
	v_mfma_f32_16x16x32_bf16 v[68:71], v[180:183], v[222:225], v[68:71]
	v_mfma_f32_16x16x32_bf16 v[64:67], v[190:193], v[222:225], v[64:67]
	v_mfma_f32_16x16x32_bf16 v[116:119], v[186:189], v[202:205], v[116:119]
	v_mfma_f32_16x16x32_bf16 v[112:115], v[194:197], v[202:205], v[112:115]
	v_mfma_f32_16x16x32_bf16 v[100:103], v[186:189], v[210:213], v[100:103]
	v_mfma_f32_16x16x32_bf16 v[96:99], v[194:197], v[210:213], v[96:99]
	v_mfma_f32_16x16x32_bf16 v[84:87], v[186:189], v[218:221], v[84:87]
	v_mfma_f32_16x16x32_bf16 v[80:83], v[194:197], v[218:221], v[80:83]
	v_mfma_f32_16x16x32_bf16 v[68:71], v[186:189], v[226:229], v[68:71]
	v_mfma_f32_16x16x32_bf16 v[64:67], v[194:197], v[226:229], v[64:67]
	s_barrier
	s_mov_b32 m0, s48
	v_lshl_add_u64 v[230:231], s[36:37], 0, v[130:131]
	s_add_u32 s72, s36, 0x40000
	ds_read_b128 v[198:201], v149 offset:16384
	ds_read_b128 v[202:205], v149 offset:17408
	ds_read_b128 v[206:209], v149 offset:18432
	ds_read_b128 v[210:213], v149 offset:19456
	ds_read_b128 v[214:217], v149 offset:20480
	ds_read_b128 v[218:221], v149 offset:21504
	ds_read_b128 v[222:225], v149 offset:22528
	ds_read_b128 v[226:229], v149 offset:23552
	global_load_lds_dwordx4 v[230:231], off
	v_lshl_add_u64 v[232:233], s[36:37], 0, v[134:135]
	s_mov_b32 m0, s49
	s_addc_u32 s73, s37, 0
	global_load_lds_dwordx4 v[232:233], off
	v_lshl_add_u64 v[234:235], s[72:73], 0, v[130:131]
	s_mov_b32 m0, s50
	v_lshl_add_u64 v[236:237], s[42:43], 0, v[132:133]
	global_load_lds_dwordx4 v[234:235], off
	v_lshl_add_u64 v[234:235], s[72:73], 0, v[134:135]
	s_mov_b32 m0, s51
	s_nop 0
	global_load_lds_dwordx4 v[234:235], off
	v_lshl_add_u64 v[234:235], s[42:43], 0, v[128:129]
	s_mov_b32 m0, s47
	s_nop 0
	global_load_lds_dwordx4 v[234:235], off
	s_mov_b32 m0, s52
	s_nop 0
	global_load_lds_dwordx4 v[236:237], off
	s_waitcnt vmcnt(8)
	s_waitcnt lgkmcnt(0)
	s_barrier
	s_waitcnt lgkmcnt(0)
	v_mfma_f32_16x16x32_bf16 v[60:63], v[144:147], v[198:201], v[60:63]
	v_mfma_f32_16x16x32_bf16 v[56:59], v[172:175], v[198:201], v[56:59]
	v_mfma_f32_16x16x32_bf16 v[44:47], v[144:147], v[206:209], v[44:47]
	v_mfma_f32_16x16x32_bf16 v[40:43], v[172:175], v[206:209], v[40:43]
	v_mfma_f32_16x16x32_bf16 v[28:31], v[144:147], v[214:217], v[28:31]
	v_mfma_f32_16x16x32_bf16 v[24:27], v[172:175], v[214:217], v[24:27]
	v_mfma_f32_16x16x32_bf16 v[12:15], v[144:147], v[222:225], v[12:15]
	v_mfma_f32_16x16x32_bf16 v[8:11], v[172:175], v[222:225], v[8:11]
	v_mfma_f32_16x16x32_bf16 v[60:63], v[168:171], v[202:205], v[60:63]
	v_mfma_f32_16x16x32_bf16 v[56:59], v[176:179], v[202:205], v[56:59]
	v_mfma_f32_16x16x32_bf16 v[44:47], v[168:171], v[210:213], v[44:47]
	v_mfma_f32_16x16x32_bf16 v[40:43], v[176:179], v[210:213], v[40:43]
	v_mfma_f32_16x16x32_bf16 v[28:31], v[168:171], v[218:221], v[28:31]
	v_mfma_f32_16x16x32_bf16 v[24:27], v[176:179], v[218:221], v[24:27]
	v_mfma_f32_16x16x32_bf16 v[12:15], v[168:171], v[226:229], v[12:15]
	v_mfma_f32_16x16x32_bf16 v[8:11], v[176:179], v[226:229], v[8:11]
	v_mfma_f32_16x16x32_bf16 v[52:55], v[180:183], v[198:201], v[52:55]
	v_mfma_f32_16x16x32_bf16 v[48:51], v[190:193], v[198:201], v[48:51]
	v_mfma_f32_16x16x32_bf16 v[36:39], v[180:183], v[206:209], v[36:39]
	v_mfma_f32_16x16x32_bf16 v[32:35], v[190:193], v[206:209], v[32:35]
	v_mfma_f32_16x16x32_bf16 v[20:23], v[180:183], v[214:217], v[20:23]
	v_mfma_f32_16x16x32_bf16 v[16:19], v[190:193], v[214:217], v[16:19]
	v_mfma_f32_16x16x32_bf16 v[4:7], v[180:183], v[222:225], v[4:7]
	v_mfma_f32_16x16x32_bf16 v[0:3], v[190:193], v[222:225], v[0:3]
	v_mfma_f32_16x16x32_bf16 v[52:55], v[186:189], v[202:205], v[52:55]
	v_mfma_f32_16x16x32_bf16 v[48:51], v[194:197], v[202:205], v[48:51]
	v_mfma_f32_16x16x32_bf16 v[36:39], v[186:189], v[210:213], v[36:39]
	v_mfma_f32_16x16x32_bf16 v[32:35], v[194:197], v[210:213], v[32:35]
	v_mfma_f32_16x16x32_bf16 v[20:23], v[186:189], v[218:221], v[20:23]
	v_mfma_f32_16x16x32_bf16 v[16:19], v[194:197], v[218:221], v[16:19]
	v_mfma_f32_16x16x32_bf16 v[4:7], v[186:189], v[226:229], v[4:7]
	v_mfma_f32_16x16x32_bf16 v[0:3], v[194:197], v[226:229], v[0:3]
	s_barrier
; #define PG8_STAGE(bufoff, gbase, voff) do { _Pragma("unroll") for (int _i = 0; _i < 2; ++_i) \
;         __builtin_amdgcn_global_load_lds((const unsigned*)((const char*)(gbase) + (voff)[_i]), (PG8_LAS unsigned*)(lds + (bufoff) + ldsw + _i * 8192), 16, 0, 0); } while (0)
; #define PG8_LDA(dst, b, h) do { _Pragma("unroll") for (int m = 0; m < 4; ++m) _Pragma("unroll") for (int k = 0; k < 2; ++k) dst[m][k] = *(const PG8_LAS bf16x8*)(lds + PG8_SA(b, h) + aoff + m * 2048 + k * 1024); } while (0)
; #define PG8_LDB(dst, b, h) do { _Pragma("unroll") for (int n = 0; n < 2; ++n) _Pragma("unroll") for (int k = 0; k < 2; ++k) dst[n][k] = *(const PG8_LAS bf16x8*)(lds + PG8_SB(b, h) + boff + n * 2048 + k * 1024); } while (0)
; #define PG8_MMA(ai, bj, At, Bt) do { __builtin_amdgcn_s_setprio(1); _Pragma("unroll") for (int m = 0; m < 4; ++m) _Pragma("unroll") for (int n = 0; n < 2; ++n) _Pragma("unroll") for (int k = 0; k < 2; ++k) \
;         acc[ai][bj][m][n] = __builtin_amdgcn_mfma_f32_16x16x32_bf16(Bt[n][k], At[m][k], acc[ai][bj][m][n], 0, 0, 0); __builtin_amdgcn_s_setprio(0); } while (0)
; #define PG8_WAIT_V(n) asm volatile("s_waitcnt vmcnt(" #n ")" ::: "memory")
; #define PG8_WAIT_L(n) asm volatile("s_waitcnt lgkmcnt(" #n ")" ::: "memory")
; #define PG8_BAR __builtin_amdgcn_s_barrier()
; #define PG8_SCHED __builtin_amdgcn_sched_barrier(0)
; template <class Epi, class Sched, bool ALIGN_EPI = false, bool SP2 = false>
; __device__ __forceinline__ void gemm_phase(PG8_LAS unsigned char* lds, const Gemm g, const Sched& S, const Epi& E) {
;     ...
;         for (int t = 0; t < nt; t += 2) {
;     ...
;             PG8_LDB(B0, 1, 0); PG8_LDB(B1, 1, 1); PG8_SCHED; PG8_LDA(At, 1, 0); PG8_STAGE(PG8_SA(0, 1), a2 + hstep, voffA);
;             PG8_WAIT_V(8); PG8_WAIT_L(0); PG8_BAR; PG8_MMA(0, 0, At, B0); PG8_MMA(0, 1, At, B1); PG8_BAR; PG8_SCHED;
;             PG8_LDA(At, 1, 1); PG8_STAGE(PG8_SB(1, 0), b3, voffB); PG8_STAGE(PG8_SB(1, 1), b3 + hstep, voffB); PG8_STAGE(PG8_SA(1, 0), a3, voffA);
;             PG8_WAIT_V(8); PG8_WAIT_L(0); PG8_BAR; PG8_MMA(1, 0, At, B0); PG8_MMA(1, 1, At, B1); PG8_BAR; PG8_SCHED;
	ds_read_b128 v[144:147], v159
	ds_read_b128 v[168:171], v160
	ds_read_b128 v[172:175], v161
	ds_read_b128 v[176:179], v162
	ds_read_b128 v[180:183], v163
	ds_read_b128 v[186:189], v164
	ds_read_b128 v[190:193], v165
	ds_read_b128 v[194:197], v166
	s_add_u32 s42, s42, 0x40000
	s_addc_u32 s43, s43, 0
	s_mov_b32 m0, s53
	v_lshl_add_u64 v[238:239], s[42:43], 0, v[128:129]
	ds_read_b128 v[198:201], v149 offset:32768
	ds_read_b128 v[202:205], v149 offset:33792
	ds_read_b128 v[206:209], v149 offset:34816
	ds_read_b128 v[210:213], v149 offset:35840
	ds_read_b128 v[214:217], v149 offset:36864
	ds_read_b128 v[218:221], v149 offset:37888
	ds_read_b128 v[222:225], v149 offset:38912
	ds_read_b128 v[226:229], v149 offset:39936
	global_load_lds_dwordx4 v[238:239], off
	v_lshl_add_u64 v[238:239], s[42:43], 0, v[132:133]
	s_mov_b32 m0, s54
	s_nop 0
	global_load_lds_dwordx4 v[238:239], off
	s_waitcnt vmcnt(8)
	s_waitcnt lgkmcnt(0)
	s_barrier
	s_waitcnt lgkmcnt(0)
	v_mfma_f32_16x16x32_bf16 v[124:127], v[144:147], v[198:201], v[124:127]
	v_mfma_f32_16x16x32_bf16 v[120:123], v[172:175], v[198:201], v[120:123]
	v_mfma_f32_16x16x32_bf16 v[108:111], v[144:147], v[206:209], v[108:111]
	v_mfma_f32_16x16x32_bf16 v[104:107], v[172:175], v[206:209], v[104:107]
	v_mfma_f32_16x16x32_bf16 v[92:95], v[144:147], v[214:217], v[92:95]
	v_mfma_f32_16x16x32_bf16 v[88:91], v[172:175], v[214:217], v[88:91]
	v_mfma_f32_16x16x32_bf16 v[76:79], v[144:147], v[222:225], v[76:79]
	v_mfma_f32_16x16x32_bf16 v[72:75], v[172:175], v[222:225], v[72:75]
	v_mfma_f32_16x16x32_bf16 v[124:127], v[168:171], v[202:205], v[124:127]
	v_mfma_f32_16x16x32_bf16 v[120:123], v[176:179], v[202:205], v[120:123]
	v_mfma_f32_16x16x32_bf16 v[108:111], v[168:171], v[210:213], v[108:111]
	v_mfma_f32_16x16x32_bf16 v[104:107], v[176:179], v[210:213], v[104:107]
	v_mfma_f32_16x16x32_bf16 v[92:95], v[168:171], v[218:221], v[92:95]
	v_mfma_f32_16x16x32_bf16 v[88:91], v[176:179], v[218:221], v[88:91]
	v_mfma_f32_16x16x32_bf16 v[76:79], v[168:171], v[226:229], v[76:79]
	v_mfma_f32_16x16x32_bf16 v[72:75], v[176:179], v[226:229], v[72:75]
	v_mfma_f32_16x16x32_bf16 v[116:119], v[180:183], v[198:201], v[116:119]
	v_mfma_f32_16x16x32_bf16 v[112:115], v[190:193], v[198:201], v[112:115]
	v_mfma_f32_16x16x32_bf16 v[100:103], v[180:183], v[206:209], v[100:103]
	v_mfma_f32_16x16x32_bf16 v[96:99], v[190:193], v[206:209], v[96:99]
	v_mfma_f32_16x16x32_bf16 v[84:87], v[180:183], v[214:217], v[84:87]
	v_mfma_f32_16x16x32_bf16 v[80:83], v[190:193], v[214:217], v[80:83]
	v_mfma_f32_16x16x32_bf16 v[68:71], v[180:183], v[222:225], v[68:71]
	v_mfma_f32_16x16x32_bf16 v[64:67], v[190:193], v[222:225], v[64:67]
	v_mfma_f32_16x16x32_bf16 v[116:119], v[186:189], v[202:205], v[116:119]
	v_mfma_f32_16x16x32_bf16 v[112:115], v[194:197], v[202:205], v[112:115]
	v_mfma_f32_16x16x32_bf16 v[100:103], v[186:189], v[210:213], v[100:103]
	v_mfma_f32_16x16x32_bf16 v[96:99], v[194:197], v[210:213], v[96:99]
	v_mfma_f32_16x16x32_bf16 v[84:87], v[186:189], v[218:221], v[84:87]
	v_mfma_f32_16x16x32_bf16 v[80:83], v[194:197], v[218:221], v[80:83]
	v_mfma_f32_16x16x32_bf16 v[68:71], v[186:189], v[226:229], v[68:71]
	v_mfma_f32_16x16x32_bf16 v[64:67], v[194:197], v[226:229], v[64:67]
	s_barrier
	s_mov_b32 m0, s56
	v_lshl_add_u64 v[230:231], v[230:231], 0, s[16:17]
	s_add_u32 s36, s36, 0x40080
	ds_read_b128 v[198:201], v149 offset:49152
	ds_read_b128 v[202:205], v149 offset:50176
	ds_read_b128 v[206:209], v149 offset:51200
	ds_read_b128 v[210:213], v149 offset:52224
	ds_read_b128 v[214:217], v149 offset:53248
	ds_read_b128 v[218:221], v149 offset:54272
	ds_read_b128 v[222:225], v149 offset:55296
	ds_read_b128 v[226:229], v149 offset:56320
	global_load_lds_dwordx4 v[230:231], off
	v_lshl_add_u64 v[230:231], v[232:233], 0, s[16:17]
	s_mov_b32 m0, s57
	s_addc_u32 s37, s37, 0
	global_load_lds_dwordx4 v[230:231], off
	v_lshl_add_u64 v[230:231], s[36:37], 0, v[130:131]
	s_mov_b32 m0, s60
	s_nop 0
	global_load_lds_dwordx4 v[230:231], off
	v_lshl_add_u64 v[230:231], s[36:37], 0, v[134:135]
	s_mov_b32 m0, s61
	s_nop 0
	global_load_lds_dwordx4 v[230:231], off
	v_lshl_add_u64 v[230:231], v[234:235], 0, s[16:17]
	s_mov_b32 m0, s58
	s_nop 0
	global_load_lds_dwordx4 v[230:231], off
	v_lshl_add_u64 v[230:231], v[236:237], 0, s[16:17]
	s_mov_b32 m0, s59
	s_nop 0
	global_load_lds_dwordx4 v[230:231], off
	s_waitcnt vmcnt(8)
	s_waitcnt lgkmcnt(0)
	s_barrier
	s_waitcnt lgkmcnt(0)
	v_mfma_f32_16x16x32_bf16 v[60:63], v[144:147], v[198:201], v[60:63]
	v_mfma_f32_16x16x32_bf16 v[56:59], v[172:175], v[198:201], v[56:59]
	v_mfma_f32_16x16x32_bf16 v[44:47], v[144:147], v[206:209], v[44:47]
	v_mfma_f32_16x16x32_bf16 v[40:43], v[172:175], v[206:209], v[40:43]
	v_mfma_f32_16x16x32_bf16 v[28:31], v[144:147], v[214:217], v[28:31]
	v_mfma_f32_16x16x32_bf16 v[24:27], v[172:175], v[214:217], v[24:27]
	v_mfma_f32_16x16x32_bf16 v[12:15], v[144:147], v[222:225], v[12:15]
	v_mfma_f32_16x16x32_bf16 v[8:11], v[172:175], v[222:225], v[8:11]
	v_mfma_f32_16x16x32_bf16 v[60:63], v[168:171], v[202:205], v[60:63]
	v_mfma_f32_16x16x32_bf16 v[56:59], v[176:179], v[202:205], v[56:59]
	v_mfma_f32_16x16x32_bf16 v[44:47], v[168:171], v[210:213], v[44:47]
	v_mfma_f32_16x16x32_bf16 v[40:43], v[176:179], v[210:213], v[40:43]
	v_mfma_f32_16x16x32_bf16 v[28:31], v[168:171], v[218:221], v[28:31]
	v_mfma_f32_16x16x32_bf16 v[24:27], v[176:179], v[218:221], v[24:27]
	v_mfma_f32_16x16x32_bf16 v[12:15], v[168:171], v[226:229], v[12:15]
	v_mfma_f32_16x16x32_bf16 v[8:11], v[176:179], v[226:229], v[8:11]
	v_mfma_f32_16x16x32_bf16 v[52:55], v[180:183], v[198:201], v[52:55]
	v_mfma_f32_16x16x32_bf16 v[48:51], v[190:193], v[198:201], v[48:51]
	v_mfma_f32_16x16x32_bf16 v[36:39], v[180:183], v[206:209], v[36:39]
	v_mfma_f32_16x16x32_bf16 v[32:35], v[190:193], v[206:209], v[32:35]
	v_mfma_f32_16x16x32_bf16 v[20:23], v[180:183], v[214:217], v[20:23]
	v_mfma_f32_16x16x32_bf16 v[16:19], v[190:193], v[214:217], v[16:19]
	v_mfma_f32_16x16x32_bf16 v[4:7], v[180:183], v[222:225], v[4:7]
	v_mfma_f32_16x16x32_bf16 v[0:3], v[190:193], v[222:225], v[0:3]
	v_mfma_f32_16x16x32_bf16 v[52:55], v[186:189], v[202:205], v[52:55]
	v_mfma_f32_16x16x32_bf16 v[48:51], v[194:197], v[202:205], v[48:51]
	v_mfma_f32_16x16x32_bf16 v[36:39], v[186:189], v[210:213], v[36:39]
	v_mfma_f32_16x16x32_bf16 v[32:35], v[194:197], v[210:213], v[32:35]
	v_mfma_f32_16x16x32_bf16 v[20:23], v[186:189], v[218:221], v[20:23]
	v_mfma_f32_16x16x32_bf16 v[16:19], v[194:197], v[218:221], v[16:19]
	v_mfma_f32_16x16x32_bf16 v[4:7], v[186:189], v[226:229], v[4:7]
	v_mfma_f32_16x16x32_bf16 v[0:3], v[194:197], v[226:229], v[0:3]
	s_barrier
	s_add_i32 s70, s70, 2
	s_add_u32 s68, s68, 0x100
	s_addc_u32 s69, s69, 0
	s_add_u32 s34, s34, 0x100
	s_addc_u32 s35, s35, 0
	s_cmp_gt_u32 s70, 13
	s_cbranch_scc0 .LBB0_390
	s_and_b64 vcc, exec, s[18:19]
	s_cbranch_vccz .LBB0_393
	s_barrier

; #define PG8_STAGE(bufoff, gbase, voff) do { _Pragma("unroll") for (int _i = 0; _i < 2; ++_i) \
;         __builtin_amdgcn_global_load_lds((const unsigned*)((const char*)(gbase) + (voff)[_i]), (PG8_LAS unsigned*)(lds + (bufoff) + ldsw + _i * 8192), 16, 0, 0); } while (0)
; #define PG8_LDA(dst, b, h) do { _Pragma("unroll") for (int m = 0; m < 4; ++m) _Pragma("unroll") for (int k = 0; k < 2; ++k) dst[m][k] = *(const PG8_LAS bf16x8*)(lds + PG8_SA(b, h) + aoff + m * 2048 + k * 1024); } while (0)
; #define PG8_LDB(dst, b, h) do { _Pragma("unroll") for (int n = 0; n < 2; ++n) _Pragma("unroll") for (int k = 0; k < 2; ++k) dst[n][k] = *(const PG8_LAS bf16x8*)(lds + PG8_SB(b, h) + boff + n * 2048 + k * 1024); } while (0)
; #define PG8_MMA(ai, bj, At, Bt) do { __builtin_amdgcn_s_setprio(1); _Pragma("unroll") for (int m = 0; m < 4; ++m) _Pragma("unroll") for (int n = 0; n < 2; ++n) _Pragma("unroll") for (int k = 0; k < 2; ++k) \
;         acc[ai][bj][m][n] = __builtin_amdgcn_mfma_f32_16x16x32_bf16(Bt[n][k], At[m][k], acc[ai][bj][m][n], 0, 0, 0); __builtin_amdgcn_s_setprio(0); } while (0)
; #define PG8_WAIT_V(n) asm volatile("s_waitcnt vmcnt(" #n ")" ::: "memory")
; #define PG8_WAIT_L(n) asm volatile("s_waitcnt lgkmcnt(" #n ")" ::: "memory")
; template <class Epi, class Sched, bool ALIGN_EPI = false, bool SP2 = false>
; __device__ __forceinline__ void gemm_phase(PG8_LAS unsigned char* lds, const Gemm g, const Sched& S, const Epi& E) {
;     ...
;             const bool last = (t == nt - 2);
;             const char* a1 = cA + (size_t)(t + 1) * kstep;
;             const char* a2 = last ? nA : cA + (size_t)(t + 2) * kstep; const char* b2 = last ? nB : cB + (size_t)(t + 2) * kstep;
;             const char* a3 = a2 + kstep; const char* b3 = b2 + kstep;
;             if (last && has_next) S.a_ready(nxt);
;             if constexpr (SP2) {
;             PG8_LDB(B0, 0, 0); PG8_LDB(B1, 0, 1); PG8_SCHED; PG8_LDA(At, 0, 0); PG8_STAGE(PG8_SA(1, 1), a1 + hstep, voffA);
;             PG8_WAIT_V(8); PG8_WAIT_L(0); PG8_BAR; PG8_MMA(0, 0, At, B0); PG8_MMA(0, 1, At, B1); PG8_BAR; PG8_SCHED;
;             PG8_LDA(At, 0, 1); PG8_STAGE(PG8_SB(0, 0), b2, voffB); PG8_STAGE(PG8_SB(0, 1), b2 + hstep, voffB); PG8_STAGE(PG8_SA(0, 0), a2, voffA);
;             PG8_WAIT_V(8); PG8_WAIT_L(0); PG8_BAR; PG8_MMA(1, 0, At, B0); PG8_MMA(1, 1, At, B1); PG8_BAR; PG8_SCHED;
.LBB0_477:
	ds_read_b128 v[144:147], v151
	ds_read_b128 v[170:173], v152
	ds_read_b128 v[174:177], v153
	ds_read_b128 v[178:181], v154
	ds_read_b128 v[186:189], v155
	ds_read_b128 v[190:193], v156
	ds_read_b128 v[194:197], v157
	ds_read_b128 v[198:201], v158
	s_add_u32 s30, s28, 0xfffc0080
	s_addc_u32 s31, s29, -1
	s_cmp_eq_u32 s67, 12
	s_cselect_b32 s35, s23, s31
	s_cselect_b32 s34, s63, s30
	s_cselect_b32 s31, s21, s66
	s_cselect_b32 s30, s64, s65
	s_mov_b32 m0, s60
	v_lshl_add_u64 v[182:183], s[28:29], 0, v[138:139]
	ds_read_b128 v[202:205], v149
	ds_read_b128 v[206:209], v149 offset:1024
	ds_read_b128 v[210:213], v149 offset:2048
	ds_read_b128 v[214:217], v149 offset:3072
	ds_read_b128 v[218:221], v149 offset:4096
	ds_read_b128 v[222:225], v149 offset:5120
	ds_read_b128 v[226:229], v149 offset:6144
	ds_read_b128 v[230:233], v149 offset:7168
	global_load_lds_dwordx4 v[182:183], off
	v_lshl_add_u64 v[182:183], s[28:29], 0, v[136:137]
	s_mov_b32 m0, s61
	s_nop 0
	global_load_lds_dwordx4 v[182:183], off
	s_waitcnt vmcnt(8)
	s_waitcnt lgkmcnt(0)
	s_barrier
	s_waitcnt lgkmcnt(0)
	v_mfma_f32_16x16x32_bf16 v[124:127], v[144:147], v[202:205], v[124:127]
	v_mfma_f32_16x16x32_bf16 v[120:123], v[174:177], v[202:205], v[120:123]
	v_mfma_f32_16x16x32_bf16 v[108:111], v[144:147], v[210:213], v[108:111]
	v_mfma_f32_16x16x32_bf16 v[104:107], v[174:177], v[210:213], v[104:107]
	v_mfma_f32_16x16x32_bf16 v[92:95], v[144:147], v[218:221], v[92:95]
	v_mfma_f32_16x16x32_bf16 v[88:91], v[174:177], v[218:221], v[88:91]
	v_mfma_f32_16x16x32_bf16 v[76:79], v[144:147], v[226:229], v[76:79]
	v_mfma_f32_16x16x32_bf16 v[72:75], v[174:177], v[226:229], v[72:75]
	v_mfma_f32_16x16x32_bf16 v[124:127], v[170:173], v[206:209], v[124:127]
	v_mfma_f32_16x16x32_bf16 v[120:123], v[178:181], v[206:209], v[120:123]
	v_mfma_f32_16x16x32_bf16 v[108:111], v[170:173], v[214:217], v[108:111]
	v_mfma_f32_16x16x32_bf16 v[104:107], v[178:181], v[214:217], v[104:107]
	v_mfma_f32_16x16x32_bf16 v[92:95], v[170:173], v[222:225], v[92:95]
	v_mfma_f32_16x16x32_bf16 v[88:91], v[178:181], v[222:225], v[88:91]
	v_mfma_f32_16x16x32_bf16 v[76:79], v[170:173], v[230:233], v[76:79]
	v_mfma_f32_16x16x32_bf16 v[72:75], v[178:181], v[230:233], v[72:75]
	v_mfma_f32_16x16x32_bf16 v[116:119], v[186:189], v[202:205], v[116:119]
	v_mfma_f32_16x16x32_bf16 v[112:115], v[194:197], v[202:205], v[112:115]
	v_mfma_f32_16x16x32_bf16 v[100:103], v[186:189], v[210:213], v[100:103]
	v_mfma_f32_16x16x32_bf16 v[96:99], v[194:197], v[210:213], v[96:99]
	v_mfma_f32_16x16x32_bf16 v[84:87], v[186:189], v[218:221], v[84:87]
	v_mfma_f32_16x16x32_bf16 v[80:83], v[194:197], v[218:221], v[80:83]
	v_mfma_f32_16x16x32_bf16 v[68:71], v[186:189], v[226:229], v[68:71]
	v_mfma_f32_16x16x32_bf16 v[64:67], v[194:197], v[226:229], v[64:67]
	v_mfma_f32_16x16x32_bf16 v[116:119], v[190:193], v[206:209], v[116:119]
	v_mfma_f32_16x16x32_bf16 v[112:115], v[198:201], v[206:209], v[112:115]
	v_mfma_f32_16x16x32_bf16 v[100:103], v[190:193], v[214:217], v[100:103]
	v_mfma_f32_16x16x32_bf16 v[96:99], v[198:201], v[214:217], v[96:99]
	v_mfma_f32_16x16x32_bf16 v[84:87], v[190:193], v[222:225], v[84:87]
	v_mfma_f32_16x16x32_bf16 v[80:83], v[198:201], v[222:225], v[80:83]
	v_mfma_f32_16x16x32_bf16 v[68:71], v[190:193], v[230:233], v[68:71]
	v_mfma_f32_16x16x32_bf16 v[64:67], v[198:201], v[230:233], v[64:67]
	s_barrier
	s_mov_b32 m0, s44
	v_lshl_add_u64 v[182:183], s[30:31], 0, v[132:133]
	s_add_u32 s68, s30, 0x40000
	ds_read_b128 v[202:205], v149 offset:16384
	ds_read_b128 v[206:209], v149 offset:17408
	ds_read_b128 v[210:213], v149 offset:18432
	ds_read_b128 v[214:217], v149 offset:19456
	ds_read_b128 v[218:221], v149 offset:20480
	ds_read_b128 v[222:225], v149 offset:21504
	ds_read_b128 v[226:229], v149 offset:22528
	ds_read_b128 v[230:233], v149 offset:23552
	global_load_lds_dwordx4 v[182:183], off
	v_lshl_add_u64 v[234:235], s[30:31], 0, v[128:129]
	s_mov_b32 m0, s45
	s_addc_u32 s69, s31, 0
	global_load_lds_dwordx4 v[234:235], off
	v_lshl_add_u64 v[236:237], s[68:69], 0, v[132:133]
	s_mov_b32 m0, s46
	v_lshl_add_u64 v[238:239], s[34:35], 0, v[130:131]
	global_load_lds_dwordx4 v[236:237], off
	v_lshl_add_u64 v[236:237], s[68:69], 0, v[128:129]
	s_mov_b32 m0, s47
	s_nop 0
	global_load_lds_dwordx4 v[236:237], off
	v_lshl_add_u64 v[236:237], s[34:35], 0, v[134:135]
	s_mov_b32 m0, s42
	s_nop 0
	global_load_lds_dwordx4 v[236:237], off
	s_mov_b32 m0, s48
	s_nop 0
	global_load_lds_dwordx4 v[238:239], off
	s_waitcnt vmcnt(8)
	s_waitcnt lgkmcnt(0)
	s_barrier
	s_waitcnt lgkmcnt(0)
	v_mfma_f32_16x16x32_bf16 v[60:63], v[144:147], v[202:205], v[60:63]
	v_mfma_f32_16x16x32_bf16 v[56:59], v[174:177], v[202:205], v[56:59]
	v_mfma_f32_16x16x32_bf16 v[44:47], v[144:147], v[210:213], v[44:47]
	v_mfma_f32_16x16x32_bf16 v[40:43], v[174:177], v[210:213], v[40:43]
	v_mfma_f32_16x16x32_bf16 v[28:31], v[144:147], v[218:221], v[28:31]
	v_mfma_f32_16x16x32_bf16 v[24:27], v[174:177], v[218:221], v[24:27]
	v_mfma_f32_16x16x32_bf16 v[12:15], v[144:147], v[226:229], v[12:15]
	v_mfma_f32_16x16x32_bf16 v[8:11], v[174:177], v[226:229], v[8:11]
	v_mfma_f32_16x16x32_bf16 v[60:63], v[170:173], v[206:209], v[60:63]
	v_mfma_f32_16x16x32_bf16 v[56:59], v[178:181], v[206:209], v[56:59]
	v_mfma_f32_16x16x32_bf16 v[44:47], v[170:173], v[214:217], v[44:47]
	v_mfma_f32_16x16x32_bf16 v[40:43], v[178:181], v[214:217], v[40:43]
	v_mfma_f32_16x16x32_bf16 v[28:31], v[170:173], v[222:225], v[28:31]
	v_mfma_f32_16x16x32_bf16 v[24:27], v[178:181], v[222:225], v[24:27]
	v_mfma_f32_16x16x32_bf16 v[12:15], v[170:173], v[230:233], v[12:15]
	v_mfma_f32_16x16x32_bf16 v[8:11], v[178:181], v[230:233], v[8:11]
	v_mfma_f32_16x16x32_bf16 v[52:55], v[186:189], v[202:205], v[52:55]
	v_mfma_f32_16x16x32_bf16 v[48:51], v[194:197], v[202:205], v[48:51]
	v_mfma_f32_16x16x32_bf16 v[36:39], v[186:189], v[210:213], v[36:39]
	v_mfma_f32_16x16x32_bf16 v[32:35], v[194:197], v[210:213], v[32:35]
	v_mfma_f32_16x16x32_bf16 v[20:23], v[186:189], v[218:221], v[20:23]
	v_mfma_f32_16x16x32_bf16 v[16:19], v[194:197], v[218:221], v[16:19]
	v_mfma_f32_16x16x32_bf16 v[4:7], v[186:189], v[226:229], v[4:7]
	v_mfma_f32_16x16x32_bf16 v[0:3], v[194:197], v[226:229], v[0:3]
	v_mfma_f32_16x16x32_bf16 v[52:55], v[190:193], v[206:209], v[52:55]
	v_mfma_f32_16x16x32_bf16 v[48:51], v[198:201], v[206:209], v[48:51]
	v_mfma_f32_16x16x32_bf16 v[36:39], v[190:193], v[214:217], v[36:39]
	v_mfma_f32_16x16x32_bf16 v[32:35], v[198:201], v[214:217], v[32:35]
	v_mfma_f32_16x16x32_bf16 v[20:23], v[190:193], v[222:225], v[20:23]
	v_mfma_f32_16x16x32_bf16 v[16:19], v[198:201], v[222:225], v[16:19]
	v_mfma_f32_16x16x32_bf16 v[4:7], v[190:193], v[230:233], v[4:7]
	v_mfma_f32_16x16x32_bf16 v[0:3], v[198:201], v[230:233], v[0:3]
	s_barrier
; #define PG8_STAGE(bufoff, gbase, voff) do { _Pragma("unroll") for (int _i = 0; _i < 2; ++_i) \
;         __builtin_amdgcn_global_load_lds((const unsigned*)((const char*)(gbase) + (voff)[_i]), (PG8_LAS unsigned*)(lds + (bufoff) + ldsw + _i * 8192), 16, 0, 0); } while (0)
; #define PG8_LDA(dst, b, h) do { _Pragma("unroll") for (int m = 0; m < 4; ++m) _Pragma("unroll") for (int k = 0; k < 2; ++k) dst[m][k] = *(const PG8_LAS bf16x8*)(lds + PG8_SA(b, h) + aoff + m * 2048 + k * 1024); } while (0)
; #define PG8_LDB(dst, b, h) do { _Pragma("unroll") for (int n = 0; n < 2; ++n) _Pragma("unroll") for (int k = 0; k < 2; ++k) dst[n][k] = *(const PG8_LAS bf16x8*)(lds + PG8_SB(b, h) + boff + n * 2048 + k * 1024); } while (0)
; #define PG8_MMA(ai, bj, At, Bt) do { __builtin_amdgcn_s_setprio(1); _Pragma("unroll") for (int m = 0; m < 4; ++m) _Pragma("unroll") for (int n = 0; n < 2; ++n) _Pragma("unroll") for (int k = 0; k < 2; ++k) \
;         acc[ai][bj][m][n] = __builtin_amdgcn_mfma_f32_16x16x32_bf16(Bt[n][k], At[m][k], acc[ai][bj][m][n], 0, 0, 0); __builtin_amdgcn_s_setprio(0); } while (0)
; #define PG8_WAIT_V(n) asm volatile("s_waitcnt vmcnt(" #n ")" ::: "memory")
; #define PG8_WAIT_L(n) asm volatile("s_waitcnt lgkmcnt(" #n ")" ::: "memory")
; #define PG8_BAR __builtin_amdgcn_s_barrier()
; #define PG8_SCHED __builtin_amdgcn_sched_barrier(0)
; template <class Epi, class Sched, bool ALIGN_EPI = false, bool SP2 = false>
; __device__ __forceinline__ void gemm_phase(PG8_LAS unsigned char* lds, const Gemm g, const Sched& S, const Epi& E) {
;     ...
;         for (int t = 0; t < nt; t += 2) {
;     ...
;             PG8_LDB(B0, 1, 0); PG8_LDB(B1, 1, 1); PG8_SCHED; PG8_LDA(At, 1, 0); PG8_STAGE(PG8_SA(0, 1), a2 + hstep, voffA);
;             PG8_WAIT_V(8); PG8_WAIT_L(0); PG8_BAR; PG8_MMA(0, 0, At, B0); PG8_MMA(0, 1, At, B1); PG8_BAR; PG8_SCHED;
;             PG8_LDA(At, 1, 1); PG8_STAGE(PG8_SB(1, 0), b3, voffB); PG8_STAGE(PG8_SB(1, 1), b3 + hstep, voffB); PG8_STAGE(PG8_SA(1, 0), a3, voffA);
;             PG8_WAIT_V(8); PG8_WAIT_L(0); PG8_BAR; PG8_MMA(1, 0, At, B0); PG8_MMA(1, 1, At, B1); PG8_BAR; PG8_SCHED;
	ds_read_b128 v[144:147], v159
	ds_read_b128 v[170:173], v160
	ds_read_b128 v[174:177], v161
	ds_read_b128 v[178:181], v162
	ds_read_b128 v[186:189], v163
	ds_read_b128 v[190:193], v164
	ds_read_b128 v[194:197], v165
	ds_read_b128 v[198:201], v166
	s_add_u32 s34, s34, 0x40000
	s_addc_u32 s35, s35, 0
	s_mov_b32 m0, s49
	v_lshl_add_u64 v[240:241], s[34:35], 0, v[134:135]
	ds_read_b128 v[202:205], v149 offset:32768
	ds_read_b128 v[206:209], v149 offset:33792
	ds_read_b128 v[210:213], v149 offset:34816
	ds_read_b128 v[214:217], v149 offset:35840
	ds_read_b128 v[218:221], v149 offset:36864
	ds_read_b128 v[222:225], v149 offset:37888
	ds_read_b128 v[226:229], v149 offset:38912
	ds_read_b128 v[230:233], v149 offset:39936
	global_load_lds_dwordx4 v[240:241], off
	v_lshl_add_u64 v[240:241], s[34:35], 0, v[130:131]
	s_mov_b32 m0, s50
	s_nop 0
	global_load_lds_dwordx4 v[240:241], off
	s_waitcnt vmcnt(8)
	s_waitcnt lgkmcnt(0)
	s_barrier
	s_waitcnt lgkmcnt(0)
	v_mfma_f32_16x16x32_bf16 v[124:127], v[144:147], v[202:205], v[124:127]
	v_mfma_f32_16x16x32_bf16 v[120:123], v[174:177], v[202:205], v[120:123]
	v_mfma_f32_16x16x32_bf16 v[108:111], v[144:147], v[210:213], v[108:111]
	v_mfma_f32_16x16x32_bf16 v[104:107], v[174:177], v[210:213], v[104:107]
	v_mfma_f32_16x16x32_bf16 v[92:95], v[144:147], v[218:221], v[92:95]
	v_mfma_f32_16x16x32_bf16 v[88:91], v[174:177], v[218:221], v[88:91]
	v_mfma_f32_16x16x32_bf16 v[76:79], v[144:147], v[226:229], v[76:79]
	v_mfma_f32_16x16x32_bf16 v[72:75], v[174:177], v[226:229], v[72:75]
	v_mfma_f32_16x16x32_bf16 v[124:127], v[170:173], v[206:209], v[124:127]
	v_mfma_f32_16x16x32_bf16 v[120:123], v[178:181], v[206:209], v[120:123]
	v_mfma_f32_16x16x32_bf16 v[108:111], v[170:173], v[214:217], v[108:111]
	v_mfma_f32_16x16x32_bf16 v[104:107], v[178:181], v[214:217], v[104:107]
	v_mfma_f32_16x16x32_bf16 v[92:95], v[170:173], v[222:225], v[92:95]
	v_mfma_f32_16x16x32_bf16 v[88:91], v[178:181], v[222:225], v[88:91]
	v_mfma_f32_16x16x32_bf16 v[76:79], v[170:173], v[230:233], v[76:79]
	v_mfma_f32_16x16x32_bf16 v[72:75], v[178:181], v[230:233], v[72:75]
	v_mfma_f32_16x16x32_bf16 v[116:119], v[186:189], v[202:205], v[116:119]
	v_mfma_f32_16x16x32_bf16 v[112:115], v[194:197], v[202:205], v[112:115]
	v_mfma_f32_16x16x32_bf16 v[100:103], v[186:189], v[210:213], v[100:103]
	v_mfma_f32_16x16x32_bf16 v[96:99], v[194:197], v[210:213], v[96:99]
	v_mfma_f32_16x16x32_bf16 v[84:87], v[186:189], v[218:221], v[84:87]
	v_mfma_f32_16x16x32_bf16 v[80:83], v[194:197], v[218:221], v[80:83]
	v_mfma_f32_16x16x32_bf16 v[68:71], v[186:189], v[226:229], v[68:71]
	v_mfma_f32_16x16x32_bf16 v[64:67], v[194:197], v[226:229], v[64:67]
	v_mfma_f32_16x16x32_bf16 v[116:119], v[190:193], v[206:209], v[116:119]
	v_mfma_f32_16x16x32_bf16 v[112:115], v[198:201], v[206:209], v[112:115]
	v_mfma_f32_16x16x32_bf16 v[100:103], v[190:193], v[214:217], v[100:103]
	v_mfma_f32_16x16x32_bf16 v[96:99], v[198:201], v[214:217], v[96:99]
	v_mfma_f32_16x16x32_bf16 v[84:87], v[190:193], v[222:225], v[84:87]
	v_mfma_f32_16x16x32_bf16 v[80:83], v[198:201], v[222:225], v[80:83]
	v_mfma_f32_16x16x32_bf16 v[68:71], v[190:193], v[230:233], v[68:71]
	v_mfma_f32_16x16x32_bf16 v[64:67], v[198:201], v[230:233], v[64:67]
	s_barrier
	s_mov_b32 m0, s53
	v_lshl_add_u64 v[182:183], v[182:183], 0, s[16:17]
	s_add_u32 s30, s30, 0x40080
	ds_read_b128 v[202:205], v149 offset:49152
	ds_read_b128 v[206:209], v149 offset:50176
	ds_read_b128 v[210:213], v149 offset:51200
	ds_read_b128 v[214:217], v149 offset:52224
	ds_read_b128 v[218:221], v149 offset:53248
	ds_read_b128 v[222:225], v149 offset:54272
	ds_read_b128 v[226:229], v149 offset:55296
	ds_read_b128 v[230:233], v149 offset:56320
	global_load_lds_dwordx4 v[182:183], off
	v_lshl_add_u64 v[182:183], v[234:235], 0, s[16:17]
	s_mov_b32 m0, s54
	s_addc_u32 s31, s31, 0
	global_load_lds_dwordx4 v[182:183], off
	v_lshl_add_u64 v[182:183], s[30:31], 0, v[132:133]
	s_mov_b32 m0, s57
	s_nop 0
	global_load_lds_dwordx4 v[182:183], off
	v_lshl_add_u64 v[182:183], s[30:31], 0, v[128:129]
	s_mov_b32 m0, s58
	s_nop 0
	global_load_lds_dwordx4 v[182:183], off
	v_lshl_add_u64 v[182:183], v[236:237], 0, s[16:17]
	s_mov_b32 m0, s55
	s_nop 0
	global_load_lds_dwordx4 v[182:183], off
	v_lshl_add_u64 v[182:183], v[238:239], 0, s[16:17]
	s_mov_b32 m0, s56
	s_nop 0
	global_load_lds_dwordx4 v[182:183], off
	s_waitcnt vmcnt(8)
	s_waitcnt lgkmcnt(0)
	s_barrier
	s_waitcnt lgkmcnt(0)
	v_mfma_f32_16x16x32_bf16 v[60:63], v[144:147], v[202:205], v[60:63]
	v_mfma_f32_16x16x32_bf16 v[56:59], v[174:177], v[202:205], v[56:59]
	v_mfma_f32_16x16x32_bf16 v[44:47], v[144:147], v[210:213], v[44:47]
	v_mfma_f32_16x16x32_bf16 v[40:43], v[174:177], v[210:213], v[40:43]
	v_mfma_f32_16x16x32_bf16 v[28:31], v[144:147], v[218:221], v[28:31]
	v_mfma_f32_16x16x32_bf16 v[24:27], v[174:177], v[218:221], v[24:27]
	v_mfma_f32_16x16x32_bf16 v[12:15], v[144:147], v[226:229], v[12:15]
	v_mfma_f32_16x16x32_bf16 v[8:11], v[174:177], v[226:229], v[8:11]
	v_mfma_f32_16x16x32_bf16 v[60:63], v[170:173], v[206:209], v[60:63]
	v_mfma_f32_16x16x32_bf16 v[56:59], v[178:181], v[206:209], v[56:59]
	v_mfma_f32_16x16x32_bf16 v[44:47], v[170:173], v[214:217], v[44:47]
	v_mfma_f32_16x16x32_bf16 v[40:43], v[178:181], v[214:217], v[40:43]
	v_mfma_f32_16x16x32_bf16 v[28:31], v[170:173], v[222:225], v[28:31]
	v_mfma_f32_16x16x32_bf16 v[24:27], v[178:181], v[222:225], v[24:27]
	v_mfma_f32_16x16x32_bf16 v[12:15], v[170:173], v[230:233], v[12:15]
	v_mfma_f32_16x16x32_bf16 v[8:11], v[178:181], v[230:233], v[8:11]
	v_mfma_f32_16x16x32_bf16 v[52:55], v[186:189], v[202:205], v[52:55]
	v_mfma_f32_16x16x32_bf16 v[48:51], v[194:197], v[202:205], v[48:51]
	v_mfma_f32_16x16x32_bf16 v[36:39], v[186:189], v[210:213], v[36:39]
	v_mfma_f32_16x16x32_bf16 v[32:35], v[194:197], v[210:213], v[32:35]
	v_mfma_f32_16x16x32_bf16 v[20:23], v[186:189], v[218:221], v[20:23]
	v_mfma_f32_16x16x32_bf16 v[16:19], v[194:197], v[218:221], v[16:19]
	v_mfma_f32_16x16x32_bf16 v[4:7], v[186:189], v[226:229], v[4:7]
	v_mfma_f32_16x16x32_bf16 v[0:3], v[194:197], v[226:229], v[0:3]
	v_mfma_f32_16x16x32_bf16 v[52:55], v[190:193], v[206:209], v[52:55]
	v_mfma_f32_16x16x32_bf16 v[48:51], v[198:201], v[206:209], v[48:51]
	v_mfma_f32_16x16x32_bf16 v[36:39], v[190:193], v[214:217], v[36:39]
	v_mfma_f32_16x16x32_bf16 v[32:35], v[198:201], v[214:217], v[32:35]
	v_mfma_f32_16x16x32_bf16 v[20:23], v[190:193], v[222:225], v[20:23]
	v_mfma_f32_16x16x32_bf16 v[16:19], v[198:201], v[222:225], v[16:19]
	v_mfma_f32_16x16x32_bf16 v[4:7], v[190:193], v[230:233], v[4:7]
	v_mfma_f32_16x16x32_bf16 v[0:3], v[198:201], v[230:233], v[0:3]
	s_barrier
	s_add_i32 s67, s67, 2
	s_add_u32 s65, s65, 0x100
	s_addc_u32 s66, s66, 0
	s_add_u32 s28, s28, 0x100
	s_addc_u32 s29, s29, 0
	s_cmp_gt_u32 s67, 13
	s_cbranch_scc0 .LBB0_477
	s_and_b64 vcc, exec, s[18:19]
	s_cbranch_vccz .LBB0_480
	s_barrier

; #define PG8_STAGE(bufoff, gbase, voff) do { _Pragma("unroll") for (int _i = 0; _i < 2; ++_i) \
;         __builtin_amdgcn_global_load_lds((const unsigned*)((const char*)(gbase) + (voff)[_i]), (PG8_LAS unsigned*)(lds + (bufoff) + ldsw + _i * 8192), 16, 0, 0); } while (0)
; #define PG8_LDA(dst, b, h) do { _Pragma("unroll") for (int m = 0; m < 4; ++m) _Pragma("unroll") for (int k = 0; k < 2; ++k) dst[m][k] = *(const PG8_LAS bf16x8*)(lds + PG8_SA(b, h) + aoff + m * 2048 + k * 1024); } while (0)
; #define PG8_LDB(dst, b, h) do { _Pragma("unroll") for (int n = 0; n < 2; ++n) _Pragma("unroll") for (int k = 0; k < 2; ++k) dst[n][k] = *(const PG8_LAS bf16x8*)(lds + PG8_SB(b, h) + boff + n * 2048 + k * 1024); } while (0)
; #define PG8_MMA(ai, bj, At, Bt) do { __builtin_amdgcn_s_setprio(1); _Pragma("unroll") for (int m = 0; m < 4; ++m) _Pragma("unroll") for (int n = 0; n < 2; ++n) _Pragma("unroll") for (int k = 0; k < 2; ++k) \
;         acc[ai][bj][m][n] = __builtin_amdgcn_mfma_f32_16x16x32_bf16(Bt[n][k], At[m][k], acc[ai][bj][m][n], 0, 0, 0); __builtin_amdgcn_s_setprio(0); } while (0)
; #define PG8_WAIT_V(n) asm volatile("s_waitcnt vmcnt(" #n ")" ::: "memory")
; #define PG8_WAIT_L(n) asm volatile("s_waitcnt lgkmcnt(" #n ")" ::: "memory")
; template <class Epi, class Sched, bool ALIGN_EPI = false, bool SP2 = false>
; __device__ __forceinline__ void gemm_phase(PG8_LAS unsigned char* lds, const Gemm g, const Sched& S, const Epi& E) {
;     ...
;             const bool last = (t == nt - 2);
;             const char* a1 = cA + (size_t)(t + 1) * kstep;
;             const char* a2 = last ? nA : cA + (size_t)(t + 2) * kstep; const char* b2 = last ? nB : cB + (size_t)(t + 2) * kstep;
;             const char* a3 = a2 + kstep; const char* b3 = b2 + kstep;
;             if (last && has_next) S.a_ready(nxt);
;             if constexpr (SP2) {
;             PG8_LDB(B0, 0, 0); PG8_LDB(B1, 0, 1); PG8_SCHED; PG8_LDA(At, 0, 0); PG8_STAGE(PG8_SA(1, 1), a1 + hstep, voffA);
;             PG8_WAIT_V(8); PG8_WAIT_L(0); PG8_BAR; PG8_MMA(0, 0, At, B0); PG8_MMA(0, 1, At, B1); PG8_BAR; PG8_SCHED;
;             PG8_LDA(At, 0, 1); PG8_STAGE(PG8_SB(0, 0), b2, voffB); PG8_STAGE(PG8_SB(0, 1), b2 + hstep, voffB); PG8_STAGE(PG8_SA(0, 0), a2, voffA);
;             PG8_WAIT_V(8); PG8_WAIT_L(0); PG8_BAR; PG8_MMA(1, 0, At, B0); PG8_MMA(1, 1, At, B1); PG8_BAR; PG8_SCHED;
.LBB0_558:
	ds_read_b128 v[144:147], v151
	ds_read_b128 v[168:171], v152
	ds_read_b128 v[172:175], v153
	ds_read_b128 v[176:179], v154
	ds_read_b128 v[180:183], v155
	ds_read_b128 v[186:189], v156
	ds_read_b128 v[190:193], v157
	ds_read_b128 v[194:197], v158
	s_add_u32 s36, s34, 0xfff00080
	s_addc_u32 s37, s35, -1
	s_cmp_eq_u32 s70, 60
	s_cselect_b32 s43, s25, s37
	s_cselect_b32 s42, s31, s36
	s_cselect_b32 s37, s23, s69
	s_cselect_b32 s36, s67, s68
	s_mov_b32 m0, s64
	v_lshl_add_u64 v[230:231], s[34:35], 0, v[138:139]
	ds_read_b128 v[198:201], v149
	ds_read_b128 v[202:205], v149 offset:1024
	ds_read_b128 v[206:209], v149 offset:2048
	ds_read_b128 v[210:213], v149 offset:3072
	ds_read_b128 v[214:217], v149 offset:4096
	ds_read_b128 v[218:221], v149 offset:5120
	ds_read_b128 v[222:225], v149 offset:6144
	ds_read_b128 v[226:229], v149 offset:7168
	global_load_lds_dwordx4 v[230:231], off
	v_lshl_add_u64 v[230:231], s[34:35], 0, v[136:137]
	s_mov_b32 m0, s65
	s_nop 0
	global_load_lds_dwordx4 v[230:231], off
	s_waitcnt vmcnt(8)
	s_waitcnt lgkmcnt(0)
	s_barrier
	s_waitcnt lgkmcnt(0)
	v_mfma_f32_16x16x32_bf16 v[124:127], v[144:147], v[198:201], v[124:127]
	v_mfma_f32_16x16x32_bf16 v[120:123], v[172:175], v[198:201], v[120:123]
	v_mfma_f32_16x16x32_bf16 v[108:111], v[144:147], v[206:209], v[108:111]
	v_mfma_f32_16x16x32_bf16 v[104:107], v[172:175], v[206:209], v[104:107]
	v_mfma_f32_16x16x32_bf16 v[92:95], v[144:147], v[214:217], v[92:95]
	v_mfma_f32_16x16x32_bf16 v[88:91], v[172:175], v[214:217], v[88:91]
	v_mfma_f32_16x16x32_bf16 v[76:79], v[144:147], v[222:225], v[76:79]
	v_mfma_f32_16x16x32_bf16 v[72:75], v[172:175], v[222:225], v[72:75]
	v_mfma_f32_16x16x32_bf16 v[124:127], v[168:171], v[202:205], v[124:127]
	v_mfma_f32_16x16x32_bf16 v[120:123], v[176:179], v[202:205], v[120:123]
	v_mfma_f32_16x16x32_bf16 v[108:111], v[168:171], v[210:213], v[108:111]
	v_mfma_f32_16x16x32_bf16 v[104:107], v[176:179], v[210:213], v[104:107]
	v_mfma_f32_16x16x32_bf16 v[92:95], v[168:171], v[218:221], v[92:95]
	v_mfma_f32_16x16x32_bf16 v[88:91], v[176:179], v[218:221], v[88:91]
	v_mfma_f32_16x16x32_bf16 v[76:79], v[168:171], v[226:229], v[76:79]
	v_mfma_f32_16x16x32_bf16 v[72:75], v[176:179], v[226:229], v[72:75]
	v_mfma_f32_16x16x32_bf16 v[116:119], v[180:183], v[198:201], v[116:119]
	v_mfma_f32_16x16x32_bf16 v[112:115], v[190:193], v[198:201], v[112:115]
	v_mfma_f32_16x16x32_bf16 v[100:103], v[180:183], v[206:209], v[100:103]
	v_mfma_f32_16x16x32_bf16 v[96:99], v[190:193], v[206:209], v[96:99]
	v_mfma_f32_16x16x32_bf16 v[84:87], v[180:183], v[214:217], v[84:87]
	v_mfma_f32_16x16x32_bf16 v[80:83], v[190:193], v[214:217], v[80:83]
	v_mfma_f32_16x16x32_bf16 v[68:71], v[180:183], v[222:225], v[68:71]
	v_mfma_f32_16x16x32_bf16 v[64:67], v[190:193], v[222:225], v[64:67]
	v_mfma_f32_16x16x32_bf16 v[116:119], v[186:189], v[202:205], v[116:119]
	v_mfma_f32_16x16x32_bf16 v[112:115], v[194:197], v[202:205], v[112:115]
	v_mfma_f32_16x16x32_bf16 v[100:103], v[186:189], v[210:213], v[100:103]
	v_mfma_f32_16x16x32_bf16 v[96:99], v[194:197], v[210:213], v[96:99]
	v_mfma_f32_16x16x32_bf16 v[84:87], v[186:189], v[218:221], v[84:87]
	v_mfma_f32_16x16x32_bf16 v[80:83], v[194:197], v[218:221], v[80:83]
	v_mfma_f32_16x16x32_bf16 v[68:71], v[186:189], v[226:229], v[68:71]
	v_mfma_f32_16x16x32_bf16 v[64:67], v[194:197], v[226:229], v[64:67]
	s_barrier
	s_mov_b32 m0, s48
	v_lshl_add_u64 v[230:231], s[36:37], 0, v[130:131]
	s_add_u32 s72, s36, 0x100000
	ds_read_b128 v[198:201], v149 offset:16384
	ds_read_b128 v[202:205], v149 offset:17408
	ds_read_b128 v[206:209], v149 offset:18432
	ds_read_b128 v[210:213], v149 offset:19456
	ds_read_b128 v[214:217], v149 offset:20480
	ds_read_b128 v[218:221], v149 offset:21504
	ds_read_b128 v[222:225], v149 offset:22528
	ds_read_b128 v[226:229], v149 offset:23552
	global_load_lds_dwordx4 v[230:231], off
	v_lshl_add_u64 v[232:233], s[36:37], 0, v[134:135]
	s_mov_b32 m0, s49
	s_addc_u32 s73, s37, 0
	global_load_lds_dwordx4 v[232:233], off
	v_lshl_add_u64 v[234:235], s[72:73], 0, v[130:131]
	s_mov_b32 m0, s50
	v_lshl_add_u64 v[236:237], s[42:43], 0, v[132:133]
	global_load_lds_dwordx4 v[234:235], off
	v_lshl_add_u64 v[234:235], s[72:73], 0, v[134:135]
	s_mov_b32 m0, s51
	s_nop 0
	global_load_lds_dwordx4 v[234:235], off
	v_lshl_add_u64 v[234:235], s[42:43], 0, v[128:129]
	s_mov_b32 m0, s47
	s_nop 0
	global_load_lds_dwordx4 v[234:235], off
	s_mov_b32 m0, s52
	s_nop 0
	global_load_lds_dwordx4 v[236:237], off
	s_waitcnt vmcnt(8)
	s_waitcnt lgkmcnt(0)
	s_barrier
	s_waitcnt lgkmcnt(0)
	v_mfma_f32_16x16x32_bf16 v[60:63], v[144:147], v[198:201], v[60:63]
	v_mfma_f32_16x16x32_bf16 v[56:59], v[172:175], v[198:201], v[56:59]
	v_mfma_f32_16x16x32_bf16 v[44:47], v[144:147], v[206:209], v[44:47]
	v_mfma_f32_16x16x32_bf16 v[40:43], v[172:175], v[206:209], v[40:43]
	v_mfma_f32_16x16x32_bf16 v[28:31], v[144:147], v[214:217], v[28:31]
	v_mfma_f32_16x16x32_bf16 v[24:27], v[172:175], v[214:217], v[24:27]
	v_mfma_f32_16x16x32_bf16 v[12:15], v[144:147], v[222:225], v[12:15]
	v_mfma_f32_16x16x32_bf16 v[8:11], v[172:175], v[222:225], v[8:11]
	v_mfma_f32_16x16x32_bf16 v[60:63], v[168:171], v[202:205], v[60:63]
	v_mfma_f32_16x16x32_bf16 v[56:59], v[176:179], v[202:205], v[56:59]
	v_mfma_f32_16x16x32_bf16 v[44:47], v[168:171], v[210:213], v[44:47]
	v_mfma_f32_16x16x32_bf16 v[40:43], v[176:179], v[210:213], v[40:43]
	v_mfma_f32_16x16x32_bf16 v[28:31], v[168:171], v[218:221], v[28:31]
	v_mfma_f32_16x16x32_bf16 v[24:27], v[176:179], v[218:221], v[24:27]
	v_mfma_f32_16x16x32_bf16 v[12:15], v[168:171], v[226:229], v[12:15]
	v_mfma_f32_16x16x32_bf16 v[8:11], v[176:179], v[226:229], v[8:11]
	v_mfma_f32_16x16x32_bf16 v[52:55], v[180:183], v[198:201], v[52:55]
	v_mfma_f32_16x16x32_bf16 v[48:51], v[190:193], v[198:201], v[48:51]
	v_mfma_f32_16x16x32_bf16 v[36:39], v[180:183], v[206:209], v[36:39]
	v_mfma_f32_16x16x32_bf16 v[32:35], v[190:193], v[206:209], v[32:35]
	v_mfma_f32_16x16x32_bf16 v[20:23], v[180:183], v[214:217], v[20:23]
	v_mfma_f32_16x16x32_bf16 v[16:19], v[190:193], v[214:217], v[16:19]
	v_mfma_f32_16x16x32_bf16 v[4:7], v[180:183], v[222:225], v[4:7]
	v_mfma_f32_16x16x32_bf16 v[0:3], v[190:193], v[222:225], v[0:3]
	v_mfma_f32_16x16x32_bf16 v[52:55], v[186:189], v[202:205], v[52:55]
	v_mfma_f32_16x16x32_bf16 v[48:51], v[194:197], v[202:205], v[48:51]
	v_mfma_f32_16x16x32_bf16 v[36:39], v[186:189], v[210:213], v[36:39]
	v_mfma_f32_16x16x32_bf16 v[32:35], v[194:197], v[210:213], v[32:35]
	v_mfma_f32_16x16x32_bf16 v[20:23], v[186:189], v[218:221], v[20:23]
	v_mfma_f32_16x16x32_bf16 v[16:19], v[194:197], v[218:221], v[16:19]
	v_mfma_f32_16x16x32_bf16 v[4:7], v[186:189], v[226:229], v[4:7]
	v_mfma_f32_16x16x32_bf16 v[0:3], v[194:197], v[226:229], v[0:3]
	s_barrier
; #define PG8_STAGE(bufoff, gbase, voff) do { _Pragma("unroll") for (int _i = 0; _i < 2; ++_i) \
;         __builtin_amdgcn_global_load_lds((const unsigned*)((const char*)(gbase) + (voff)[_i]), (PG8_LAS unsigned*)(lds + (bufoff) + ldsw + _i * 8192), 16, 0, 0); } while (0)
; #define PG8_LDA(dst, b, h) do { _Pragma("unroll") for (int m = 0; m < 4; ++m) _Pragma("unroll") for (int k = 0; k < 2; ++k) dst[m][k] = *(const PG8_LAS bf16x8*)(lds + PG8_SA(b, h) + aoff + m * 2048 + k * 1024); } while (0)
; #define PG8_LDB(dst, b, h) do { _Pragma("unroll") for (int n = 0; n < 2; ++n) _Pragma("unroll") for (int k = 0; k < 2; ++k) dst[n][k] = *(const PG8_LAS bf16x8*)(lds + PG8_SB(b, h) + boff + n * 2048 + k * 1024); } while (0)
; #define PG8_MMA(ai, bj, At, Bt) do { __builtin_amdgcn_s_setprio(1); _Pragma("unroll") for (int m = 0; m < 4; ++m) _Pragma("unroll") for (int n = 0; n < 2; ++n) _Pragma("unroll") for (int k = 0; k < 2; ++k) \
;         acc[ai][bj][m][n] = __builtin_amdgcn_mfma_f32_16x16x32_bf16(Bt[n][k], At[m][k], acc[ai][bj][m][n], 0, 0, 0); __builtin_amdgcn_s_setprio(0); } while (0)
; #define PG8_WAIT_V(n) asm volatile("s_waitcnt vmcnt(" #n ")" ::: "memory")
; #define PG8_WAIT_L(n) asm volatile("s_waitcnt lgkmcnt(" #n ")" ::: "memory")
; #define PG8_BAR __builtin_amdgcn_s_barrier()
; #define PG8_SCHED __builtin_amdgcn_sched_barrier(0)
; template <class Epi, class Sched, bool ALIGN_EPI = false, bool SP2 = false>
; __device__ __forceinline__ void gemm_phase(PG8_LAS unsigned char* lds, const Gemm g, const Sched& S, const Epi& E) {
;     ...
;             PG8_LDB(B0, 1, 0); PG8_LDB(B1, 1, 1); PG8_SCHED; PG8_LDA(At, 1, 0); PG8_STAGE(PG8_SA(0, 1), a2 + hstep, voffA);
;             PG8_WAIT_V(8); PG8_WAIT_L(0); PG8_BAR; PG8_MMA(0, 0, At, B0); PG8_MMA(0, 1, At, B1); PG8_BAR; PG8_SCHED;
;             PG8_LDA(At, 1, 1); PG8_STAGE(PG8_SB(1, 0), b3, voffB); PG8_STAGE(PG8_SB(1, 1), b3 + hstep, voffB); PG8_STAGE(PG8_SA(1, 0), a3, voffA);
;             PG8_WAIT_V(8); PG8_WAIT_L(0); PG8_BAR; PG8_MMA(1, 0, At, B0); PG8_MMA(1, 1, At, B1); PG8_BAR; PG8_SCHED;
	ds_read_b128 v[144:147], v159
	ds_read_b128 v[168:171], v160
	ds_read_b128 v[172:175], v161
	ds_read_b128 v[176:179], v162
	ds_read_b128 v[180:183], v163
	ds_read_b128 v[186:189], v164
	ds_read_b128 v[190:193], v165
	ds_read_b128 v[194:197], v166
	s_add_u32 s42, s42, 0x100000
	s_addc_u32 s43, s43, 0
	s_mov_b32 m0, s53
	v_lshl_add_u64 v[238:239], s[42:43], 0, v[128:129]
	ds_read_b128 v[198:201], v149 offset:32768
	ds_read_b128 v[202:205], v149 offset:33792
	ds_read_b128 v[206:209], v149 offset:34816
	ds_read_b128 v[210:213], v149 offset:35840
	ds_read_b128 v[214:217], v149 offset:36864
	ds_read_b128 v[218:221], v149 offset:37888
	ds_read_b128 v[222:225], v149 offset:38912
	ds_read_b128 v[226:229], v149 offset:39936
	global_load_lds_dwordx4 v[238:239], off
	v_lshl_add_u64 v[238:239], s[42:43], 0, v[132:133]
	s_mov_b32 m0, s54
	s_nop 0
	global_load_lds_dwordx4 v[238:239], off
	s_waitcnt vmcnt(8)
	s_waitcnt lgkmcnt(0)
	s_barrier
	s_waitcnt lgkmcnt(0)
	v_mfma_f32_16x16x32_bf16 v[124:127], v[144:147], v[198:201], v[124:127]
	v_mfma_f32_16x16x32_bf16 v[120:123], v[172:175], v[198:201], v[120:123]
	v_mfma_f32_16x16x32_bf16 v[108:111], v[144:147], v[206:209], v[108:111]
	v_mfma_f32_16x16x32_bf16 v[104:107], v[172:175], v[206:209], v[104:107]
	v_mfma_f32_16x16x32_bf16 v[92:95], v[144:147], v[214:217], v[92:95]
	v_mfma_f32_16x16x32_bf16 v[88:91], v[172:175], v[214:217], v[88:91]
	v_mfma_f32_16x16x32_bf16 v[76:79], v[144:147], v[222:225], v[76:79]
	v_mfma_f32_16x16x32_bf16 v[72:75], v[172:175], v[222:225], v[72:75]
	v_mfma_f32_16x16x32_bf16 v[124:127], v[168:171], v[202:205], v[124:127]
	v_mfma_f32_16x16x32_bf16 v[120:123], v[176:179], v[202:205], v[120:123]
	v_mfma_f32_16x16x32_bf16 v[108:111], v[168:171], v[210:213], v[108:111]
	v_mfma_f32_16x16x32_bf16 v[104:107], v[176:179], v[210:213], v[104:107]
	v_mfma_f32_16x16x32_bf16 v[92:95], v[168:171], v[218:221], v[92:95]
	v_mfma_f32_16x16x32_bf16 v[88:91], v[176:179], v[218:221], v[88:91]
	v_mfma_f32_16x16x32_bf16 v[76:79], v[168:171], v[226:229], v[76:79]
	v_mfma_f32_16x16x32_bf16 v[72:75], v[176:179], v[226:229], v[72:75]
	v_mfma_f32_16x16x32_bf16 v[116:119], v[180:183], v[198:201], v[116:119]
	v_mfma_f32_16x16x32_bf16 v[112:115], v[190:193], v[198:201], v[112:115]
	v_mfma_f32_16x16x32_bf16 v[100:103], v[180:183], v[206:209], v[100:103]
	v_mfma_f32_16x16x32_bf16 v[96:99], v[190:193], v[206:209], v[96:99]
	v_mfma_f32_16x16x32_bf16 v[84:87], v[180:183], v[214:217], v[84:87]
	v_mfma_f32_16x16x32_bf16 v[80:83], v[190:193], v[214:217], v[80:83]
	v_mfma_f32_16x16x32_bf16 v[68:71], v[180:183], v[222:225], v[68:71]
	v_mfma_f32_16x16x32_bf16 v[64:67], v[190:193], v[222:225], v[64:67]
	v_mfma_f32_16x16x32_bf16 v[116:119], v[186:189], v[202:205], v[116:119]
	v_mfma_f32_16x16x32_bf16 v[112:115], v[194:197], v[202:205], v[112:115]
	v_mfma_f32_16x16x32_bf16 v[100:103], v[186:189], v[210:213], v[100:103]
	v_mfma_f32_16x16x32_bf16 v[96:99], v[194:197], v[210:213], v[96:99]
	v_mfma_f32_16x16x32_bf16 v[84:87], v[186:189], v[218:221], v[84:87]
	v_mfma_f32_16x16x32_bf16 v[80:83], v[194:197], v[218:221], v[80:83]
	v_mfma_f32_16x16x32_bf16 v[68:71], v[186:189], v[226:229], v[68:71]
	v_mfma_f32_16x16x32_bf16 v[64:67], v[194:197], v[226:229], v[64:67]
	s_barrier
	s_mov_b32 m0, s56
	v_lshl_add_u64 v[230:231], v[230:231], 0, s[16:17]
	s_add_u32 s36, s36, 0x100080
	ds_read_b128 v[198:201], v149 offset:49152
	ds_read_b128 v[202:205], v149 offset:50176
	ds_read_b128 v[206:209], v149 offset:51200
	ds_read_b128 v[210:213], v149 offset:52224
	ds_read_b128 v[214:217], v149 offset:53248
	ds_read_b128 v[218:221], v149 offset:54272
	ds_read_b128 v[222:225], v149 offset:55296
	ds_read_b128 v[226:229], v149 offset:56320
	global_load_lds_dwordx4 v[230:231], off
	v_lshl_add_u64 v[230:231], v[232:233], 0, s[16:17]
	s_mov_b32 m0, s57
	s_addc_u32 s37, s37, 0
	global_load_lds_dwordx4 v[230:231], off
	v_lshl_add_u64 v[230:231], s[36:37], 0, v[130:131]
	s_mov_b32 m0, s60
	s_nop 0
	global_load_lds_dwordx4 v[230:231], off
	v_lshl_add_u64 v[230:231], s[36:37], 0, v[134:135]
	s_mov_b32 m0, s61
	s_nop 0
	global_load_lds_dwordx4 v[230:231], off
	v_lshl_add_u64 v[230:231], v[234:235], 0, s[16:17]
	s_mov_b32 m0, s58
	s_nop 0
	global_load_lds_dwordx4 v[230:231], off
	v_lshl_add_u64 v[230:231], v[236:237], 0, s[16:17]
	s_mov_b32 m0, s59
	s_nop 0
	global_load_lds_dwordx4 v[230:231], off
	s_waitcnt vmcnt(8)
	s_waitcnt lgkmcnt(0)
	s_barrier
	s_waitcnt lgkmcnt(0)
	v_mfma_f32_16x16x32_bf16 v[60:63], v[144:147], v[198:201], v[60:63]
	v_mfma_f32_16x16x32_bf16 v[56:59], v[172:175], v[198:201], v[56:59]
	v_mfma_f32_16x16x32_bf16 v[44:47], v[144:147], v[206:209], v[44:47]
	v_mfma_f32_16x16x32_bf16 v[40:43], v[172:175], v[206:209], v[40:43]
	v_mfma_f32_16x16x32_bf16 v[28:31], v[144:147], v[214:217], v[28:31]
	v_mfma_f32_16x16x32_bf16 v[24:27], v[172:175], v[214:217], v[24:27]
	v_mfma_f32_16x16x32_bf16 v[12:15], v[144:147], v[222:225], v[12:15]
	v_mfma_f32_16x16x32_bf16 v[8:11], v[172:175], v[222:225], v[8:11]
	v_mfma_f32_16x16x32_bf16 v[60:63], v[168:171], v[202:205], v[60:63]
	v_mfma_f32_16x16x32_bf16 v[56:59], v[176:179], v[202:205], v[56:59]
	v_mfma_f32_16x16x32_bf16 v[44:47], v[168:171], v[210:213], v[44:47]
	v_mfma_f32_16x16x32_bf16 v[40:43], v[176:179], v[210:213], v[40:43]
	v_mfma_f32_16x16x32_bf16 v[28:31], v[168:171], v[218:221], v[28:31]
	v_mfma_f32_16x16x32_bf16 v[24:27], v[176:179], v[218:221], v[24:27]
	v_mfma_f32_16x16x32_bf16 v[12:15], v[168:171], v[226:229], v[12:15]
	v_mfma_f32_16x16x32_bf16 v[8:11], v[176:179], v[226:229], v[8:11]
	v_mfma_f32_16x16x32_bf16 v[52:55], v[180:183], v[198:201], v[52:55]
	v_mfma_f32_16x16x32_bf16 v[48:51], v[190:193], v[198:201], v[48:51]
	v_mfma_f32_16x16x32_bf16 v[36:39], v[180:183], v[206:209], v[36:39]
	v_mfma_f32_16x16x32_bf16 v[32:35], v[190:193], v[206:209], v[32:35]
	v_mfma_f32_16x16x32_bf16 v[20:23], v[180:183], v[214:217], v[20:23]
	v_mfma_f32_16x16x32_bf16 v[16:19], v[190:193], v[214:217], v[16:19]
	v_mfma_f32_16x16x32_bf16 v[4:7], v[180:183], v[222:225], v[4:7]
	v_mfma_f32_16x16x32_bf16 v[0:3], v[190:193], v[222:225], v[0:3]
	v_mfma_f32_16x16x32_bf16 v[52:55], v[186:189], v[202:205], v[52:55]
	v_mfma_f32_16x16x32_bf16 v[48:51], v[194:197], v[202:205], v[48:51]
	v_mfma_f32_16x16x32_bf16 v[36:39], v[186:189], v[210:213], v[36:39]
	v_mfma_f32_16x16x32_bf16 v[32:35], v[194:197], v[210:213], v[32:35]
	v_mfma_f32_16x16x32_bf16 v[20:23], v[186:189], v[218:221], v[20:23]
	v_mfma_f32_16x16x32_bf16 v[16:19], v[194:197], v[218:221], v[16:19]
	v_mfma_f32_16x16x32_bf16 v[4:7], v[186:189], v[226:229], v[4:7]
	v_mfma_f32_16x16x32_bf16 v[0:3], v[194:197], v[226:229], v[0:3]
	s_barrier
	s_add_i32 s70, s70, 2
	s_add_u32 s68, s68, 0x100
	s_addc_u32 s69, s69, 0
	s_add_u32 s34, s34, 0x100
	s_addc_u32 s35, s35, 0
	s_cmp_gt_u32 s70, 61
	s_cbranch_scc0 .LBB0_558
	s_and_b64 vcc, exec, s[18:19]
	s_cbranch_vccz .LBB0_561
	s_barrier

; #define PG8_STAGE(bufoff, gbase, voff) do { _Pragma("unroll") for (int _i = 0; _i < 2; ++_i) \
;         __builtin_amdgcn_global_load_lds((const unsigned*)((const char*)(gbase) + (voff)[_i]), (PG8_LAS unsigned*)(lds + (bufoff) + ldsw + _i * 8192), 16, 0, 0); } while (0)
; #define PG8_LDA(dst, b, h) do { _Pragma("unroll") for (int m = 0; m < 4; ++m) _Pragma("unroll") for (int k = 0; k < 2; ++k) dst[m][k] = *(const PG8_LAS bf16x8*)(lds + PG8_SA(b, h) + aoff + m * 2048 + k * 1024); } while (0)
; #define PG8_LDB(dst, b, h) do { _Pragma("unroll") for (int n = 0; n < 2; ++n) _Pragma("unroll") for (int k = 0; k < 2; ++k) dst[n][k] = *(const PG8_LAS bf16x8*)(lds + PG8_SB(b, h) + boff + n * 2048 + k * 1024); } while (0)
; #define PG8_WAIT_V(n) asm volatile("s_waitcnt vmcnt(" #n ")" ::: "memory")
; #define PG8_WAIT_L(n) asm volatile("s_waitcnt lgkmcnt(" #n ")" ::: "memory")
; #define PG8_BAR __builtin_amdgcn_s_barrier()
; #define PG8_SCHED __builtin_amdgcn_sched_barrier(0)
; template <class Epi, class Sched, bool ALIGN_EPI = false, bool SP2 = false>
; __device__ __forceinline__ void gemm_phase(PG8_LAS unsigned char* lds, const Gemm g, const Sched& S, const Epi& E) {
;     ...
;         const char* nA = has_next ? (const char*)g.A + (size_t)nxt.pm * tstep : cA; const char* nB = has_next ? (const char*)g.Bt + (size_t)nxt.pn * tstep : cB;
;         for (int t = 0; t < nt; t += 2) {
;             const bool last = (t == nt - 2);
;             const char* a1 = cA + (size_t)(t + 1) * kstep;
;             const char* a2 = last ? nA : cA + (size_t)(t + 2) * kstep; const char* b2 = last ? nB : cB + (size_t)(t + 2) * kstep;
;             const char* a3 = a2 + kstep; const char* b3 = b2 + kstep;
;             if (last && has_next) S.a_ready(nxt);
;             if constexpr (SP2) {
;             PG8_LDB(B0, 0, 0); PG8_LDB(B1, 0, 1); PG8_SCHED; PG8_LDA(At, 0, 0); PG8_STAGE(PG8_SA(1, 1), a1 + hstep, voffA);
;             PG8_WAIT_V(8); PG8_WAIT_L(0); PG8_BAR; PG8_MMA(0, 0, At, B0); PG8_MMA(0, 1, At, B1); PG8_BAR; PG8_SCHED;
;             PG8_LDA(At, 0, 1); PG8_STAGE(PG8_SB(0, 0), b2, voffB); PG8_STAGE(PG8_SB(0, 1), b2 + hstep, voffB); PG8_STAGE(PG8_SA(0, 0), a2, voffA);
;             PG8_WAIT_V(8); PG8_WAIT_L(0); PG8_BAR; PG8_MMA(1, 0, At, B0); PG8_MMA(1, 1, At, B1); PG8_BAR; PG8_SCHED;
.LBB0_645:
	s_add_u32 s54, s36, s52
	s_addc_u32 s55, s37, 0
	s_add_u32 s53, s54, 0x100
	s_addc_u32 s56, s55, 0
	s_and_b64 s[50:51], s[48:49], exec
	s_cselect_b32 s51, s31, s56
	s_cselect_b32 s50, s86, s53
	s_add_u32 s52, s34, s52
	s_addc_u32 s53, s35, 0
	ds_read_b128 v[160:163], v143
	ds_read_b128 v[164:167], v144
	ds_read_b128 v[168:171], v145
	ds_read_b128 v[172:175], v146
	ds_read_b128 v[176:179], v147
	ds_read_b128 v[180:183], v148
	ds_read_b128 v[186:189], v149
	ds_read_b128 v[190:193], v150
	s_add_u32 s52, s52, 0x100
	s_addc_u32 s53, s53, 0
	s_and_b64 s[48:49], s[48:49], exec
	s_cselect_b32 s53, s29, s53
	s_cselect_b32 s52, s87, s52
	s_add_u32 s58, s54, 0x10080
	s_addc_u32 s59, s55, 0
	s_add_u32 s54, s52, 0x10000
	s_addc_u32 s55, s53, 0
	s_add_u32 s48, s50, 0x10000
	s_addc_u32 s49, s51, 0
	s_add_u32 s56, s52, 0x10080
	s_addc_u32 s57, s53, 0
	s_mov_b32 m0, s79
	v_lshl_add_u64 v[226:227], s[58:59], 0, v[134:135]
	ds_read_b128 v[194:197], v141
	ds_read_b128 v[198:201], v141 offset:1024
	ds_read_b128 v[202:205], v141 offset:2048
	ds_read_b128 v[206:209], v141 offset:3072
	ds_read_b128 v[210:213], v141 offset:4096
	ds_read_b128 v[214:217], v141 offset:5120
	ds_read_b128 v[218:221], v141 offset:6144
	ds_read_b128 v[222:225], v141 offset:7168
	global_load_lds_dwordx4 v[226:227], off
	v_lshl_add_u64 v[226:227], s[58:59], 0, v[130:131]
	s_mov_b32 m0, s80
	s_nop 0
	global_load_lds_dwordx4 v[226:227], off
	s_waitcnt vmcnt(8)
	s_waitcnt lgkmcnt(0)
	s_barrier
	s_waitcnt lgkmcnt(0)
	v_mfma_f32_16x16x32_bf16 v[124:127], v[160:163], v[194:197], v[124:127]
	v_mfma_f32_16x16x32_bf16 v[120:123], v[168:171], v[194:197], v[120:123]
	v_mfma_f32_16x16x32_bf16 v[116:119], v[160:163], v[202:205], v[116:119]
	v_mfma_f32_16x16x32_bf16 v[112:115], v[168:171], v[202:205], v[112:115]
	v_mfma_f32_16x16x32_bf16 v[100:103], v[160:163], v[210:213], v[100:103]
	v_mfma_f32_16x16x32_bf16 v[96:99], v[168:171], v[210:213], v[96:99]
	v_mfma_f32_16x16x32_bf16 v[84:87], v[160:163], v[218:221], v[84:87]
	v_mfma_f32_16x16x32_bf16 v[80:83], v[168:171], v[218:221], v[80:83]
	v_mfma_f32_16x16x32_bf16 v[124:127], v[164:167], v[198:201], v[124:127]
	v_mfma_f32_16x16x32_bf16 v[120:123], v[172:175], v[198:201], v[120:123]
	v_mfma_f32_16x16x32_bf16 v[116:119], v[164:167], v[206:209], v[116:119]
	v_mfma_f32_16x16x32_bf16 v[112:115], v[172:175], v[206:209], v[112:115]
	v_mfma_f32_16x16x32_bf16 v[100:103], v[164:167], v[214:217], v[100:103]
	v_mfma_f32_16x16x32_bf16 v[96:99], v[172:175], v[214:217], v[96:99]
	v_mfma_f32_16x16x32_bf16 v[84:87], v[164:167], v[222:225], v[84:87]
	v_mfma_f32_16x16x32_bf16 v[80:83], v[172:175], v[222:225], v[80:83]
	v_mfma_f32_16x16x32_bf16 v[108:111], v[176:179], v[194:197], v[108:111]
	v_mfma_f32_16x16x32_bf16 v[104:107], v[186:189], v[194:197], v[104:107]
	v_mfma_f32_16x16x32_bf16 v[92:95], v[176:179], v[202:205], v[92:95]
	v_mfma_f32_16x16x32_bf16 v[88:91], v[186:189], v[202:205], v[88:91]
	v_mfma_f32_16x16x32_bf16 v[76:79], v[176:179], v[210:213], v[76:79]
	v_mfma_f32_16x16x32_bf16 v[72:75], v[186:189], v[210:213], v[72:75]
	v_mfma_f32_16x16x32_bf16 v[68:71], v[176:179], v[218:221], v[68:71]
	v_mfma_f32_16x16x32_bf16 v[64:67], v[186:189], v[218:221], v[64:67]
	v_mfma_f32_16x16x32_bf16 v[108:111], v[180:183], v[198:201], v[108:111]
	v_mfma_f32_16x16x32_bf16 v[104:107], v[190:193], v[198:201], v[104:107]
	v_mfma_f32_16x16x32_bf16 v[92:95], v[180:183], v[206:209], v[92:95]
	v_mfma_f32_16x16x32_bf16 v[88:91], v[190:193], v[206:209], v[88:91]
	v_mfma_f32_16x16x32_bf16 v[76:79], v[180:183], v[214:217], v[76:79]
	v_mfma_f32_16x16x32_bf16 v[72:75], v[190:193], v[214:217], v[72:75]
	v_mfma_f32_16x16x32_bf16 v[68:71], v[180:183], v[222:225], v[68:71]
	v_mfma_f32_16x16x32_bf16 v[64:67], v[190:193], v[222:225], v[64:67]
	s_barrier
	s_mov_b32 m0, s27
	v_lshl_add_u64 v[226:227], s[52:53], 0, v[132:133]
	ds_read_b128 v[194:197], v141 offset:16384
	ds_read_b128 v[198:201], v141 offset:17408
	ds_read_b128 v[202:205], v141 offset:18432
	ds_read_b128 v[206:209], v141 offset:19456
	ds_read_b128 v[210:213], v141 offset:20480
	ds_read_b128 v[214:217], v141 offset:21504
	ds_read_b128 v[218:221], v141 offset:22528
	ds_read_b128 v[222:225], v141 offset:23552
	global_load_lds_dwordx4 v[226:227], off
	v_lshl_add_u64 v[228:229], s[52:53], 0, v[128:129]
	s_mov_b32 m0, s65
	v_lshl_add_u64 v[230:231], s[54:55], 0, v[132:133]
	global_load_lds_dwordx4 v[228:229], off
	s_mov_b32 m0, s66
	v_lshl_add_u64 v[232:233], s[50:51], 0, v[130:131]
	global_load_lds_dwordx4 v[230:231], off
	v_lshl_add_u64 v[230:231], s[54:55], 0, v[128:129]
	s_mov_b32 m0, s67
	s_nop 0
	global_load_lds_dwordx4 v[230:231], off
	v_lshl_add_u64 v[230:231], s[50:51], 0, v[134:135]
	s_mov_b32 m0, s63
	s_nop 0
	global_load_lds_dwordx4 v[230:231], off
	s_mov_b32 m0, s68
	s_nop 0
	global_load_lds_dwordx4 v[232:233], off
	s_waitcnt vmcnt(8)
	s_waitcnt lgkmcnt(0)
	s_barrier
; #define PG8_STAGE(bufoff, gbase, voff) do { _Pragma("unroll") for (int _i = 0; _i < 2; ++_i) \
;         __builtin_amdgcn_global_load_lds((const unsigned*)((const char*)(gbase) + (voff)[_i]), (PG8_LAS unsigned*)(lds + (bufoff) + ldsw + _i * 8192), 16, 0, 0); } while (0)
; #define PG8_LDA(dst, b, h) do { _Pragma("unroll") for (int m = 0; m < 4; ++m) _Pragma("unroll") for (int k = 0; k < 2; ++k) dst[m][k] = *(const PG8_LAS bf16x8*)(lds + PG8_SA(b, h) + aoff + m * 2048 + k * 1024); } while (0)
; #define PG8_LDB(dst, b, h) do { _Pragma("unroll") for (int n = 0; n < 2; ++n) _Pragma("unroll") for (int k = 0; k < 2; ++k) dst[n][k] = *(const PG8_LAS bf16x8*)(lds + PG8_SB(b, h) + boff + n * 2048 + k * 1024); } while (0)
; #define PG8_MMA(ai, bj, At, Bt) do { __builtin_amdgcn_s_setprio(1); _Pragma("unroll") for (int m = 0; m < 4; ++m) _Pragma("unroll") for (int n = 0; n < 2; ++n) _Pragma("unroll") for (int k = 0; k < 2; ++k) \
;         acc[ai][bj][m][n] = __builtin_amdgcn_mfma_f32_16x16x32_bf16(Bt[n][k], At[m][k], acc[ai][bj][m][n], 0, 0, 0); __builtin_amdgcn_s_setprio(0); } while (0)
; #define PG8_WAIT_V(n) asm volatile("s_waitcnt vmcnt(" #n ")" ::: "memory")
; #define PG8_WAIT_L(n) asm volatile("s_waitcnt lgkmcnt(" #n ")" ::: "memory")
; #define PG8_BAR __builtin_amdgcn_s_barrier()
; #define PG8_SCHED __builtin_amdgcn_sched_barrier(0)
; template <class Epi, class Sched, bool ALIGN_EPI = false, bool SP2 = false>
; __device__ __forceinline__ void gemm_phase(PG8_LAS unsigned char* lds, const Gemm g, const Sched& S, const Epi& E) {
;     ...
;             PG8_WAIT_V(8); PG8_WAIT_L(0); PG8_BAR; PG8_MMA(0, 0, At, B0); PG8_MMA(0, 1, At, B1); PG8_BAR; PG8_SCHED;
;             PG8_LDA(At, 0, 1); PG8_STAGE(PG8_SB(0, 0), b2, voffB); PG8_STAGE(PG8_SB(0, 1), b2 + hstep, voffB); PG8_STAGE(PG8_SA(0, 0), a2, voffA);
;             PG8_WAIT_V(8); PG8_WAIT_L(0); PG8_BAR; PG8_MMA(1, 0, At, B0); PG8_MMA(1, 1, At, B1); PG8_BAR; PG8_SCHED;
;             PG8_LDB(B0, 1, 0); PG8_LDB(B1, 1, 1); PG8_SCHED; PG8_LDA(At, 1, 0); PG8_STAGE(PG8_SA(0, 1), a2 + hstep, voffA);
;             PG8_WAIT_V(8); PG8_WAIT_L(0); PG8_BAR; PG8_MMA(0, 0, At, B0); PG8_MMA(0, 1, At, B1); PG8_BAR; PG8_SCHED;
	s_waitcnt lgkmcnt(0)
	v_mfma_f32_16x16x32_bf16 v[60:63], v[160:163], v[194:197], v[60:63]
	v_mfma_f32_16x16x32_bf16 v[56:59], v[168:171], v[194:197], v[56:59]
	v_mfma_f32_16x16x32_bf16 v[52:55], v[160:163], v[202:205], v[52:55]
	v_mfma_f32_16x16x32_bf16 v[48:51], v[168:171], v[202:205], v[48:51]
	v_mfma_f32_16x16x32_bf16 v[36:39], v[160:163], v[210:213], v[36:39]
	v_mfma_f32_16x16x32_bf16 v[32:35], v[168:171], v[210:213], v[32:35]
	v_mfma_f32_16x16x32_bf16 v[20:23], v[160:163], v[218:221], v[20:23]
	v_mfma_f32_16x16x32_bf16 v[16:19], v[168:171], v[218:221], v[16:19]
	v_mfma_f32_16x16x32_bf16 v[60:63], v[164:167], v[198:201], v[60:63]
	v_mfma_f32_16x16x32_bf16 v[56:59], v[172:175], v[198:201], v[56:59]
	v_mfma_f32_16x16x32_bf16 v[52:55], v[164:167], v[206:209], v[52:55]
	v_mfma_f32_16x16x32_bf16 v[48:51], v[172:175], v[206:209], v[48:51]
	v_mfma_f32_16x16x32_bf16 v[36:39], v[164:167], v[214:217], v[36:39]
	v_mfma_f32_16x16x32_bf16 v[32:35], v[172:175], v[214:217], v[32:35]
	v_mfma_f32_16x16x32_bf16 v[20:23], v[164:167], v[222:225], v[20:23]
	v_mfma_f32_16x16x32_bf16 v[16:19], v[172:175], v[222:225], v[16:19]
	v_mfma_f32_16x16x32_bf16 v[44:47], v[176:179], v[194:197], v[44:47]
	v_mfma_f32_16x16x32_bf16 v[40:43], v[186:189], v[194:197], v[40:43]
	v_mfma_f32_16x16x32_bf16 v[28:31], v[176:179], v[202:205], v[28:31]
	v_mfma_f32_16x16x32_bf16 v[24:27], v[186:189], v[202:205], v[24:27]
	v_mfma_f32_16x16x32_bf16 v[12:15], v[176:179], v[210:213], v[12:15]
	v_mfma_f32_16x16x32_bf16 v[8:11], v[186:189], v[210:213], v[8:11]
	v_mfma_f32_16x16x32_bf16 v[4:7], v[176:179], v[218:221], v[4:7]
	v_mfma_f32_16x16x32_bf16 v[0:3], v[186:189], v[218:221], v[0:3]
	v_mfma_f32_16x16x32_bf16 v[44:47], v[180:183], v[198:201], v[44:47]
	v_mfma_f32_16x16x32_bf16 v[40:43], v[190:193], v[198:201], v[40:43]
	v_mfma_f32_16x16x32_bf16 v[28:31], v[180:183], v[206:209], v[28:31]
	v_mfma_f32_16x16x32_bf16 v[24:27], v[190:193], v[206:209], v[24:27]
	v_mfma_f32_16x16x32_bf16 v[12:15], v[180:183], v[214:217], v[12:15]
	v_mfma_f32_16x16x32_bf16 v[8:11], v[190:193], v[214:217], v[8:11]
	v_mfma_f32_16x16x32_bf16 v[4:7], v[180:183], v[222:225], v[4:7]
	v_mfma_f32_16x16x32_bf16 v[0:3], v[190:193], v[222:225], v[0:3]
	s_barrier
	ds_read_b128 v[160:163], v151
	ds_read_b128 v[164:167], v152
	ds_read_b128 v[168:171], v153
	ds_read_b128 v[172:175], v154
	ds_read_b128 v[176:179], v155
	ds_read_b128 v[180:183], v156
	ds_read_b128 v[186:189], v157
	ds_read_b128 v[190:193], v158
	s_mov_b32 m0, s69
	v_lshl_add_u64 v[234:235], s[48:49], 0, v[134:135]
	ds_read_b128 v[194:197], v141 offset:32768
	ds_read_b128 v[198:201], v141 offset:33792
	ds_read_b128 v[202:205], v141 offset:34816
	ds_read_b128 v[206:209], v141 offset:35840
	ds_read_b128 v[210:213], v141 offset:36864
	ds_read_b128 v[214:217], v141 offset:37888
	ds_read_b128 v[218:221], v141 offset:38912
	ds_read_b128 v[222:225], v141 offset:39936
	global_load_lds_dwordx4 v[234:235], off
	v_lshl_add_u64 v[234:235], s[48:49], 0, v[130:131]
	s_mov_b32 m0, s70
	s_nop 0
	global_load_lds_dwordx4 v[234:235], off
	s_waitcnt vmcnt(8)
	s_waitcnt lgkmcnt(0)
	s_barrier
	s_waitcnt lgkmcnt(0)
	v_mfma_f32_16x16x32_bf16 v[124:127], v[160:163], v[194:197], v[124:127]
	v_mfma_f32_16x16x32_bf16 v[120:123], v[168:171], v[194:197], v[120:123]
	v_mfma_f32_16x16x32_bf16 v[116:119], v[160:163], v[202:205], v[116:119]
	v_mfma_f32_16x16x32_bf16 v[112:115], v[168:171], v[202:205], v[112:115]
	v_mfma_f32_16x16x32_bf16 v[100:103], v[160:163], v[210:213], v[100:103]
	v_mfma_f32_16x16x32_bf16 v[96:99], v[168:171], v[210:213], v[96:99]
	v_mfma_f32_16x16x32_bf16 v[84:87], v[160:163], v[218:221], v[84:87]
	v_mfma_f32_16x16x32_bf16 v[80:83], v[168:171], v[218:221], v[80:83]
	v_mfma_f32_16x16x32_bf16 v[124:127], v[164:167], v[198:201], v[124:127]
	v_mfma_f32_16x16x32_bf16 v[120:123], v[172:175], v[198:201], v[120:123]
	v_mfma_f32_16x16x32_bf16 v[116:119], v[164:167], v[206:209], v[116:119]
	v_mfma_f32_16x16x32_bf16 v[112:115], v[172:175], v[206:209], v[112:115]
	v_mfma_f32_16x16x32_bf16 v[100:103], v[164:167], v[214:217], v[100:103]
	v_mfma_f32_16x16x32_bf16 v[96:99], v[172:175], v[214:217], v[96:99]
	v_mfma_f32_16x16x32_bf16 v[84:87], v[164:167], v[222:225], v[84:87]
	v_mfma_f32_16x16x32_bf16 v[80:83], v[172:175], v[222:225], v[80:83]
	v_mfma_f32_16x16x32_bf16 v[108:111], v[176:179], v[194:197], v[108:111]
	v_mfma_f32_16x16x32_bf16 v[104:107], v[186:189], v[194:197], v[104:107]
	v_mfma_f32_16x16x32_bf16 v[92:95], v[176:179], v[202:205], v[92:95]
	v_mfma_f32_16x16x32_bf16 v[88:91], v[186:189], v[202:205], v[88:91]
	v_mfma_f32_16x16x32_bf16 v[76:79], v[176:179], v[210:213], v[76:79]
	v_mfma_f32_16x16x32_bf16 v[72:75], v[186:189], v[210:213], v[72:75]
	v_mfma_f32_16x16x32_bf16 v[68:71], v[176:179], v[218:221], v[68:71]
	v_mfma_f32_16x16x32_bf16 v[64:67], v[186:189], v[218:221], v[64:67]
	v_mfma_f32_16x16x32_bf16 v[108:111], v[180:183], v[198:201], v[108:111]
	v_mfma_f32_16x16x32_bf16 v[104:107], v[190:193], v[198:201], v[104:107]
	v_mfma_f32_16x16x32_bf16 v[92:95], v[180:183], v[206:209], v[92:95]
	v_mfma_f32_16x16x32_bf16 v[88:91], v[190:193], v[206:209], v[88:91]
	v_mfma_f32_16x16x32_bf16 v[76:79], v[180:183], v[214:217], v[76:79]
	v_mfma_f32_16x16x32_bf16 v[72:75], v[190:193], v[214:217], v[72:75]
	v_mfma_f32_16x16x32_bf16 v[68:71], v[180:183], v[222:225], v[68:71]
	v_mfma_f32_16x16x32_bf16 v[64:67], v[190:193], v[222:225], v[64:67]
	s_barrier
; #define PG8_STAGE(bufoff, gbase, voff) do { _Pragma("unroll") for (int _i = 0; _i < 2; ++_i) \
;         __builtin_amdgcn_global_load_lds((const unsigned*)((const char*)(gbase) + (voff)[_i]), (PG8_LAS unsigned*)(lds + (bufoff) + ldsw + _i * 8192), 16, 0, 0); } while (0)
; #define PG8_LDA(dst, b, h) do { _Pragma("unroll") for (int m = 0; m < 4; ++m) _Pragma("unroll") for (int k = 0; k < 2; ++k) dst[m][k] = *(const PG8_LAS bf16x8*)(lds + PG8_SA(b, h) + aoff + m * 2048 + k * 1024); } while (0)
; #define PG8_MMA(ai, bj, At, Bt) do { __builtin_amdgcn_s_setprio(1); _Pragma("unroll") for (int m = 0; m < 4; ++m) _Pragma("unroll") for (int n = 0; n < 2; ++n) _Pragma("unroll") for (int k = 0; k < 2; ++k) \
;         acc[ai][bj][m][n] = __builtin_amdgcn_mfma_f32_16x16x32_bf16(Bt[n][k], At[m][k], acc[ai][bj][m][n], 0, 0, 0); __builtin_amdgcn_s_setprio(0); } while (0)
; #define PG8_WAIT_V(n) asm volatile("s_waitcnt vmcnt(" #n ")" ::: "memory")
; #define PG8_WAIT_L(n) asm volatile("s_waitcnt lgkmcnt(" #n ")" ::: "memory")
; #define PG8_BAR __builtin_amdgcn_s_barrier()
; #define PG8_SCHED __builtin_amdgcn_sched_barrier(0)
; template <class Epi, class Sched, bool ALIGN_EPI = false, bool SP2 = false>
; __device__ __forceinline__ void gemm_phase(PG8_LAS unsigned char* lds, const Gemm g, const Sched& S, const Epi& E) {
;     ...
;             PG8_LDA(At, 1, 1); PG8_STAGE(PG8_SB(1, 0), b3, voffB); PG8_STAGE(PG8_SB(1, 1), b3 + hstep, voffB); PG8_STAGE(PG8_SA(1, 0), a3, voffA);
;             PG8_WAIT_V(8); PG8_WAIT_L(0); PG8_BAR; PG8_MMA(1, 0, At, B0); PG8_MMA(1, 1, At, B1); PG8_BAR; PG8_SCHED;
	s_mov_b32 m0, s72
	v_lshl_add_u64 v[226:227], v[226:227], 0, s[12:13]
	ds_read_b128 v[194:197], v141 offset:49152
	ds_read_b128 v[198:201], v141 offset:50176
	ds_read_b128 v[202:205], v141 offset:51200
	ds_read_b128 v[206:209], v141 offset:52224
	ds_read_b128 v[210:213], v141 offset:53248
	ds_read_b128 v[214:217], v141 offset:54272
	ds_read_b128 v[218:221], v141 offset:55296
	ds_read_b128 v[222:225], v141 offset:56320
	global_load_lds_dwordx4 v[226:227], off
	v_lshl_add_u64 v[226:227], v[228:229], 0, s[12:13]
	s_mov_b32 m0, s73
	s_nop 0
	global_load_lds_dwordx4 v[226:227], off
	v_lshl_add_u64 v[226:227], s[56:57], 0, v[132:133]
	s_mov_b32 m0, s76
	s_nop 0
	global_load_lds_dwordx4 v[226:227], off
	v_lshl_add_u64 v[226:227], s[56:57], 0, v[128:129]
	s_mov_b32 m0, s77
	s_nop 0
	global_load_lds_dwordx4 v[226:227], off
	v_lshl_add_u64 v[226:227], v[230:231], 0, s[12:13]
	s_mov_b32 m0, s74
	s_nop 0
	global_load_lds_dwordx4 v[226:227], off
	v_lshl_add_u64 v[226:227], v[232:233], 0, s[12:13]
	s_mov_b32 m0, s75
	s_nop 0
	global_load_lds_dwordx4 v[226:227], off
	s_waitcnt vmcnt(8)
	s_waitcnt lgkmcnt(0)
	s_barrier
	s_waitcnt lgkmcnt(0)
	v_mfma_f32_16x16x32_bf16 v[60:63], v[160:163], v[194:197], v[60:63]
	v_mfma_f32_16x16x32_bf16 v[56:59], v[168:171], v[194:197], v[56:59]
	v_mfma_f32_16x16x32_bf16 v[52:55], v[160:163], v[202:205], v[52:55]
	v_mfma_f32_16x16x32_bf16 v[48:51], v[168:171], v[202:205], v[48:51]
	v_mfma_f32_16x16x32_bf16 v[36:39], v[160:163], v[210:213], v[36:39]
	v_mfma_f32_16x16x32_bf16 v[32:35], v[168:171], v[210:213], v[32:35]
	v_mfma_f32_16x16x32_bf16 v[20:23], v[160:163], v[218:221], v[20:23]
	v_mfma_f32_16x16x32_bf16 v[16:19], v[168:171], v[218:221], v[16:19]
	v_mfma_f32_16x16x32_bf16 v[60:63], v[164:167], v[198:201], v[60:63]
	v_mfma_f32_16x16x32_bf16 v[56:59], v[172:175], v[198:201], v[56:59]
	v_mfma_f32_16x16x32_bf16 v[52:55], v[164:167], v[206:209], v[52:55]
	v_mfma_f32_16x16x32_bf16 v[48:51], v[172:175], v[206:209], v[48:51]
	v_mfma_f32_16x16x32_bf16 v[36:39], v[164:167], v[214:217], v[36:39]
	v_mfma_f32_16x16x32_bf16 v[32:35], v[172:175], v[214:217], v[32:35]
	v_mfma_f32_16x16x32_bf16 v[20:23], v[164:167], v[222:225], v[20:23]
	v_mfma_f32_16x16x32_bf16 v[16:19], v[172:175], v[222:225], v[16:19]
	v_mfma_f32_16x16x32_bf16 v[44:47], v[176:179], v[194:197], v[44:47]
	v_mfma_f32_16x16x32_bf16 v[40:43], v[186:189], v[194:197], v[40:43]
	v_mfma_f32_16x16x32_bf16 v[28:31], v[176:179], v[202:205], v[28:31]
	v_mfma_f32_16x16x32_bf16 v[24:27], v[186:189], v[202:205], v[24:27]
	v_mfma_f32_16x16x32_bf16 v[12:15], v[176:179], v[210:213], v[12:15]
	v_mfma_f32_16x16x32_bf16 v[8:11], v[186:189], v[210:213], v[8:11]
	v_mfma_f32_16x16x32_bf16 v[4:7], v[176:179], v[218:221], v[4:7]
	v_mfma_f32_16x16x32_bf16 v[0:3], v[186:189], v[218:221], v[0:3]
	v_mfma_f32_16x16x32_bf16 v[44:47], v[180:183], v[198:201], v[44:47]
	v_mfma_f32_16x16x32_bf16 v[40:43], v[190:193], v[198:201], v[40:43]
	v_mfma_f32_16x16x32_bf16 v[28:31], v[180:183], v[206:209], v[28:31]
	v_mfma_f32_16x16x32_bf16 v[24:27], v[190:193], v[206:209], v[24:27]
	v_mfma_f32_16x16x32_bf16 v[12:15], v[180:183], v[214:217], v[12:15]
	v_mfma_f32_16x16x32_bf16 v[8:11], v[190:193], v[214:217], v[8:11]
	v_mfma_f32_16x16x32_bf16 v[4:7], v[180:183], v[222:225], v[4:7]
	v_mfma_f32_16x16x32_bf16 v[0:3], v[190:193], v[222:225], v[0:3]
	s_barrier
	s_movk_i32 s52, 0x100
	s_andn2_b64 vcc, exec, s[46:47]
	s_mov_b64 s[48:49], -1
	s_mov_b64 s[46:47], 0
	s_cbranch_vccz .LBB0_645
	s_and_b64 vcc, exec, s[16:17]
	s_cbranch_vccz .LBB0_648
	s_barrier

; #define PG8_STAGE(bufoff, gbase, voff) do { _Pragma("unroll") for (int _i = 0; _i < 2; ++_i) \
;         __builtin_amdgcn_global_load_lds((const unsigned*)((const char*)(gbase) + (voff)[_i]), (PG8_LAS unsigned*)(lds + (bufoff) + ldsw + _i * 8192), 16, 0, 0); } while (0)
; #define PG8_LDA(dst, b, h) do { _Pragma("unroll") for (int m = 0; m < 4; ++m) _Pragma("unroll") for (int k = 0; k < 2; ++k) dst[m][k] = *(const PG8_LAS bf16x8*)(lds + PG8_SA(b, h) + aoff + m * 2048 + k * 1024); } while (0)
; #define PG8_LDB(dst, b, h) do { _Pragma("unroll") for (int n = 0; n < 2; ++n) _Pragma("unroll") for (int k = 0; k < 2; ++k) dst[n][k] = *(const PG8_LAS bf16x8*)(lds + PG8_SB(b, h) + boff + n * 2048 + k * 1024); } while (0)
; #define PG8_MMA(ai, bj, At, Bt) do { __builtin_amdgcn_s_setprio(1); _Pragma("unroll") for (int m = 0; m < 4; ++m) _Pragma("unroll") for (int n = 0; n < 2; ++n) _Pragma("unroll") for (int k = 0; k < 2; ++k) \
;         acc[ai][bj][m][n] = __builtin_amdgcn_mfma_f32_16x16x32_bf16(Bt[n][k], At[m][k], acc[ai][bj][m][n], 0, 0, 0); __builtin_amdgcn_s_setprio(0); } while (0)
; #define PG8_WAIT_V(n) asm volatile("s_waitcnt vmcnt(" #n ")" ::: "memory")
; #define PG8_WAIT_L(n) asm volatile("s_waitcnt lgkmcnt(" #n ")" ::: "memory")
; #define PG8_BAR __builtin_amdgcn_s_barrier()
; #define PG8_SCHED __builtin_amdgcn_sched_barrier(0)
; template <class Epi, class Sched, bool ALIGN_EPI = false, bool SP2 = false>
; __device__ __forceinline__ void gemm_phase(PG8_LAS unsigned char* lds, const Gemm g, const Sched& S, const Epi& E) {
;     ...
;             PG8_LDB(B0, 0, 0); PG8_LDB(B1, 0, 1); PG8_SCHED; PG8_LDA(At, 0, 0); PG8_STAGE(PG8_SA(1, 1), a1 + hstep, voffA);
;             PG8_WAIT_V(8); PG8_WAIT_L(0); PG8_BAR; PG8_MMA(0, 0, At, B0); PG8_MMA(0, 1, At, B1); PG8_BAR; PG8_SCHED;
;             PG8_LDA(At, 0, 1); PG8_STAGE(PG8_SB(0, 0), b2, voffB); PG8_STAGE(PG8_SB(0, 1), b2 + hstep, voffB); PG8_STAGE(PG8_SA(0, 0), a2, voffA);
;             PG8_WAIT_V(8); PG8_WAIT_L(0); PG8_BAR; PG8_MMA(1, 0, At, B0); PG8_MMA(1, 1, At, B1); PG8_BAR; PG8_SCHED;
.LBB0_671:
	ds_read_b128 v[128:131], v161
	ds_read_b128 v[132:135], v162
	ds_read_b128 v[152:155], v163
	ds_read_b128 v[180:183], v164
	ds_read_b128 v[186:189], v165
	ds_read_b128 v[190:193], v166
	ds_read_b128 v[194:197], v167
	ds_read_b128 v[198:201], v168
	s_add_u32 s12, s10, 0xfffc0080
	s_addc_u32 s13, s11, -1
	s_cmp_eq_u32 s75, 12
	s_cselect_b32 s49, s9, s13
	s_cselect_b32 s48, s43, s12
	s_cselect_b32 s13, s37, s74
	s_cselect_b32 s12, s72, s73
	s_mov_b32 m0, s68
	v_lshl_add_u64 v[156:157], s[10:11], 0, v[146:147]
	ds_read_b128 v[202:205], v159
	ds_read_b128 v[206:209], v159 offset:1024
	ds_read_b128 v[210:213], v159 offset:2048
	ds_read_b128 v[214:217], v159 offset:3072
	ds_read_b128 v[218:221], v159 offset:4096
	ds_read_b128 v[222:225], v159 offset:5120
	ds_read_b128 v[226:229], v159 offset:6144
	ds_read_b128 v[230:233], v159 offset:7168
	global_load_lds_dwordx4 v[156:157], off
	v_lshl_add_u64 v[156:157], s[10:11], 0, v[144:145]
	s_mov_b32 m0, s69
	s_nop 0
	global_load_lds_dwordx4 v[156:157], off
	s_waitcnt vmcnt(8)
	s_waitcnt lgkmcnt(0)
	s_barrier
	s_waitcnt lgkmcnt(0)
	v_mfma_f32_16x16x32_bf16 v[124:127], v[128:131], v[202:205], v[124:127]
	v_mfma_f32_16x16x32_bf16 v[120:123], v[152:155], v[202:205], v[120:123]
	v_mfma_f32_16x16x32_bf16 v[108:111], v[128:131], v[210:213], v[108:111]
	v_mfma_f32_16x16x32_bf16 v[104:107], v[152:155], v[210:213], v[104:107]
	v_mfma_f32_16x16x32_bf16 v[92:95], v[128:131], v[218:221], v[92:95]
	v_mfma_f32_16x16x32_bf16 v[88:91], v[152:155], v[218:221], v[88:91]
	v_mfma_f32_16x16x32_bf16 v[76:79], v[128:131], v[226:229], v[76:79]
	v_mfma_f32_16x16x32_bf16 v[72:75], v[152:155], v[226:229], v[72:75]
	v_mfma_f32_16x16x32_bf16 v[124:127], v[132:135], v[206:209], v[124:127]
	v_mfma_f32_16x16x32_bf16 v[120:123], v[180:183], v[206:209], v[120:123]
	v_mfma_f32_16x16x32_bf16 v[108:111], v[132:135], v[214:217], v[108:111]
	v_mfma_f32_16x16x32_bf16 v[104:107], v[180:183], v[214:217], v[104:107]
	v_mfma_f32_16x16x32_bf16 v[92:95], v[132:135], v[222:225], v[92:95]
	v_mfma_f32_16x16x32_bf16 v[88:91], v[180:183], v[222:225], v[88:91]
	v_mfma_f32_16x16x32_bf16 v[76:79], v[132:135], v[230:233], v[76:79]
	v_mfma_f32_16x16x32_bf16 v[72:75], v[180:183], v[230:233], v[72:75]
	v_mfma_f32_16x16x32_bf16 v[116:119], v[186:189], v[202:205], v[116:119]
	v_mfma_f32_16x16x32_bf16 v[112:115], v[194:197], v[202:205], v[112:115]
	v_mfma_f32_16x16x32_bf16 v[100:103], v[186:189], v[210:213], v[100:103]
	v_mfma_f32_16x16x32_bf16 v[96:99], v[194:197], v[210:213], v[96:99]
	v_mfma_f32_16x16x32_bf16 v[84:87], v[186:189], v[218:221], v[84:87]
	v_mfma_f32_16x16x32_bf16 v[80:83], v[194:197], v[218:221], v[80:83]
	v_mfma_f32_16x16x32_bf16 v[68:71], v[186:189], v[226:229], v[68:71]
	v_mfma_f32_16x16x32_bf16 v[64:67], v[194:197], v[226:229], v[64:67]
	v_mfma_f32_16x16x32_bf16 v[116:119], v[190:193], v[206:209], v[116:119]
	v_mfma_f32_16x16x32_bf16 v[112:115], v[198:201], v[206:209], v[112:115]
	v_mfma_f32_16x16x32_bf16 v[100:103], v[190:193], v[214:217], v[100:103]
	v_mfma_f32_16x16x32_bf16 v[96:99], v[198:201], v[214:217], v[96:99]
	v_mfma_f32_16x16x32_bf16 v[84:87], v[190:193], v[222:225], v[84:87]
	v_mfma_f32_16x16x32_bf16 v[80:83], v[198:201], v[222:225], v[80:83]
	v_mfma_f32_16x16x32_bf16 v[68:71], v[190:193], v[230:233], v[68:71]
	v_mfma_f32_16x16x32_bf16 v[64:67], v[198:201], v[230:233], v[64:67]
	s_barrier
	s_mov_b32 m0, s52
	v_lshl_add_u64 v[156:157], s[12:13], 0, v[138:139]
	s_add_u32 s76, s12, 0x40000
	ds_read_b128 v[202:205], v159 offset:16384
	ds_read_b128 v[206:209], v159 offset:17408
	ds_read_b128 v[210:213], v159 offset:18432
	ds_read_b128 v[214:217], v159 offset:19456
	ds_read_b128 v[218:221], v159 offset:20480
	ds_read_b128 v[222:225], v159 offset:21504
	ds_read_b128 v[226:229], v159 offset:22528
	ds_read_b128 v[230:233], v159 offset:23552
	global_load_lds_dwordx4 v[156:157], off
	v_lshl_add_u64 v[234:235], s[12:13], 0, v[142:143]
	s_mov_b32 m0, s53
	s_addc_u32 s77, s13, 0
	global_load_lds_dwordx4 v[234:235], off
	v_lshl_add_u64 v[236:237], s[76:77], 0, v[138:139]
	s_mov_b32 m0, s54
	v_lshl_add_u64 v[238:239], s[48:49], 0, v[140:141]
	global_load_lds_dwordx4 v[236:237], off
	v_lshl_add_u64 v[236:237], s[76:77], 0, v[142:143]
	s_mov_b32 m0, s55
	s_nop 0
	global_load_lds_dwordx4 v[236:237], off
	v_lshl_add_u64 v[236:237], s[48:49], 0, v[136:137]
	s_mov_b32 m0, s51
	s_nop 0
	global_load_lds_dwordx4 v[236:237], off
	s_mov_b32 m0, s56
	s_nop 0
	global_load_lds_dwordx4 v[238:239], off
	s_waitcnt vmcnt(8)
	s_waitcnt lgkmcnt(0)
	s_barrier
	s_waitcnt lgkmcnt(0)
	v_mfma_f32_16x16x32_bf16 v[60:63], v[128:131], v[202:205], v[60:63]
	v_mfma_f32_16x16x32_bf16 v[56:59], v[152:155], v[202:205], v[56:59]
	v_mfma_f32_16x16x32_bf16 v[44:47], v[128:131], v[210:213], v[44:47]
	v_mfma_f32_16x16x32_bf16 v[40:43], v[152:155], v[210:213], v[40:43]
	v_mfma_f32_16x16x32_bf16 v[28:31], v[128:131], v[218:221], v[28:31]
	v_mfma_f32_16x16x32_bf16 v[24:27], v[152:155], v[218:221], v[24:27]
	v_mfma_f32_16x16x32_bf16 v[12:15], v[128:131], v[226:229], v[12:15]
	v_mfma_f32_16x16x32_bf16 v[8:11], v[152:155], v[226:229], v[8:11]
	v_mfma_f32_16x16x32_bf16 v[60:63], v[132:135], v[206:209], v[60:63]
	v_mfma_f32_16x16x32_bf16 v[56:59], v[180:183], v[206:209], v[56:59]
	v_mfma_f32_16x16x32_bf16 v[44:47], v[132:135], v[214:217], v[44:47]
	v_mfma_f32_16x16x32_bf16 v[40:43], v[180:183], v[214:217], v[40:43]
	v_mfma_f32_16x16x32_bf16 v[28:31], v[132:135], v[222:225], v[28:31]
	v_mfma_f32_16x16x32_bf16 v[24:27], v[180:183], v[222:225], v[24:27]
	v_mfma_f32_16x16x32_bf16 v[12:15], v[132:135], v[230:233], v[12:15]
	v_mfma_f32_16x16x32_bf16 v[8:11], v[180:183], v[230:233], v[8:11]
	v_mfma_f32_16x16x32_bf16 v[52:55], v[186:189], v[202:205], v[52:55]
	v_mfma_f32_16x16x32_bf16 v[48:51], v[194:197], v[202:205], v[48:51]
	v_mfma_f32_16x16x32_bf16 v[36:39], v[186:189], v[210:213], v[36:39]
	v_mfma_f32_16x16x32_bf16 v[32:35], v[194:197], v[210:213], v[32:35]
	v_mfma_f32_16x16x32_bf16 v[20:23], v[186:189], v[218:221], v[20:23]
	v_mfma_f32_16x16x32_bf16 v[16:19], v[194:197], v[218:221], v[16:19]
	v_mfma_f32_16x16x32_bf16 v[4:7], v[186:189], v[226:229], v[4:7]
	v_mfma_f32_16x16x32_bf16 v[0:3], v[194:197], v[226:229], v[0:3]
	v_mfma_f32_16x16x32_bf16 v[52:55], v[190:193], v[206:209], v[52:55]
	v_mfma_f32_16x16x32_bf16 v[48:51], v[198:201], v[206:209], v[48:51]
	v_mfma_f32_16x16x32_bf16 v[36:39], v[190:193], v[214:217], v[36:39]
	v_mfma_f32_16x16x32_bf16 v[32:35], v[198:201], v[214:217], v[32:35]
	v_mfma_f32_16x16x32_bf16 v[20:23], v[190:193], v[222:225], v[20:23]
	v_mfma_f32_16x16x32_bf16 v[16:19], v[198:201], v[222:225], v[16:19]
	v_mfma_f32_16x16x32_bf16 v[4:7], v[190:193], v[230:233], v[4:7]
	v_mfma_f32_16x16x32_bf16 v[0:3], v[198:201], v[230:233], v[0:3]
	s_barrier
; #define PG8_STAGE(bufoff, gbase, voff) do { _Pragma("unroll") for (int _i = 0; _i < 2; ++_i) \
;         __builtin_amdgcn_global_load_lds((const unsigned*)((const char*)(gbase) + (voff)[_i]), (PG8_LAS unsigned*)(lds + (bufoff) + ldsw + _i * 8192), 16, 0, 0); } while (0)
; #define PG8_LDA(dst, b, h) do { _Pragma("unroll") for (int m = 0; m < 4; ++m) _Pragma("unroll") for (int k = 0; k < 2; ++k) dst[m][k] = *(const PG8_LAS bf16x8*)(lds + PG8_SA(b, h) + aoff + m * 2048 + k * 1024); } while (0)
; #define PG8_LDB(dst, b, h) do { _Pragma("unroll") for (int n = 0; n < 2; ++n) _Pragma("unroll") for (int k = 0; k < 2; ++k) dst[n][k] = *(const PG8_LAS bf16x8*)(lds + PG8_SB(b, h) + boff + n * 2048 + k * 1024); } while (0)
; #define PG8_MMA(ai, bj, At, Bt) do { __builtin_amdgcn_s_setprio(1); _Pragma("unroll") for (int m = 0; m < 4; ++m) _Pragma("unroll") for (int n = 0; n < 2; ++n) _Pragma("unroll") for (int k = 0; k < 2; ++k) \
;         acc[ai][bj][m][n] = __builtin_amdgcn_mfma_f32_16x16x32_bf16(Bt[n][k], At[m][k], acc[ai][bj][m][n], 0, 0, 0); __builtin_amdgcn_s_setprio(0); } while (0)
; #define PG8_WAIT_V(n) asm volatile("s_waitcnt vmcnt(" #n ")" ::: "memory")
; #define PG8_WAIT_L(n) asm volatile("s_waitcnt lgkmcnt(" #n ")" ::: "memory")
; #define PG8_BAR __builtin_amdgcn_s_barrier()
; #define PG8_SCHED __builtin_amdgcn_sched_barrier(0)
; template <class Epi, class Sched, bool ALIGN_EPI = false, bool SP2 = false>
; __device__ __forceinline__ void gemm_phase(PG8_LAS unsigned char* lds, const Gemm g, const Sched& S, const Epi& E) {
;     ...
;             PG8_LDB(B0, 1, 0); PG8_LDB(B1, 1, 1); PG8_SCHED; PG8_LDA(At, 1, 0); PG8_STAGE(PG8_SA(0, 1), a2 + hstep, voffA);
;             PG8_WAIT_V(8); PG8_WAIT_L(0); PG8_BAR; PG8_MMA(0, 0, At, B0); PG8_MMA(0, 1, At, B1); PG8_BAR; PG8_SCHED;
;             PG8_LDA(At, 1, 1); PG8_STAGE(PG8_SB(1, 0), b3, voffB); PG8_STAGE(PG8_SB(1, 1), b3 + hstep, voffB); PG8_STAGE(PG8_SA(1, 0), a3, voffA);
;             PG8_WAIT_V(8); PG8_WAIT_L(0); PG8_BAR; PG8_MMA(1, 0, At, B0); PG8_MMA(1, 1, At, B1); PG8_BAR; PG8_SCHED;
	ds_read_b128 v[128:131], v169
	ds_read_b128 v[132:135], v170
	ds_read_b128 v[152:155], v171
	ds_read_b128 v[180:183], v172
	ds_read_b128 v[186:189], v173
	ds_read_b128 v[190:193], v174
	ds_read_b128 v[194:197], v175
	ds_read_b128 v[198:201], v176
	s_add_u32 s48, s48, 0x40000
	s_addc_u32 s49, s49, 0
	s_mov_b32 m0, s57
	v_lshl_add_u64 v[240:241], s[48:49], 0, v[136:137]
	ds_read_b128 v[202:205], v159 offset:32768
	ds_read_b128 v[206:209], v159 offset:33792
	ds_read_b128 v[210:213], v159 offset:34816
	ds_read_b128 v[214:217], v159 offset:35840
	ds_read_b128 v[218:221], v159 offset:36864
	ds_read_b128 v[222:225], v159 offset:37888
	ds_read_b128 v[226:229], v159 offset:38912
	ds_read_b128 v[230:233], v159 offset:39936
	global_load_lds_dwordx4 v[240:241], off
	v_lshl_add_u64 v[240:241], s[48:49], 0, v[140:141]
	s_mov_b32 m0, s58
	s_nop 0
	global_load_lds_dwordx4 v[240:241], off
	s_waitcnt vmcnt(8)
	s_waitcnt lgkmcnt(0)
	s_barrier
	s_waitcnt lgkmcnt(0)
	v_mfma_f32_16x16x32_bf16 v[124:127], v[128:131], v[202:205], v[124:127]
	v_mfma_f32_16x16x32_bf16 v[120:123], v[152:155], v[202:205], v[120:123]
	v_mfma_f32_16x16x32_bf16 v[108:111], v[128:131], v[210:213], v[108:111]
	v_mfma_f32_16x16x32_bf16 v[104:107], v[152:155], v[210:213], v[104:107]
	v_mfma_f32_16x16x32_bf16 v[92:95], v[128:131], v[218:221], v[92:95]
	v_mfma_f32_16x16x32_bf16 v[88:91], v[152:155], v[218:221], v[88:91]
	v_mfma_f32_16x16x32_bf16 v[76:79], v[128:131], v[226:229], v[76:79]
	v_mfma_f32_16x16x32_bf16 v[72:75], v[152:155], v[226:229], v[72:75]
	v_mfma_f32_16x16x32_bf16 v[124:127], v[132:135], v[206:209], v[124:127]
	v_mfma_f32_16x16x32_bf16 v[120:123], v[180:183], v[206:209], v[120:123]
	v_mfma_f32_16x16x32_bf16 v[108:111], v[132:135], v[214:217], v[108:111]
	v_mfma_f32_16x16x32_bf16 v[104:107], v[180:183], v[214:217], v[104:107]
	v_mfma_f32_16x16x32_bf16 v[92:95], v[132:135], v[222:225], v[92:95]
	v_mfma_f32_16x16x32_bf16 v[88:91], v[180:183], v[222:225], v[88:91]
	v_mfma_f32_16x16x32_bf16 v[76:79], v[132:135], v[230:233], v[76:79]
	v_mfma_f32_16x16x32_bf16 v[72:75], v[180:183], v[230:233], v[72:75]
	v_mfma_f32_16x16x32_bf16 v[116:119], v[186:189], v[202:205], v[116:119]
	v_mfma_f32_16x16x32_bf16 v[112:115], v[194:197], v[202:205], v[112:115]
	v_mfma_f32_16x16x32_bf16 v[100:103], v[186:189], v[210:213], v[100:103]
	v_mfma_f32_16x16x32_bf16 v[96:99], v[194:197], v[210:213], v[96:99]
	v_mfma_f32_16x16x32_bf16 v[84:87], v[186:189], v[218:221], v[84:87]
	v_mfma_f32_16x16x32_bf16 v[80:83], v[194:197], v[218:221], v[80:83]
	v_mfma_f32_16x16x32_bf16 v[68:71], v[186:189], v[226:229], v[68:71]
	v_mfma_f32_16x16x32_bf16 v[64:67], v[194:197], v[226:229], v[64:67]
	v_mfma_f32_16x16x32_bf16 v[116:119], v[190:193], v[206:209], v[116:119]
	v_mfma_f32_16x16x32_bf16 v[112:115], v[198:201], v[206:209], v[112:115]
	v_mfma_f32_16x16x32_bf16 v[100:103], v[190:193], v[214:217], v[100:103]
	v_mfma_f32_16x16x32_bf16 v[96:99], v[198:201], v[214:217], v[96:99]
	v_mfma_f32_16x16x32_bf16 v[84:87], v[190:193], v[222:225], v[84:87]
	v_mfma_f32_16x16x32_bf16 v[80:83], v[198:201], v[222:225], v[80:83]
	v_mfma_f32_16x16x32_bf16 v[68:71], v[190:193], v[230:233], v[68:71]
	v_mfma_f32_16x16x32_bf16 v[64:67], v[198:201], v[230:233], v[64:67]
	s_barrier
	s_mov_b32 m0, s60
	v_lshl_add_u64 v[156:157], v[156:157], 0, s[28:29]
	s_add_u32 s12, s12, 0x40080
	ds_read_b128 v[202:205], v159 offset:49152
	ds_read_b128 v[206:209], v159 offset:50176
	ds_read_b128 v[210:213], v159 offset:51200
	ds_read_b128 v[214:217], v159 offset:52224
	ds_read_b128 v[218:221], v159 offset:53248
	ds_read_b128 v[222:225], v159 offset:54272
	ds_read_b128 v[226:229], v159 offset:55296
	ds_read_b128 v[230:233], v159 offset:56320
	global_load_lds_dwordx4 v[156:157], off
	v_lshl_add_u64 v[156:157], v[234:235], 0, s[28:29]
	s_mov_b32 m0, s61
	s_addc_u32 s13, s13, 0
	global_load_lds_dwordx4 v[156:157], off
	v_lshl_add_u64 v[156:157], s[12:13], 0, v[138:139]
	s_mov_b32 m0, s64
	s_nop 0
	global_load_lds_dwordx4 v[156:157], off
	v_lshl_add_u64 v[156:157], s[12:13], 0, v[142:143]
	s_mov_b32 m0, s65
	s_nop 0
	global_load_lds_dwordx4 v[156:157], off
	v_lshl_add_u64 v[156:157], v[236:237], 0, s[28:29]
	s_mov_b32 m0, s62
	s_nop 0
	global_load_lds_dwordx4 v[156:157], off
	v_lshl_add_u64 v[156:157], v[238:239], 0, s[28:29]
	s_mov_b32 m0, s63
	s_nop 0
	global_load_lds_dwordx4 v[156:157], off
	s_waitcnt vmcnt(8)
	s_waitcnt lgkmcnt(0)
	s_barrier
	s_waitcnt lgkmcnt(0)
	v_mfma_f32_16x16x32_bf16 v[60:63], v[128:131], v[202:205], v[60:63]
	v_mfma_f32_16x16x32_bf16 v[56:59], v[152:155], v[202:205], v[56:59]
	v_mfma_f32_16x16x32_bf16 v[44:47], v[128:131], v[210:213], v[44:47]
	v_mfma_f32_16x16x32_bf16 v[40:43], v[152:155], v[210:213], v[40:43]
	v_mfma_f32_16x16x32_bf16 v[28:31], v[128:131], v[218:221], v[28:31]
	v_mfma_f32_16x16x32_bf16 v[24:27], v[152:155], v[218:221], v[24:27]
	v_mfma_f32_16x16x32_bf16 v[12:15], v[128:131], v[226:229], v[12:15]
	v_mfma_f32_16x16x32_bf16 v[8:11], v[152:155], v[226:229], v[8:11]
	v_mfma_f32_16x16x32_bf16 v[60:63], v[132:135], v[206:209], v[60:63]
	v_mfma_f32_16x16x32_bf16 v[56:59], v[180:183], v[206:209], v[56:59]
	v_mfma_f32_16x16x32_bf16 v[44:47], v[132:135], v[214:217], v[44:47]
	v_mfma_f32_16x16x32_bf16 v[40:43], v[180:183], v[214:217], v[40:43]
	v_mfma_f32_16x16x32_bf16 v[28:31], v[132:135], v[222:225], v[28:31]
	v_mfma_f32_16x16x32_bf16 v[24:27], v[180:183], v[222:225], v[24:27]
	v_mfma_f32_16x16x32_bf16 v[12:15], v[132:135], v[230:233], v[12:15]
	v_mfma_f32_16x16x32_bf16 v[8:11], v[180:183], v[230:233], v[8:11]
	v_mfma_f32_16x16x32_bf16 v[52:55], v[186:189], v[202:205], v[52:55]
	v_mfma_f32_16x16x32_bf16 v[48:51], v[194:197], v[202:205], v[48:51]
	v_mfma_f32_16x16x32_bf16 v[36:39], v[186:189], v[210:213], v[36:39]
	v_mfma_f32_16x16x32_bf16 v[32:35], v[194:197], v[210:213], v[32:35]
	v_mfma_f32_16x16x32_bf16 v[20:23], v[186:189], v[218:221], v[20:23]
	v_mfma_f32_16x16x32_bf16 v[16:19], v[194:197], v[218:221], v[16:19]
	v_mfma_f32_16x16x32_bf16 v[4:7], v[186:189], v[226:229], v[4:7]
	v_mfma_f32_16x16x32_bf16 v[0:3], v[194:197], v[226:229], v[0:3]
	v_mfma_f32_16x16x32_bf16 v[52:55], v[190:193], v[206:209], v[52:55]
	v_mfma_f32_16x16x32_bf16 v[48:51], v[198:201], v[206:209], v[48:51]
	v_mfma_f32_16x16x32_bf16 v[36:39], v[190:193], v[214:217], v[36:39]
	v_mfma_f32_16x16x32_bf16 v[32:35], v[198:201], v[214:217], v[32:35]
	v_mfma_f32_16x16x32_bf16 v[20:23], v[190:193], v[222:225], v[20:23]
	v_mfma_f32_16x16x32_bf16 v[16:19], v[198:201], v[222:225], v[16:19]
	v_mfma_f32_16x16x32_bf16 v[4:7], v[190:193], v[230:233], v[4:7]
	v_mfma_f32_16x16x32_bf16 v[0:3], v[198:201], v[230:233], v[0:3]
	s_barrier
	s_add_i32 s75, s75, 2
	s_add_u32 s73, s73, 0x100
	s_addc_u32 s74, s74, 0
	s_add_u32 s10, s10, 0x100
	s_addc_u32 s11, s11, 0
	s_cmp_gt_u32 s75, 13
	s_cbranch_scc0 .LBB0_671
	s_and_b64 vcc, exec, s[30:31]
	s_cbranch_vccz .LBB0_674
	s_barrier

; #define PG8_STAGE(bufoff, gbase, voff) do { _Pragma("unroll") for (int _i = 0; _i < 2; ++_i) \
;         __builtin_amdgcn_global_load_lds((const unsigned*)((const char*)(gbase) + (voff)[_i]), (PG8_LAS unsigned*)(lds + (bufoff) + ldsw + _i * 8192), 16, 0, 0); } while (0)
; #define PG8_LDA(dst, b, h) do { _Pragma("unroll") for (int m = 0; m < 4; ++m) _Pragma("unroll") for (int k = 0; k < 2; ++k) dst[m][k] = *(const PG8_LAS bf16x8*)(lds + PG8_SA(b, h) + aoff + m * 2048 + k * 1024); } while (0)
; #define PG8_LDB(dst, b, h) do { _Pragma("unroll") for (int n = 0; n < 2; ++n) _Pragma("unroll") for (int k = 0; k < 2; ++k) dst[n][k] = *(const PG8_LAS bf16x8*)(lds + PG8_SB(b, h) + boff + n * 2048 + k * 1024); } while (0)
; #define PG8_MMA(ai, bj, At, Bt) do { __builtin_amdgcn_s_setprio(1); _Pragma("unroll") for (int m = 0; m < 4; ++m) _Pragma("unroll") for (int n = 0; n < 2; ++n) _Pragma("unroll") for (int k = 0; k < 2; ++k) \
;         acc[ai][bj][m][n] = __builtin_amdgcn_mfma_f32_16x16x32_bf16(Bt[n][k], At[m][k], acc[ai][bj][m][n], 0, 0, 0); __builtin_amdgcn_s_setprio(0); } while (0)
; #define PG8_WAIT_V(n) asm volatile("s_waitcnt vmcnt(" #n ")" ::: "memory")
; #define PG8_WAIT_L(n) asm volatile("s_waitcnt lgkmcnt(" #n ")" ::: "memory")
; #define PG8_BAR __builtin_amdgcn_s_barrier()
; #define PG8_SCHED __builtin_amdgcn_sched_barrier(0)
; template <class Epi, class Sched, bool ALIGN_EPI = false, bool SP2 = false>
; __device__ __forceinline__ void gemm_phase(PG8_LAS unsigned char* lds, const Gemm g, const Sched& S, const Epi& E) {
;     ...
;             PG8_LDB(B0, 0, 0); PG8_LDB(B1, 0, 1); PG8_SCHED; PG8_LDA(At, 0, 0); PG8_STAGE(PG8_SA(1, 1), a1 + hstep, voffA);
;             PG8_WAIT_V(8); PG8_WAIT_L(0); PG8_BAR; PG8_MMA(0, 0, At, B0); PG8_MMA(0, 1, At, B1); PG8_BAR; PG8_SCHED;
;             PG8_LDA(At, 0, 1); PG8_STAGE(PG8_SB(0, 0), b2, voffB); PG8_STAGE(PG8_SB(0, 1), b2 + hstep, voffB); PG8_STAGE(PG8_SA(0, 0), a2, voffA);
;             PG8_WAIT_V(8); PG8_WAIT_L(0); PG8_BAR; PG8_MMA(1, 0, At, B0); PG8_MMA(1, 1, At, B1); PG8_BAR; PG8_SCHED;
.LBB0_760:
	ds_read_b128 v[128:131], v188
	ds_read_b128 v[132:135], v189
	ds_read_b128 v[136:139], v190
	ds_read_b128 v[140:143], v191
	ds_read_b128 v[144:147], v192
	ds_read_b128 v[148:151], v193
	ds_read_b128 v[172:175], v194
	ds_read_b128 v[176:179], v195
	s_add_u32 s46, s44, 0xfffc0080
	s_addc_u32 s47, s45, -1
	s_cmp_eq_u32 s74, 12
	s_cselect_b32 s49, s9, s47
	s_cselect_b32 s48, s11, s46
	s_cselect_b32 s47, s31, s73
	s_cselect_b32 s46, s35, s72
	s_mov_b32 m0, s68
	v_lshl_add_u64 v[236:237], s[44:45], 0, v[166:167]
	ds_read_b128 v[180:183], v186
	ds_read_b128 v[208:211], v186 offset:1024
	ds_read_b128 v[212:215], v186 offset:2048
	ds_read_b128 v[216:219], v186 offset:3072
	ds_read_b128 v[220:223], v186 offset:4096
	ds_read_b128 v[224:227], v186 offset:5120
	ds_read_b128 v[228:231], v186 offset:6144
	ds_read_b128 v[232:235], v186 offset:7168
	global_load_lds_dwordx4 v[236:237], off
	v_lshl_add_u64 v[236:237], s[44:45], 0, v[164:165]
	s_mov_b32 m0, s69
	s_nop 0
	global_load_lds_dwordx4 v[236:237], off
	s_waitcnt vmcnt(8)
	s_waitcnt lgkmcnt(0)
	s_barrier
	s_waitcnt lgkmcnt(0)
	v_mfma_f32_16x16x32_bf16 v[124:127], v[128:131], v[180:183], v[124:127]
	v_mfma_f32_16x16x32_bf16 v[120:123], v[136:139], v[180:183], v[120:123]
	v_mfma_f32_16x16x32_bf16 v[108:111], v[128:131], v[212:215], v[108:111]
	v_mfma_f32_16x16x32_bf16 v[104:107], v[136:139], v[212:215], v[104:107]
	v_mfma_f32_16x16x32_bf16 v[92:95], v[128:131], v[220:223], v[92:95]
	v_mfma_f32_16x16x32_bf16 v[88:91], v[136:139], v[220:223], v[88:91]
	v_mfma_f32_16x16x32_bf16 v[76:79], v[128:131], v[228:231], v[76:79]
	v_mfma_f32_16x16x32_bf16 v[72:75], v[136:139], v[228:231], v[72:75]
	v_mfma_f32_16x16x32_bf16 v[124:127], v[132:135], v[208:211], v[124:127]
	v_mfma_f32_16x16x32_bf16 v[120:123], v[140:143], v[208:211], v[120:123]
	v_mfma_f32_16x16x32_bf16 v[108:111], v[132:135], v[216:219], v[108:111]
	v_mfma_f32_16x16x32_bf16 v[104:107], v[140:143], v[216:219], v[104:107]
	v_mfma_f32_16x16x32_bf16 v[92:95], v[132:135], v[224:227], v[92:95]
	v_mfma_f32_16x16x32_bf16 v[88:91], v[140:143], v[224:227], v[88:91]
	v_mfma_f32_16x16x32_bf16 v[76:79], v[132:135], v[232:235], v[76:79]
	v_mfma_f32_16x16x32_bf16 v[72:75], v[140:143], v[232:235], v[72:75]
	v_mfma_f32_16x16x32_bf16 v[116:119], v[144:147], v[180:183], v[116:119]
	v_mfma_f32_16x16x32_bf16 v[112:115], v[172:175], v[180:183], v[112:115]
	v_mfma_f32_16x16x32_bf16 v[100:103], v[144:147], v[212:215], v[100:103]
	v_mfma_f32_16x16x32_bf16 v[96:99], v[172:175], v[212:215], v[96:99]
	v_mfma_f32_16x16x32_bf16 v[84:87], v[144:147], v[220:223], v[84:87]
	v_mfma_f32_16x16x32_bf16 v[80:83], v[172:175], v[220:223], v[80:83]
	v_mfma_f32_16x16x32_bf16 v[68:71], v[144:147], v[228:231], v[68:71]
	v_mfma_f32_16x16x32_bf16 v[64:67], v[172:175], v[228:231], v[64:67]
	v_mfma_f32_16x16x32_bf16 v[116:119], v[148:151], v[208:211], v[116:119]
	v_mfma_f32_16x16x32_bf16 v[112:115], v[176:179], v[208:211], v[112:115]
	v_mfma_f32_16x16x32_bf16 v[100:103], v[148:151], v[216:219], v[100:103]
	v_mfma_f32_16x16x32_bf16 v[96:99], v[176:179], v[216:219], v[96:99]
	v_mfma_f32_16x16x32_bf16 v[84:87], v[148:151], v[224:227], v[84:87]
	v_mfma_f32_16x16x32_bf16 v[80:83], v[176:179], v[224:227], v[80:83]
	v_mfma_f32_16x16x32_bf16 v[68:71], v[148:151], v[232:235], v[68:71]
	v_mfma_f32_16x16x32_bf16 v[64:67], v[176:179], v[232:235], v[64:67]
	s_barrier
	s_mov_b32 m0, s51
	v_lshl_add_u64 v[236:237], s[46:47], 0, v[154:155]
	s_add_u32 s76, s46, 0x40000
	ds_read_b128 v[180:183], v186 offset:16384
	ds_read_b128 v[208:211], v186 offset:17408
	ds_read_b128 v[212:215], v186 offset:18432
	ds_read_b128 v[216:219], v186 offset:19456
	ds_read_b128 v[220:223], v186 offset:20480
	ds_read_b128 v[224:227], v186 offset:21504
	ds_read_b128 v[228:231], v186 offset:22528
	ds_read_b128 v[232:235], v186 offset:23552
	global_load_lds_dwordx4 v[236:237], off
	v_lshl_add_u64 v[238:239], s[46:47], 0, v[158:159]
	s_mov_b32 m0, s52
	s_addc_u32 s77, s47, 0
	global_load_lds_dwordx4 v[238:239], off
	v_lshl_add_u64 v[240:241], s[76:77], 0, v[154:155]
	s_mov_b32 m0, s53
	v_lshl_add_u64 v[242:243], s[48:49], 0, v[156:157]
	global_load_lds_dwordx4 v[240:241], off
	v_lshl_add_u64 v[240:241], s[76:77], 0, v[158:159]
	s_mov_b32 m0, s54
	s_nop 0
	global_load_lds_dwordx4 v[240:241], off
	v_lshl_add_u64 v[240:241], s[48:49], 0, v[152:153]
	s_mov_b32 m0, s50
	s_nop 0
	global_load_lds_dwordx4 v[240:241], off
	s_mov_b32 m0, s55
	s_nop 0
	global_load_lds_dwordx4 v[242:243], off
	s_waitcnt vmcnt(8)
	s_waitcnt lgkmcnt(0)
	s_barrier
	s_waitcnt lgkmcnt(0)
	v_mfma_f32_16x16x32_bf16 v[60:63], v[128:131], v[180:183], v[60:63]
	v_mfma_f32_16x16x32_bf16 v[56:59], v[136:139], v[180:183], v[56:59]
	v_mfma_f32_16x16x32_bf16 v[44:47], v[128:131], v[212:215], v[44:47]
	v_mfma_f32_16x16x32_bf16 v[40:43], v[136:139], v[212:215], v[40:43]
	v_mfma_f32_16x16x32_bf16 v[28:31], v[128:131], v[220:223], v[28:31]
	v_mfma_f32_16x16x32_bf16 v[24:27], v[136:139], v[220:223], v[24:27]
	v_mfma_f32_16x16x32_bf16 v[12:15], v[128:131], v[228:231], v[12:15]
	v_mfma_f32_16x16x32_bf16 v[8:11], v[136:139], v[228:231], v[8:11]
	v_mfma_f32_16x16x32_bf16 v[60:63], v[132:135], v[208:211], v[60:63]
	v_mfma_f32_16x16x32_bf16 v[56:59], v[140:143], v[208:211], v[56:59]
	v_mfma_f32_16x16x32_bf16 v[44:47], v[132:135], v[216:219], v[44:47]
	v_mfma_f32_16x16x32_bf16 v[40:43], v[140:143], v[216:219], v[40:43]
	v_mfma_f32_16x16x32_bf16 v[28:31], v[132:135], v[224:227], v[28:31]
	v_mfma_f32_16x16x32_bf16 v[24:27], v[140:143], v[224:227], v[24:27]
	v_mfma_f32_16x16x32_bf16 v[12:15], v[132:135], v[232:235], v[12:15]
	v_mfma_f32_16x16x32_bf16 v[8:11], v[140:143], v[232:235], v[8:11]
	v_mfma_f32_16x16x32_bf16 v[52:55], v[144:147], v[180:183], v[52:55]
	v_mfma_f32_16x16x32_bf16 v[48:51], v[172:175], v[180:183], v[48:51]
	v_mfma_f32_16x16x32_bf16 v[36:39], v[144:147], v[212:215], v[36:39]
	v_mfma_f32_16x16x32_bf16 v[32:35], v[172:175], v[212:215], v[32:35]
	v_mfma_f32_16x16x32_bf16 v[20:23], v[144:147], v[220:223], v[20:23]
	v_mfma_f32_16x16x32_bf16 v[16:19], v[172:175], v[220:223], v[16:19]
	v_mfma_f32_16x16x32_bf16 v[4:7], v[144:147], v[228:231], v[4:7]
	v_mfma_f32_16x16x32_bf16 v[0:3], v[172:175], v[228:231], v[0:3]
	v_mfma_f32_16x16x32_bf16 v[52:55], v[148:151], v[208:211], v[52:55]
	v_mfma_f32_16x16x32_bf16 v[48:51], v[176:179], v[208:211], v[48:51]
	v_mfma_f32_16x16x32_bf16 v[36:39], v[148:151], v[216:219], v[36:39]
	v_mfma_f32_16x16x32_bf16 v[32:35], v[176:179], v[216:219], v[32:35]
	v_mfma_f32_16x16x32_bf16 v[20:23], v[148:151], v[224:227], v[20:23]
	v_mfma_f32_16x16x32_bf16 v[16:19], v[176:179], v[224:227], v[16:19]
	v_mfma_f32_16x16x32_bf16 v[4:7], v[148:151], v[232:235], v[4:7]
	v_mfma_f32_16x16x32_bf16 v[0:3], v[176:179], v[232:235], v[0:3]
	s_barrier
; #define PG8_STAGE(bufoff, gbase, voff) do { _Pragma("unroll") for (int _i = 0; _i < 2; ++_i) \
;         __builtin_amdgcn_global_load_lds((const unsigned*)((const char*)(gbase) + (voff)[_i]), (PG8_LAS unsigned*)(lds + (bufoff) + ldsw + _i * 8192), 16, 0, 0); } while (0)
; #define PG8_LDA(dst, b, h) do { _Pragma("unroll") for (int m = 0; m < 4; ++m) _Pragma("unroll") for (int k = 0; k < 2; ++k) dst[m][k] = *(const PG8_LAS bf16x8*)(lds + PG8_SA(b, h) + aoff + m * 2048 + k * 1024); } while (0)
; #define PG8_LDB(dst, b, h) do { _Pragma("unroll") for (int n = 0; n < 2; ++n) _Pragma("unroll") for (int k = 0; k < 2; ++k) dst[n][k] = *(const PG8_LAS bf16x8*)(lds + PG8_SB(b, h) + boff + n * 2048 + k * 1024); } while (0)
; #define PG8_MMA(ai, bj, At, Bt) do { __builtin_amdgcn_s_setprio(1); _Pragma("unroll") for (int m = 0; m < 4; ++m) _Pragma("unroll") for (int n = 0; n < 2; ++n) _Pragma("unroll") for (int k = 0; k < 2; ++k) \
;         acc[ai][bj][m][n] = __builtin_amdgcn_mfma_f32_16x16x32_bf16(Bt[n][k], At[m][k], acc[ai][bj][m][n], 0, 0, 0); __builtin_amdgcn_s_setprio(0); } while (0)
; #define PG8_WAIT_V(n) asm volatile("s_waitcnt vmcnt(" #n ")" ::: "memory")
; #define PG8_WAIT_L(n) asm volatile("s_waitcnt lgkmcnt(" #n ")" ::: "memory")
; #define PG8_BAR __builtin_amdgcn_s_barrier()
; #define PG8_SCHED __builtin_amdgcn_sched_barrier(0)
; template <class Epi, class Sched, bool ALIGN_EPI = false, bool SP2 = false>
; __device__ __forceinline__ void gemm_phase(PG8_LAS unsigned char* lds, const Gemm g, const Sched& S, const Epi& E) {
;     ...
;             PG8_LDB(B0, 1, 0); PG8_LDB(B1, 1, 1); PG8_SCHED; PG8_LDA(At, 1, 0); PG8_STAGE(PG8_SA(0, 1), a2 + hstep, voffA);
;             PG8_WAIT_V(8); PG8_WAIT_L(0); PG8_BAR; PG8_MMA(0, 0, At, B0); PG8_MMA(0, 1, At, B1); PG8_BAR; PG8_SCHED;
;             PG8_LDA(At, 1, 1); PG8_STAGE(PG8_SB(1, 0), b3, voffB); PG8_STAGE(PG8_SB(1, 1), b3 + hstep, voffB); PG8_STAGE(PG8_SA(1, 0), a3, voffA);
;             PG8_WAIT_V(8); PG8_WAIT_L(0); PG8_BAR; PG8_MMA(1, 0, At, B0); PG8_MMA(1, 1, At, B1); PG8_BAR; PG8_SCHED;
	ds_read_b128 v[128:131], v196
	ds_read_b128 v[132:135], v197
	ds_read_b128 v[136:139], v198
	ds_read_b128 v[140:143], v199
	ds_read_b128 v[144:147], v200
	ds_read_b128 v[148:151], v201
	ds_read_b128 v[172:175], v202
	ds_read_b128 v[176:179], v203
	s_add_u32 s48, s48, 0x40000
	s_addc_u32 s49, s49, 0
	s_mov_b32 m0, s56
	v_lshl_add_u64 v[244:245], s[48:49], 0, v[152:153]
	ds_read_b128 v[180:183], v186 offset:32768
	ds_read_b128 v[208:211], v186 offset:33792
	ds_read_b128 v[212:215], v186 offset:34816
	ds_read_b128 v[216:219], v186 offset:35840
	ds_read_b128 v[220:223], v186 offset:36864
	ds_read_b128 v[224:227], v186 offset:37888
	ds_read_b128 v[228:231], v186 offset:38912
	ds_read_b128 v[232:235], v186 offset:39936
	global_load_lds_dwordx4 v[244:245], off
	v_lshl_add_u64 v[244:245], s[48:49], 0, v[156:157]
	s_mov_b32 m0, s57
	s_nop 0
	global_load_lds_dwordx4 v[244:245], off
	s_waitcnt vmcnt(8)
	s_waitcnt lgkmcnt(0)
	s_barrier
	s_waitcnt lgkmcnt(0)
	v_mfma_f32_16x16x32_bf16 v[124:127], v[128:131], v[180:183], v[124:127]
	v_mfma_f32_16x16x32_bf16 v[120:123], v[136:139], v[180:183], v[120:123]
	v_mfma_f32_16x16x32_bf16 v[108:111], v[128:131], v[212:215], v[108:111]
	v_mfma_f32_16x16x32_bf16 v[104:107], v[136:139], v[212:215], v[104:107]
	v_mfma_f32_16x16x32_bf16 v[92:95], v[128:131], v[220:223], v[92:95]
	v_mfma_f32_16x16x32_bf16 v[88:91], v[136:139], v[220:223], v[88:91]
	v_mfma_f32_16x16x32_bf16 v[76:79], v[128:131], v[228:231], v[76:79]
	v_mfma_f32_16x16x32_bf16 v[72:75], v[136:139], v[228:231], v[72:75]
	v_mfma_f32_16x16x32_bf16 v[124:127], v[132:135], v[208:211], v[124:127]
	v_mfma_f32_16x16x32_bf16 v[120:123], v[140:143], v[208:211], v[120:123]
	v_mfma_f32_16x16x32_bf16 v[108:111], v[132:135], v[216:219], v[108:111]
	v_mfma_f32_16x16x32_bf16 v[104:107], v[140:143], v[216:219], v[104:107]
	v_mfma_f32_16x16x32_bf16 v[92:95], v[132:135], v[224:227], v[92:95]
	v_mfma_f32_16x16x32_bf16 v[88:91], v[140:143], v[224:227], v[88:91]
	v_mfma_f32_16x16x32_bf16 v[76:79], v[132:135], v[232:235], v[76:79]
	v_mfma_f32_16x16x32_bf16 v[72:75], v[140:143], v[232:235], v[72:75]
	v_mfma_f32_16x16x32_bf16 v[116:119], v[144:147], v[180:183], v[116:119]
	v_mfma_f32_16x16x32_bf16 v[112:115], v[172:175], v[180:183], v[112:115]
	v_mfma_f32_16x16x32_bf16 v[100:103], v[144:147], v[212:215], v[100:103]
	v_mfma_f32_16x16x32_bf16 v[96:99], v[172:175], v[212:215], v[96:99]
	v_mfma_f32_16x16x32_bf16 v[84:87], v[144:147], v[220:223], v[84:87]
	v_mfma_f32_16x16x32_bf16 v[80:83], v[172:175], v[220:223], v[80:83]
	v_mfma_f32_16x16x32_bf16 v[68:71], v[144:147], v[228:231], v[68:71]
	v_mfma_f32_16x16x32_bf16 v[64:67], v[172:175], v[228:231], v[64:67]
	v_mfma_f32_16x16x32_bf16 v[116:119], v[148:151], v[208:211], v[116:119]
	v_mfma_f32_16x16x32_bf16 v[112:115], v[176:179], v[208:211], v[112:115]
	v_mfma_f32_16x16x32_bf16 v[100:103], v[148:151], v[216:219], v[100:103]
	v_mfma_f32_16x16x32_bf16 v[96:99], v[176:179], v[216:219], v[96:99]
	v_mfma_f32_16x16x32_bf16 v[84:87], v[148:151], v[224:227], v[84:87]
	v_mfma_f32_16x16x32_bf16 v[80:83], v[176:179], v[224:227], v[80:83]
	v_mfma_f32_16x16x32_bf16 v[68:71], v[148:151], v[232:235], v[68:71]
	v_mfma_f32_16x16x32_bf16 v[64:67], v[176:179], v[232:235], v[64:67]
	s_barrier
	s_mov_b32 m0, s59
	v_lshl_add_u64 v[236:237], v[236:237], 0, s[24:25]
	s_add_u32 s46, s46, 0x40080
	ds_read_b128 v[180:183], v186 offset:49152
	ds_read_b128 v[208:211], v186 offset:50176
	ds_read_b128 v[212:215], v186 offset:51200
	ds_read_b128 v[216:219], v186 offset:52224
	ds_read_b128 v[220:223], v186 offset:53248
	ds_read_b128 v[224:227], v186 offset:54272
	ds_read_b128 v[228:231], v186 offset:55296
	ds_read_b128 v[232:235], v186 offset:56320
	global_load_lds_dwordx4 v[236:237], off
	v_lshl_add_u64 v[236:237], v[238:239], 0, s[24:25]
	s_mov_b32 m0, s60
	s_addc_u32 s47, s47, 0
	global_load_lds_dwordx4 v[236:237], off
	v_lshl_add_u64 v[236:237], s[46:47], 0, v[154:155]
	s_mov_b32 m0, s63
	s_nop 0
	global_load_lds_dwordx4 v[236:237], off
	v_lshl_add_u64 v[236:237], s[46:47], 0, v[158:159]
	s_mov_b32 m0, s64
	s_nop 0
	global_load_lds_dwordx4 v[236:237], off
	v_lshl_add_u64 v[236:237], v[240:241], 0, s[24:25]
	s_mov_b32 m0, s61
	s_nop 0
	global_load_lds_dwordx4 v[236:237], off
	v_lshl_add_u64 v[236:237], v[242:243], 0, s[24:25]
	s_mov_b32 m0, s62
	s_nop 0
	global_load_lds_dwordx4 v[236:237], off
	s_waitcnt vmcnt(8)
	s_waitcnt lgkmcnt(0)
	s_barrier
	s_waitcnt lgkmcnt(0)
	v_mfma_f32_16x16x32_bf16 v[60:63], v[128:131], v[180:183], v[60:63]
	v_mfma_f32_16x16x32_bf16 v[56:59], v[136:139], v[180:183], v[56:59]
	v_mfma_f32_16x16x32_bf16 v[44:47], v[128:131], v[212:215], v[44:47]
	v_mfma_f32_16x16x32_bf16 v[40:43], v[136:139], v[212:215], v[40:43]
	v_mfma_f32_16x16x32_bf16 v[28:31], v[128:131], v[220:223], v[28:31]
	v_mfma_f32_16x16x32_bf16 v[24:27], v[136:139], v[220:223], v[24:27]
	v_mfma_f32_16x16x32_bf16 v[12:15], v[128:131], v[228:231], v[12:15]
	v_mfma_f32_16x16x32_bf16 v[8:11], v[136:139], v[228:231], v[8:11]
	v_mfma_f32_16x16x32_bf16 v[60:63], v[132:135], v[208:211], v[60:63]
	v_mfma_f32_16x16x32_bf16 v[56:59], v[140:143], v[208:211], v[56:59]
	v_mfma_f32_16x16x32_bf16 v[44:47], v[132:135], v[216:219], v[44:47]
	v_mfma_f32_16x16x32_bf16 v[40:43], v[140:143], v[216:219], v[40:43]
	v_mfma_f32_16x16x32_bf16 v[28:31], v[132:135], v[224:227], v[28:31]
	v_mfma_f32_16x16x32_bf16 v[24:27], v[140:143], v[224:227], v[24:27]
	v_mfma_f32_16x16x32_bf16 v[12:15], v[132:135], v[232:235], v[12:15]
	v_mfma_f32_16x16x32_bf16 v[8:11], v[140:143], v[232:235], v[8:11]
	v_mfma_f32_16x16x32_bf16 v[52:55], v[144:147], v[180:183], v[52:55]
	v_mfma_f32_16x16x32_bf16 v[48:51], v[172:175], v[180:183], v[48:51]
	v_mfma_f32_16x16x32_bf16 v[36:39], v[144:147], v[212:215], v[36:39]
	v_mfma_f32_16x16x32_bf16 v[32:35], v[172:175], v[212:215], v[32:35]
	v_mfma_f32_16x16x32_bf16 v[20:23], v[144:147], v[220:223], v[20:23]
	v_mfma_f32_16x16x32_bf16 v[16:19], v[172:175], v[220:223], v[16:19]
	v_mfma_f32_16x16x32_bf16 v[4:7], v[144:147], v[228:231], v[4:7]
	v_mfma_f32_16x16x32_bf16 v[0:3], v[172:175], v[228:231], v[0:3]
	v_mfma_f32_16x16x32_bf16 v[52:55], v[148:151], v[208:211], v[52:55]
	v_mfma_f32_16x16x32_bf16 v[48:51], v[176:179], v[208:211], v[48:51]
	v_mfma_f32_16x16x32_bf16 v[36:39], v[148:151], v[216:219], v[36:39]
	v_mfma_f32_16x16x32_bf16 v[32:35], v[176:179], v[216:219], v[32:35]
	v_mfma_f32_16x16x32_bf16 v[20:23], v[148:151], v[224:227], v[20:23]
	v_mfma_f32_16x16x32_bf16 v[16:19], v[176:179], v[224:227], v[16:19]
	v_mfma_f32_16x16x32_bf16 v[4:7], v[148:151], v[232:235], v[4:7]
	v_mfma_f32_16x16x32_bf16 v[0:3], v[176:179], v[232:235], v[0:3]
	s_barrier
	s_add_i32 s74, s74, 2
	s_add_u32 s72, s72, 0x100
	s_addc_u32 s73, s73, 0
	s_add_u32 s44, s44, 0x100
	s_addc_u32 s45, s45, 0
	s_cmp_gt_u32 s74, 13
	s_cbranch_scc0 .LBB0_760
	s_and_b64 vcc, exec, s[26:27]
	s_cbranch_vccz .LBB0_763
	s_barrier

; #define PG8_STAGE(bufoff, gbase, voff) do { _Pragma("unroll") for (int _i = 0; _i < 2; ++_i) \
;         __builtin_amdgcn_global_load_lds((const unsigned*)((const char*)(gbase) + (voff)[_i]), (PG8_LAS unsigned*)(lds + (bufoff) + ldsw + _i * 8192), 16, 0, 0); } while (0)
; #define PG8_LDA(dst, b, h) do { _Pragma("unroll") for (int m = 0; m < 4; ++m) _Pragma("unroll") for (int k = 0; k < 2; ++k) dst[m][k] = *(const PG8_LAS bf16x8*)(lds + PG8_SA(b, h) + aoff + m * 2048 + k * 1024); } while (0)
; #define PG8_LDB(dst, b, h) do { _Pragma("unroll") for (int n = 0; n < 2; ++n) _Pragma("unroll") for (int k = 0; k < 2; ++k) dst[n][k] = *(const PG8_LAS bf16x8*)(lds + PG8_SB(b, h) + boff + n * 2048 + k * 1024); } while (0)
; #define PG8_MMA(ai, bj, At, Bt) do { __builtin_amdgcn_s_setprio(1); _Pragma("unroll") for (int m = 0; m < 4; ++m) _Pragma("unroll") for (int n = 0; n < 2; ++n) _Pragma("unroll") for (int k = 0; k < 2; ++k) \
;         acc[ai][bj][m][n] = __builtin_amdgcn_mfma_f32_16x16x32_bf16(Bt[n][k], At[m][k], acc[ai][bj][m][n], 0, 0, 0); __builtin_amdgcn_s_setprio(0); } while (0)
; #define PG8_WAIT_V(n) asm volatile("s_waitcnt vmcnt(" #n ")" ::: "memory")
; #define PG8_WAIT_L(n) asm volatile("s_waitcnt lgkmcnt(" #n ")" ::: "memory")
; #define PG8_BAR __builtin_amdgcn_s_barrier()
; #define PG8_SCHED __builtin_amdgcn_sched_barrier(0)
; template <class Epi, class Sched, bool ALIGN_EPI = false, bool SP2 = false>
; __device__ __forceinline__ void gemm_phase(PG8_LAS unsigned char* lds, const Gemm g, const Sched& S, const Epi& E) {
;     ...
;             PG8_LDB(B0, 0, 0); PG8_LDB(B1, 0, 1); PG8_SCHED; PG8_LDA(At, 0, 0); PG8_STAGE(PG8_SA(1, 1), a1 + hstep, voffA);
;             PG8_WAIT_V(8); PG8_WAIT_L(0); PG8_BAR; PG8_MMA(0, 0, At, B0); PG8_MMA(0, 1, At, B1); PG8_BAR; PG8_SCHED;
;             PG8_LDA(At, 0, 1); PG8_STAGE(PG8_SB(0, 0), b2, voffB); PG8_STAGE(PG8_SB(0, 1), b2 + hstep, voffB); PG8_STAGE(PG8_SA(0, 0), a2, voffA);
;             PG8_WAIT_V(8); PG8_WAIT_L(0); PG8_BAR; PG8_MMA(1, 0, At, B0); PG8_MMA(1, 1, At, B1); PG8_BAR; PG8_SCHED;
.LBB0_1463:
	ds_read_b128 v[144:147], v151
	ds_read_b128 v[168:171], v152
	ds_read_b128 v[172:175], v153
	ds_read_b128 v[176:179], v154
	ds_read_b128 v[180:183], v155
	ds_read_b128 v[186:189], v156
	ds_read_b128 v[190:193], v157
	ds_read_b128 v[194:197], v158
	s_add_u32 s42, s36, 0xfffc0080
	s_addc_u32 s43, s37, -1
	s_cmp_eq_u32 s72, 12
	s_cselect_b32 s45, s27, s43
	s_cselect_b32 s44, s35, s42
	s_cselect_b32 s43, s25, s71
	s_cselect_b32 s42, s69, s70
	s_mov_b32 m0, s66
	v_lshl_add_u64 v[230:231], s[36:37], 0, v[138:139]
	ds_read_b128 v[198:201], v149
	ds_read_b128 v[202:205], v149 offset:1024
	ds_read_b128 v[206:209], v149 offset:2048
	ds_read_b128 v[210:213], v149 offset:3072
	ds_read_b128 v[214:217], v149 offset:4096
	ds_read_b128 v[218:221], v149 offset:5120
	ds_read_b128 v[222:225], v149 offset:6144
	ds_read_b128 v[226:229], v149 offset:7168
	global_load_lds_dwordx4 v[230:231], off
	v_lshl_add_u64 v[230:231], s[36:37], 0, v[136:137]
	s_mov_b32 m0, s67
	s_nop 0
	global_load_lds_dwordx4 v[230:231], off
	s_waitcnt vmcnt(8)
	s_waitcnt lgkmcnt(0)
	s_barrier
	s_waitcnt lgkmcnt(0)
	v_mfma_f32_16x16x32_bf16 v[124:127], v[144:147], v[198:201], v[124:127]
	v_mfma_f32_16x16x32_bf16 v[120:123], v[172:175], v[198:201], v[120:123]
	v_mfma_f32_16x16x32_bf16 v[108:111], v[144:147], v[206:209], v[108:111]
	v_mfma_f32_16x16x32_bf16 v[104:107], v[172:175], v[206:209], v[104:107]
	v_mfma_f32_16x16x32_bf16 v[92:95], v[144:147], v[214:217], v[92:95]
	v_mfma_f32_16x16x32_bf16 v[88:91], v[172:175], v[214:217], v[88:91]
	v_mfma_f32_16x16x32_bf16 v[76:79], v[144:147], v[222:225], v[76:79]
	v_mfma_f32_16x16x32_bf16 v[72:75], v[172:175], v[222:225], v[72:75]
	v_mfma_f32_16x16x32_bf16 v[124:127], v[168:171], v[202:205], v[124:127]
	v_mfma_f32_16x16x32_bf16 v[120:123], v[176:179], v[202:205], v[120:123]
	v_mfma_f32_16x16x32_bf16 v[108:111], v[168:171], v[210:213], v[108:111]
	v_mfma_f32_16x16x32_bf16 v[104:107], v[176:179], v[210:213], v[104:107]
	v_mfma_f32_16x16x32_bf16 v[92:95], v[168:171], v[218:221], v[92:95]
	v_mfma_f32_16x16x32_bf16 v[88:91], v[176:179], v[218:221], v[88:91]
	v_mfma_f32_16x16x32_bf16 v[76:79], v[168:171], v[226:229], v[76:79]
	v_mfma_f32_16x16x32_bf16 v[72:75], v[176:179], v[226:229], v[72:75]
	v_mfma_f32_16x16x32_bf16 v[116:119], v[180:183], v[198:201], v[116:119]
	v_mfma_f32_16x16x32_bf16 v[112:115], v[190:193], v[198:201], v[112:115]
	v_mfma_f32_16x16x32_bf16 v[100:103], v[180:183], v[206:209], v[100:103]
	v_mfma_f32_16x16x32_bf16 v[96:99], v[190:193], v[206:209], v[96:99]
	v_mfma_f32_16x16x32_bf16 v[84:87], v[180:183], v[214:217], v[84:87]
	v_mfma_f32_16x16x32_bf16 v[80:83], v[190:193], v[214:217], v[80:83]
	v_mfma_f32_16x16x32_bf16 v[68:71], v[180:183], v[222:225], v[68:71]
	v_mfma_f32_16x16x32_bf16 v[64:67], v[190:193], v[222:225], v[64:67]
	v_mfma_f32_16x16x32_bf16 v[116:119], v[186:189], v[202:205], v[116:119]
	v_mfma_f32_16x16x32_bf16 v[112:115], v[194:197], v[202:205], v[112:115]
	v_mfma_f32_16x16x32_bf16 v[100:103], v[186:189], v[210:213], v[100:103]
	v_mfma_f32_16x16x32_bf16 v[96:99], v[194:197], v[210:213], v[96:99]
	v_mfma_f32_16x16x32_bf16 v[84:87], v[186:189], v[218:221], v[84:87]
	v_mfma_f32_16x16x32_bf16 v[80:83], v[194:197], v[218:221], v[80:83]
	v_mfma_f32_16x16x32_bf16 v[68:71], v[186:189], v[226:229], v[68:71]
	v_mfma_f32_16x16x32_bf16 v[64:67], v[194:197], v[226:229], v[64:67]
	s_barrier
	s_mov_b32 m0, s50
	v_lshl_add_u64 v[230:231], s[42:43], 0, v[130:131]
	s_add_u32 s74, s42, 0x40000
	ds_read_b128 v[198:201], v149 offset:16384
	ds_read_b128 v[202:205], v149 offset:17408
	ds_read_b128 v[206:209], v149 offset:18432
	ds_read_b128 v[210:213], v149 offset:19456
	ds_read_b128 v[214:217], v149 offset:20480
	ds_read_b128 v[218:221], v149 offset:21504
	ds_read_b128 v[222:225], v149 offset:22528
	ds_read_b128 v[226:229], v149 offset:23552
	global_load_lds_dwordx4 v[230:231], off
	v_lshl_add_u64 v[232:233], s[42:43], 0, v[134:135]
	s_mov_b32 m0, s51
	s_addc_u32 s75, s43, 0
	global_load_lds_dwordx4 v[232:233], off
	v_lshl_add_u64 v[234:235], s[74:75], 0, v[130:131]
	s_mov_b32 m0, s52
	v_lshl_add_u64 v[236:237], s[44:45], 0, v[132:133]
	global_load_lds_dwordx4 v[234:235], off
	v_lshl_add_u64 v[234:235], s[74:75], 0, v[134:135]
	s_mov_b32 m0, s53
	s_nop 0
	global_load_lds_dwordx4 v[234:235], off
	v_lshl_add_u64 v[234:235], s[44:45], 0, v[128:129]
	s_mov_b32 m0, s49
	s_nop 0
	global_load_lds_dwordx4 v[234:235], off
	s_mov_b32 m0, s54
	s_nop 0
	global_load_lds_dwordx4 v[236:237], off
	s_waitcnt vmcnt(8)
	s_waitcnt lgkmcnt(0)
	s_barrier
	s_waitcnt lgkmcnt(0)
	v_mfma_f32_16x16x32_bf16 v[60:63], v[144:147], v[198:201], v[60:63]
	v_mfma_f32_16x16x32_bf16 v[56:59], v[172:175], v[198:201], v[56:59]
	v_mfma_f32_16x16x32_bf16 v[44:47], v[144:147], v[206:209], v[44:47]
	v_mfma_f32_16x16x32_bf16 v[40:43], v[172:175], v[206:209], v[40:43]
	v_mfma_f32_16x16x32_bf16 v[28:31], v[144:147], v[214:217], v[28:31]
	v_mfma_f32_16x16x32_bf16 v[24:27], v[172:175], v[214:217], v[24:27]
	v_mfma_f32_16x16x32_bf16 v[12:15], v[144:147], v[222:225], v[12:15]
	v_mfma_f32_16x16x32_bf16 v[8:11], v[172:175], v[222:225], v[8:11]
	v_mfma_f32_16x16x32_bf16 v[60:63], v[168:171], v[202:205], v[60:63]
	v_mfma_f32_16x16x32_bf16 v[56:59], v[176:179], v[202:205], v[56:59]
	v_mfma_f32_16x16x32_bf16 v[44:47], v[168:171], v[210:213], v[44:47]
	v_mfma_f32_16x16x32_bf16 v[40:43], v[176:179], v[210:213], v[40:43]
	v_mfma_f32_16x16x32_bf16 v[28:31], v[168:171], v[218:221], v[28:31]
	v_mfma_f32_16x16x32_bf16 v[24:27], v[176:179], v[218:221], v[24:27]
	v_mfma_f32_16x16x32_bf16 v[12:15], v[168:171], v[226:229], v[12:15]
	v_mfma_f32_16x16x32_bf16 v[8:11], v[176:179], v[226:229], v[8:11]
	v_mfma_f32_16x16x32_bf16 v[52:55], v[180:183], v[198:201], v[52:55]
	v_mfma_f32_16x16x32_bf16 v[48:51], v[190:193], v[198:201], v[48:51]
	v_mfma_f32_16x16x32_bf16 v[36:39], v[180:183], v[206:209], v[36:39]
	v_mfma_f32_16x16x32_bf16 v[32:35], v[190:193], v[206:209], v[32:35]
	v_mfma_f32_16x16x32_bf16 v[20:23], v[180:183], v[214:217], v[20:23]
	v_mfma_f32_16x16x32_bf16 v[16:19], v[190:193], v[214:217], v[16:19]
	v_mfma_f32_16x16x32_bf16 v[4:7], v[180:183], v[222:225], v[4:7]
	v_mfma_f32_16x16x32_bf16 v[0:3], v[190:193], v[222:225], v[0:3]
	v_mfma_f32_16x16x32_bf16 v[52:55], v[186:189], v[202:205], v[52:55]
	v_mfma_f32_16x16x32_bf16 v[48:51], v[194:197], v[202:205], v[48:51]
	v_mfma_f32_16x16x32_bf16 v[36:39], v[186:189], v[210:213], v[36:39]
	v_mfma_f32_16x16x32_bf16 v[32:35], v[194:197], v[210:213], v[32:35]
	v_mfma_f32_16x16x32_bf16 v[20:23], v[186:189], v[218:221], v[20:23]
	v_mfma_f32_16x16x32_bf16 v[16:19], v[194:197], v[218:221], v[16:19]
	v_mfma_f32_16x16x32_bf16 v[4:7], v[186:189], v[226:229], v[4:7]
	v_mfma_f32_16x16x32_bf16 v[0:3], v[194:197], v[226:229], v[0:3]
	s_barrier
; #define PG8_STAGE(bufoff, gbase, voff) do { _Pragma("unroll") for (int _i = 0; _i < 2; ++_i) \
;         __builtin_amdgcn_global_load_lds((const unsigned*)((const char*)(gbase) + (voff)[_i]), (PG8_LAS unsigned*)(lds + (bufoff) + ldsw + _i * 8192), 16, 0, 0); } while (0)
; #define PG8_LDA(dst, b, h) do { _Pragma("unroll") for (int m = 0; m < 4; ++m) _Pragma("unroll") for (int k = 0; k < 2; ++k) dst[m][k] = *(const PG8_LAS bf16x8*)(lds + PG8_SA(b, h) + aoff + m * 2048 + k * 1024); } while (0)
; #define PG8_LDB(dst, b, h) do { _Pragma("unroll") for (int n = 0; n < 2; ++n) _Pragma("unroll") for (int k = 0; k < 2; ++k) dst[n][k] = *(const PG8_LAS bf16x8*)(lds + PG8_SB(b, h) + boff + n * 2048 + k * 1024); } while (0)
; #define PG8_MMA(ai, bj, At, Bt) do { __builtin_amdgcn_s_setprio(1); _Pragma("unroll") for (int m = 0; m < 4; ++m) _Pragma("unroll") for (int n = 0; n < 2; ++n) _Pragma("unroll") for (int k = 0; k < 2; ++k) \
;         acc[ai][bj][m][n] = __builtin_amdgcn_mfma_f32_16x16x32_bf16(Bt[n][k], At[m][k], acc[ai][bj][m][n], 0, 0, 0); __builtin_amdgcn_s_setprio(0); } while (0)
; #define PG8_WAIT_V(n) asm volatile("s_waitcnt vmcnt(" #n ")" ::: "memory")
; #define PG8_WAIT_L(n) asm volatile("s_waitcnt lgkmcnt(" #n ")" ::: "memory")
; #define PG8_BAR __builtin_amdgcn_s_barrier()
; #define PG8_SCHED __builtin_amdgcn_sched_barrier(0)
; template <class Epi, class Sched, bool ALIGN_EPI = false, bool SP2 = false>
; __device__ __forceinline__ void gemm_phase(PG8_LAS unsigned char* lds, const Gemm g, const Sched& S, const Epi& E) {
;     ...
;             PG8_LDB(B0, 1, 0); PG8_LDB(B1, 1, 1); PG8_SCHED; PG8_LDA(At, 1, 0); PG8_STAGE(PG8_SA(0, 1), a2 + hstep, voffA);
;             PG8_WAIT_V(8); PG8_WAIT_L(0); PG8_BAR; PG8_MMA(0, 0, At, B0); PG8_MMA(0, 1, At, B1); PG8_BAR; PG8_SCHED;
;             PG8_LDA(At, 1, 1); PG8_STAGE(PG8_SB(1, 0), b3, voffB); PG8_STAGE(PG8_SB(1, 1), b3 + hstep, voffB); PG8_STAGE(PG8_SA(1, 0), a3, voffA);
;             PG8_WAIT_V(8); PG8_WAIT_L(0); PG8_BAR; PG8_MMA(1, 0, At, B0); PG8_MMA(1, 1, At, B1); PG8_BAR; PG8_SCHED;
	ds_read_b128 v[144:147], v159
	ds_read_b128 v[168:171], v160
	ds_read_b128 v[172:175], v161
	ds_read_b128 v[176:179], v162
	ds_read_b128 v[180:183], v163
	ds_read_b128 v[186:189], v164
	ds_read_b128 v[190:193], v165
	ds_read_b128 v[194:197], v166
	s_add_u32 s44, s44, 0x40000
	s_addc_u32 s45, s45, 0
	s_mov_b32 m0, s55
	v_lshl_add_u64 v[238:239], s[44:45], 0, v[128:129]
	ds_read_b128 v[198:201], v149 offset:32768
	ds_read_b128 v[202:205], v149 offset:33792
	ds_read_b128 v[206:209], v149 offset:34816
	ds_read_b128 v[210:213], v149 offset:35840
	ds_read_b128 v[214:217], v149 offset:36864
	ds_read_b128 v[218:221], v149 offset:37888
	ds_read_b128 v[222:225], v149 offset:38912
	ds_read_b128 v[226:229], v149 offset:39936
	global_load_lds_dwordx4 v[238:239], off
	v_lshl_add_u64 v[238:239], s[44:45], 0, v[132:133]
	s_mov_b32 m0, s56
	s_nop 0
	global_load_lds_dwordx4 v[238:239], off
	s_waitcnt vmcnt(8)
	s_waitcnt lgkmcnt(0)
	s_barrier
	s_waitcnt lgkmcnt(0)
	v_mfma_f32_16x16x32_bf16 v[124:127], v[144:147], v[198:201], v[124:127]
	v_mfma_f32_16x16x32_bf16 v[120:123], v[172:175], v[198:201], v[120:123]
	v_mfma_f32_16x16x32_bf16 v[108:111], v[144:147], v[206:209], v[108:111]
	v_mfma_f32_16x16x32_bf16 v[104:107], v[172:175], v[206:209], v[104:107]
	v_mfma_f32_16x16x32_bf16 v[92:95], v[144:147], v[214:217], v[92:95]
	v_mfma_f32_16x16x32_bf16 v[88:91], v[172:175], v[214:217], v[88:91]
	v_mfma_f32_16x16x32_bf16 v[76:79], v[144:147], v[222:225], v[76:79]
	v_mfma_f32_16x16x32_bf16 v[72:75], v[172:175], v[222:225], v[72:75]
	v_mfma_f32_16x16x32_bf16 v[124:127], v[168:171], v[202:205], v[124:127]
	v_mfma_f32_16x16x32_bf16 v[120:123], v[176:179], v[202:205], v[120:123]
	v_mfma_f32_16x16x32_bf16 v[108:111], v[168:171], v[210:213], v[108:111]
	v_mfma_f32_16x16x32_bf16 v[104:107], v[176:179], v[210:213], v[104:107]
	v_mfma_f32_16x16x32_bf16 v[92:95], v[168:171], v[218:221], v[92:95]
	v_mfma_f32_16x16x32_bf16 v[88:91], v[176:179], v[218:221], v[88:91]
	v_mfma_f32_16x16x32_bf16 v[76:79], v[168:171], v[226:229], v[76:79]
	v_mfma_f32_16x16x32_bf16 v[72:75], v[176:179], v[226:229], v[72:75]
	v_mfma_f32_16x16x32_bf16 v[116:119], v[180:183], v[198:201], v[116:119]
	v_mfma_f32_16x16x32_bf16 v[112:115], v[190:193], v[198:201], v[112:115]
	v_mfma_f32_16x16x32_bf16 v[100:103], v[180:183], v[206:209], v[100:103]
	v_mfma_f32_16x16x32_bf16 v[96:99], v[190:193], v[206:209], v[96:99]
	v_mfma_f32_16x16x32_bf16 v[84:87], v[180:183], v[214:217], v[84:87]
	v_mfma_f32_16x16x32_bf16 v[80:83], v[190:193], v[214:217], v[80:83]
	v_mfma_f32_16x16x32_bf16 v[68:71], v[180:183], v[222:225], v[68:71]
	v_mfma_f32_16x16x32_bf16 v[64:67], v[190:193], v[222:225], v[64:67]
	v_mfma_f32_16x16x32_bf16 v[116:119], v[186:189], v[202:205], v[116:119]
	v_mfma_f32_16x16x32_bf16 v[112:115], v[194:197], v[202:205], v[112:115]
	v_mfma_f32_16x16x32_bf16 v[100:103], v[186:189], v[210:213], v[100:103]
	v_mfma_f32_16x16x32_bf16 v[96:99], v[194:197], v[210:213], v[96:99]
	v_mfma_f32_16x16x32_bf16 v[84:87], v[186:189], v[218:221], v[84:87]
	v_mfma_f32_16x16x32_bf16 v[80:83], v[194:197], v[218:221], v[80:83]
	v_mfma_f32_16x16x32_bf16 v[68:71], v[186:189], v[226:229], v[68:71]
	v_mfma_f32_16x16x32_bf16 v[64:67], v[194:197], v[226:229], v[64:67]
	s_barrier
	s_mov_b32 m0, s58
	v_lshl_add_u64 v[230:231], v[230:231], 0, s[18:19]
	s_add_u32 s42, s42, 0x40080
	ds_read_b128 v[198:201], v149 offset:49152
	ds_read_b128 v[202:205], v149 offset:50176
	ds_read_b128 v[206:209], v149 offset:51200
	ds_read_b128 v[210:213], v149 offset:52224
	ds_read_b128 v[214:217], v149 offset:53248
	ds_read_b128 v[218:221], v149 offset:54272
	ds_read_b128 v[222:225], v149 offset:55296
	ds_read_b128 v[226:229], v149 offset:56320
	global_load_lds_dwordx4 v[230:231], off
	v_lshl_add_u64 v[230:231], v[232:233], 0, s[18:19]
	s_mov_b32 m0, s59
	s_addc_u32 s43, s43, 0
	global_load_lds_dwordx4 v[230:231], off
	v_lshl_add_u64 v[230:231], s[42:43], 0, v[130:131]
	s_mov_b32 m0, s62
	s_nop 0
	global_load_lds_dwordx4 v[230:231], off
	v_lshl_add_u64 v[230:231], s[42:43], 0, v[134:135]
	s_mov_b32 m0, s63
	s_nop 0
	global_load_lds_dwordx4 v[230:231], off
	v_lshl_add_u64 v[230:231], v[234:235], 0, s[18:19]
	s_mov_b32 m0, s60
	s_nop 0
	global_load_lds_dwordx4 v[230:231], off
	v_lshl_add_u64 v[230:231], v[236:237], 0, s[18:19]
	s_mov_b32 m0, s61
	s_nop 0
	global_load_lds_dwordx4 v[230:231], off
	s_waitcnt vmcnt(8)
	s_waitcnt lgkmcnt(0)
	s_barrier
	s_waitcnt lgkmcnt(0)
	v_mfma_f32_16x16x32_bf16 v[60:63], v[144:147], v[198:201], v[60:63]
	v_mfma_f32_16x16x32_bf16 v[56:59], v[172:175], v[198:201], v[56:59]
	v_mfma_f32_16x16x32_bf16 v[44:47], v[144:147], v[206:209], v[44:47]
	v_mfma_f32_16x16x32_bf16 v[40:43], v[172:175], v[206:209], v[40:43]
	v_mfma_f32_16x16x32_bf16 v[28:31], v[144:147], v[214:217], v[28:31]
	v_mfma_f32_16x16x32_bf16 v[24:27], v[172:175], v[214:217], v[24:27]
	v_mfma_f32_16x16x32_bf16 v[12:15], v[144:147], v[222:225], v[12:15]
	v_mfma_f32_16x16x32_bf16 v[8:11], v[172:175], v[222:225], v[8:11]
	v_mfma_f32_16x16x32_bf16 v[60:63], v[168:171], v[202:205], v[60:63]
	v_mfma_f32_16x16x32_bf16 v[56:59], v[176:179], v[202:205], v[56:59]
	v_mfma_f32_16x16x32_bf16 v[44:47], v[168:171], v[210:213], v[44:47]
	v_mfma_f32_16x16x32_bf16 v[40:43], v[176:179], v[210:213], v[40:43]
	v_mfma_f32_16x16x32_bf16 v[28:31], v[168:171], v[218:221], v[28:31]
	v_mfma_f32_16x16x32_bf16 v[24:27], v[176:179], v[218:221], v[24:27]
	v_mfma_f32_16x16x32_bf16 v[12:15], v[168:171], v[226:229], v[12:15]
	v_mfma_f32_16x16x32_bf16 v[8:11], v[176:179], v[226:229], v[8:11]
	v_mfma_f32_16x16x32_bf16 v[52:55], v[180:183], v[198:201], v[52:55]
	v_mfma_f32_16x16x32_bf16 v[48:51], v[190:193], v[198:201], v[48:51]
	v_mfma_f32_16x16x32_bf16 v[36:39], v[180:183], v[206:209], v[36:39]
	v_mfma_f32_16x16x32_bf16 v[32:35], v[190:193], v[206:209], v[32:35]
	v_mfma_f32_16x16x32_bf16 v[20:23], v[180:183], v[214:217], v[20:23]
	v_mfma_f32_16x16x32_bf16 v[16:19], v[190:193], v[214:217], v[16:19]
	v_mfma_f32_16x16x32_bf16 v[4:7], v[180:183], v[222:225], v[4:7]
	v_mfma_f32_16x16x32_bf16 v[0:3], v[190:193], v[222:225], v[0:3]
	v_mfma_f32_16x16x32_bf16 v[52:55], v[186:189], v[202:205], v[52:55]
	v_mfma_f32_16x16x32_bf16 v[48:51], v[194:197], v[202:205], v[48:51]
	v_mfma_f32_16x16x32_bf16 v[36:39], v[186:189], v[210:213], v[36:39]
	v_mfma_f32_16x16x32_bf16 v[32:35], v[194:197], v[210:213], v[32:35]
	v_mfma_f32_16x16x32_bf16 v[20:23], v[186:189], v[218:221], v[20:23]
	v_mfma_f32_16x16x32_bf16 v[16:19], v[194:197], v[218:221], v[16:19]
	v_mfma_f32_16x16x32_bf16 v[4:7], v[186:189], v[226:229], v[4:7]
	v_mfma_f32_16x16x32_bf16 v[0:3], v[194:197], v[226:229], v[0:3]
	s_barrier
	s_add_i32 s72, s72, 2
	s_add_u32 s70, s70, 0x100
	s_addc_u32 s71, s71, 0
	s_add_u32 s36, s36, 0x100
	s_addc_u32 s37, s37, 0
	s_cmp_gt_u32 s72, 13
	s_cbranch_scc0 .LBB0_1463
	s_and_b64 vcc, exec, s[20:21]
	s_cbranch_vccz .LBB0_1466
	s_barrier

; #define PG8_STAGE(bufoff, gbase, voff) do { _Pragma("unroll") for (int _i = 0; _i < 2; ++_i) \
;         __builtin_amdgcn_global_load_lds((const unsigned*)((const char*)(gbase) + (voff)[_i]), (PG8_LAS unsigned*)(lds + (bufoff) + ldsw + _i * 8192), 16, 0, 0); } while (0)
; #define PG8_LDA(dst, b, h) do { _Pragma("unroll") for (int m = 0; m < 4; ++m) _Pragma("unroll") for (int k = 0; k < 2; ++k) dst[m][k] = *(const PG8_LAS bf16x8*)(lds + PG8_SA(b, h) + aoff + m * 2048 + k * 1024); } while (0)
; #define PG8_LDB(dst, b, h) do { _Pragma("unroll") for (int n = 0; n < 2; ++n) _Pragma("unroll") for (int k = 0; k < 2; ++k) dst[n][k] = *(const PG8_LAS bf16x8*)(lds + PG8_SB(b, h) + boff + n * 2048 + k * 1024); } while (0)
; #define PG8_MMA(ai, bj, At, Bt) do { __builtin_amdgcn_s_setprio(1); _Pragma("unroll") for (int m = 0; m < 4; ++m) _Pragma("unroll") for (int n = 0; n < 2; ++n) _Pragma("unroll") for (int k = 0; k < 2; ++k) \
;         acc[ai][bj][m][n] = __builtin_amdgcn_mfma_f32_16x16x32_bf16(Bt[n][k], At[m][k], acc[ai][bj][m][n], 0, 0, 0); __builtin_amdgcn_s_setprio(0); } while (0)
; #define PG8_WAIT_V(n) asm volatile("s_waitcnt vmcnt(" #n ")" ::: "memory")
; #define PG8_WAIT_L(n) asm volatile("s_waitcnt lgkmcnt(" #n ")" ::: "memory")
; #define PG8_BAR __builtin_amdgcn_s_barrier()
; #define PG8_SCHED __builtin_amdgcn_sched_barrier(0)
; template <class Epi, class Sched, bool ALIGN_EPI = false, bool SP2 = false>
; __device__ __forceinline__ void gemm_phase(PG8_LAS unsigned char* lds, const Gemm g, const Sched& S, const Epi& E) {
;     ...
;             PG8_LDB(B0, 0, 0); PG8_LDB(B1, 0, 1); PG8_SCHED; PG8_LDA(At, 0, 0); PG8_STAGE(PG8_SA(1, 1), a1 + hstep, voffA);
;             PG8_WAIT_V(8); PG8_WAIT_L(0); PG8_BAR; PG8_MMA(0, 0, At, B0); PG8_MMA(0, 1, At, B1); PG8_BAR; PG8_SCHED;
;             PG8_LDA(At, 0, 1); PG8_STAGE(PG8_SB(0, 0), b2, voffB); PG8_STAGE(PG8_SB(0, 1), b2 + hstep, voffB); PG8_STAGE(PG8_SA(0, 0), a2, voffA);
;             PG8_WAIT_V(8); PG8_WAIT_L(0); PG8_BAR; PG8_MMA(1, 0, At, B0); PG8_MMA(1, 1, At, B1); PG8_BAR; PG8_SCHED;
.LBB0_1744:
	ds_read_b128 v[128:131], v161
	ds_read_b128 v[132:135], v162
	ds_read_b128 v[152:155], v163
	ds_read_b128 v[180:183], v164
	ds_read_b128 v[186:189], v165
	ds_read_b128 v[190:193], v166
	ds_read_b128 v[194:197], v167
	ds_read_b128 v[198:201], v168
	s_add_u32 s48, s12, 0xfffc0080
	s_addc_u32 s49, s13, -1
	s_cmp_eq_u32 s75, 12
	s_cselect_b32 s51, s9, s49
	s_cselect_b32 s50, s11, s48
	s_cselect_b32 s49, s34, s74
	s_cselect_b32 s48, s37, s43
	s_mov_b32 m0, s70
	v_lshl_add_u64 v[156:157], s[12:13], 0, v[146:147]
	ds_read_b128 v[202:205], v159
	ds_read_b128 v[206:209], v159 offset:1024
	ds_read_b128 v[210:213], v159 offset:2048
	ds_read_b128 v[214:217], v159 offset:3072
	ds_read_b128 v[218:221], v159 offset:4096
	ds_read_b128 v[222:225], v159 offset:5120
	ds_read_b128 v[226:229], v159 offset:6144
	ds_read_b128 v[230:233], v159 offset:7168
	global_load_lds_dwordx4 v[156:157], off
	v_lshl_add_u64 v[156:157], s[12:13], 0, v[144:145]
	s_mov_b32 m0, s71
	s_nop 0
	global_load_lds_dwordx4 v[156:157], off
	s_waitcnt vmcnt(8)
	s_waitcnt lgkmcnt(0)
	s_barrier
	s_waitcnt lgkmcnt(0)
	v_mfma_f32_16x16x32_bf16 v[124:127], v[128:131], v[202:205], v[124:127]
	v_mfma_f32_16x16x32_bf16 v[120:123], v[152:155], v[202:205], v[120:123]
	v_mfma_f32_16x16x32_bf16 v[108:111], v[128:131], v[210:213], v[108:111]
	v_mfma_f32_16x16x32_bf16 v[104:107], v[152:155], v[210:213], v[104:107]
	v_mfma_f32_16x16x32_bf16 v[92:95], v[128:131], v[218:221], v[92:95]
	v_mfma_f32_16x16x32_bf16 v[88:91], v[152:155], v[218:221], v[88:91]
	v_mfma_f32_16x16x32_bf16 v[76:79], v[128:131], v[226:229], v[76:79]
	v_mfma_f32_16x16x32_bf16 v[72:75], v[152:155], v[226:229], v[72:75]
	v_mfma_f32_16x16x32_bf16 v[124:127], v[132:135], v[206:209], v[124:127]
	v_mfma_f32_16x16x32_bf16 v[120:123], v[180:183], v[206:209], v[120:123]
	v_mfma_f32_16x16x32_bf16 v[108:111], v[132:135], v[214:217], v[108:111]
	v_mfma_f32_16x16x32_bf16 v[104:107], v[180:183], v[214:217], v[104:107]
	v_mfma_f32_16x16x32_bf16 v[92:95], v[132:135], v[222:225], v[92:95]
	v_mfma_f32_16x16x32_bf16 v[88:91], v[180:183], v[222:225], v[88:91]
	v_mfma_f32_16x16x32_bf16 v[76:79], v[132:135], v[230:233], v[76:79]
	v_mfma_f32_16x16x32_bf16 v[72:75], v[180:183], v[230:233], v[72:75]
	v_mfma_f32_16x16x32_bf16 v[116:119], v[186:189], v[202:205], v[116:119]
	v_mfma_f32_16x16x32_bf16 v[112:115], v[194:197], v[202:205], v[112:115]
	v_mfma_f32_16x16x32_bf16 v[100:103], v[186:189], v[210:213], v[100:103]
	v_mfma_f32_16x16x32_bf16 v[96:99], v[194:197], v[210:213], v[96:99]
	v_mfma_f32_16x16x32_bf16 v[84:87], v[186:189], v[218:221], v[84:87]
	v_mfma_f32_16x16x32_bf16 v[80:83], v[194:197], v[218:221], v[80:83]
	v_mfma_f32_16x16x32_bf16 v[68:71], v[186:189], v[226:229], v[68:71]
	v_mfma_f32_16x16x32_bf16 v[64:67], v[194:197], v[226:229], v[64:67]
	v_mfma_f32_16x16x32_bf16 v[116:119], v[190:193], v[206:209], v[116:119]
	v_mfma_f32_16x16x32_bf16 v[112:115], v[198:201], v[206:209], v[112:115]
	v_mfma_f32_16x16x32_bf16 v[100:103], v[190:193], v[214:217], v[100:103]
	v_mfma_f32_16x16x32_bf16 v[96:99], v[198:201], v[214:217], v[96:99]
	v_mfma_f32_16x16x32_bf16 v[84:87], v[190:193], v[222:225], v[84:87]
	v_mfma_f32_16x16x32_bf16 v[80:83], v[198:201], v[222:225], v[80:83]
	v_mfma_f32_16x16x32_bf16 v[68:71], v[190:193], v[230:233], v[68:71]
	v_mfma_f32_16x16x32_bf16 v[64:67], v[198:201], v[230:233], v[64:67]
	s_barrier
	s_mov_b32 m0, s54
	v_lshl_add_u64 v[156:157], s[48:49], 0, v[138:139]
	s_add_u32 s76, s48, 0x40000
	ds_read_b128 v[202:205], v159 offset:16384
	ds_read_b128 v[206:209], v159 offset:17408
	ds_read_b128 v[210:213], v159 offset:18432
	ds_read_b128 v[214:217], v159 offset:19456
	ds_read_b128 v[218:221], v159 offset:20480
	ds_read_b128 v[222:225], v159 offset:21504
	ds_read_b128 v[226:229], v159 offset:22528
	ds_read_b128 v[230:233], v159 offset:23552
	global_load_lds_dwordx4 v[156:157], off
	v_lshl_add_u64 v[234:235], s[48:49], 0, v[142:143]
	s_mov_b32 m0, s55
	s_addc_u32 s77, s49, 0
	global_load_lds_dwordx4 v[234:235], off
	v_lshl_add_u64 v[236:237], s[76:77], 0, v[138:139]
	s_mov_b32 m0, s56
	v_lshl_add_u64 v[238:239], s[50:51], 0, v[140:141]
	global_load_lds_dwordx4 v[236:237], off
	v_lshl_add_u64 v[236:237], s[76:77], 0, v[142:143]
	s_mov_b32 m0, s57
	s_nop 0
	global_load_lds_dwordx4 v[236:237], off
	v_lshl_add_u64 v[236:237], s[50:51], 0, v[136:137]
	s_mov_b32 m0, s53
	s_nop 0
	global_load_lds_dwordx4 v[236:237], off
	s_mov_b32 m0, s58
	s_nop 0
	global_load_lds_dwordx4 v[238:239], off
	s_waitcnt vmcnt(8)
	s_waitcnt lgkmcnt(0)
	s_barrier
	s_waitcnt lgkmcnt(0)
	v_mfma_f32_16x16x32_bf16 v[60:63], v[128:131], v[202:205], v[60:63]
	v_mfma_f32_16x16x32_bf16 v[56:59], v[152:155], v[202:205], v[56:59]
	v_mfma_f32_16x16x32_bf16 v[44:47], v[128:131], v[210:213], v[44:47]
	v_mfma_f32_16x16x32_bf16 v[40:43], v[152:155], v[210:213], v[40:43]
	v_mfma_f32_16x16x32_bf16 v[28:31], v[128:131], v[218:221], v[28:31]
	v_mfma_f32_16x16x32_bf16 v[24:27], v[152:155], v[218:221], v[24:27]
	v_mfma_f32_16x16x32_bf16 v[12:15], v[128:131], v[226:229], v[12:15]
	v_mfma_f32_16x16x32_bf16 v[8:11], v[152:155], v[226:229], v[8:11]
	v_mfma_f32_16x16x32_bf16 v[60:63], v[132:135], v[206:209], v[60:63]
	v_mfma_f32_16x16x32_bf16 v[56:59], v[180:183], v[206:209], v[56:59]
	v_mfma_f32_16x16x32_bf16 v[44:47], v[132:135], v[214:217], v[44:47]
	v_mfma_f32_16x16x32_bf16 v[40:43], v[180:183], v[214:217], v[40:43]
	v_mfma_f32_16x16x32_bf16 v[28:31], v[132:135], v[222:225], v[28:31]
	v_mfma_f32_16x16x32_bf16 v[24:27], v[180:183], v[222:225], v[24:27]
	v_mfma_f32_16x16x32_bf16 v[12:15], v[132:135], v[230:233], v[12:15]
	v_mfma_f32_16x16x32_bf16 v[8:11], v[180:183], v[230:233], v[8:11]
	v_mfma_f32_16x16x32_bf16 v[52:55], v[186:189], v[202:205], v[52:55]
	v_mfma_f32_16x16x32_bf16 v[48:51], v[194:197], v[202:205], v[48:51]
	v_mfma_f32_16x16x32_bf16 v[36:39], v[186:189], v[210:213], v[36:39]
	v_mfma_f32_16x16x32_bf16 v[32:35], v[194:197], v[210:213], v[32:35]
	v_mfma_f32_16x16x32_bf16 v[20:23], v[186:189], v[218:221], v[20:23]
	v_mfma_f32_16x16x32_bf16 v[16:19], v[194:197], v[218:221], v[16:19]
	v_mfma_f32_16x16x32_bf16 v[4:7], v[186:189], v[226:229], v[4:7]
	v_mfma_f32_16x16x32_bf16 v[0:3], v[194:197], v[226:229], v[0:3]
	v_mfma_f32_16x16x32_bf16 v[52:55], v[190:193], v[206:209], v[52:55]
	v_mfma_f32_16x16x32_bf16 v[48:51], v[198:201], v[206:209], v[48:51]
	v_mfma_f32_16x16x32_bf16 v[36:39], v[190:193], v[214:217], v[36:39]
	v_mfma_f32_16x16x32_bf16 v[32:35], v[198:201], v[214:217], v[32:35]
	v_mfma_f32_16x16x32_bf16 v[20:23], v[190:193], v[222:225], v[20:23]
	v_mfma_f32_16x16x32_bf16 v[16:19], v[198:201], v[222:225], v[16:19]
	v_mfma_f32_16x16x32_bf16 v[4:7], v[190:193], v[230:233], v[4:7]
	v_mfma_f32_16x16x32_bf16 v[0:3], v[198:201], v[230:233], v[0:3]
	s_barrier
; #define PG8_STAGE(bufoff, gbase, voff) do { _Pragma("unroll") for (int _i = 0; _i < 2; ++_i) \
;         __builtin_amdgcn_global_load_lds((const unsigned*)((const char*)(gbase) + (voff)[_i]), (PG8_LAS unsigned*)(lds + (bufoff) + ldsw + _i * 8192), 16, 0, 0); } while (0)
; #define PG8_LDA(dst, b, h) do { _Pragma("unroll") for (int m = 0; m < 4; ++m) _Pragma("unroll") for (int k = 0; k < 2; ++k) dst[m][k] = *(const PG8_LAS bf16x8*)(lds + PG8_SA(b, h) + aoff + m * 2048 + k * 1024); } while (0)
; #define PG8_LDB(dst, b, h) do { _Pragma("unroll") for (int n = 0; n < 2; ++n) _Pragma("unroll") for (int k = 0; k < 2; ++k) dst[n][k] = *(const PG8_LAS bf16x8*)(lds + PG8_SB(b, h) + boff + n * 2048 + k * 1024); } while (0)
; #define PG8_MMA(ai, bj, At, Bt) do { __builtin_amdgcn_s_setprio(1); _Pragma("unroll") for (int m = 0; m < 4; ++m) _Pragma("unroll") for (int n = 0; n < 2; ++n) _Pragma("unroll") for (int k = 0; k < 2; ++k) \
;         acc[ai][bj][m][n] = __builtin_amdgcn_mfma_f32_16x16x32_bf16(Bt[n][k], At[m][k], acc[ai][bj][m][n], 0, 0, 0); __builtin_amdgcn_s_setprio(0); } while (0)
; #define PG8_WAIT_V(n) asm volatile("s_waitcnt vmcnt(" #n ")" ::: "memory")
; #define PG8_WAIT_L(n) asm volatile("s_waitcnt lgkmcnt(" #n ")" ::: "memory")
; #define PG8_BAR __builtin_amdgcn_s_barrier()
; #define PG8_SCHED __builtin_amdgcn_sched_barrier(0)
; template <class Epi, class Sched, bool ALIGN_EPI = false, bool SP2 = false>
; __device__ __forceinline__ void gemm_phase(PG8_LAS unsigned char* lds, const Gemm g, const Sched& S, const Epi& E) {
;     ...
;             PG8_LDB(B0, 1, 0); PG8_LDB(B1, 1, 1); PG8_SCHED; PG8_LDA(At, 1, 0); PG8_STAGE(PG8_SA(0, 1), a2 + hstep, voffA);
;             PG8_WAIT_V(8); PG8_WAIT_L(0); PG8_BAR; PG8_MMA(0, 0, At, B0); PG8_MMA(0, 1, At, B1); PG8_BAR; PG8_SCHED;
;             PG8_LDA(At, 1, 1); PG8_STAGE(PG8_SB(1, 0), b3, voffB); PG8_STAGE(PG8_SB(1, 1), b3 + hstep, voffB); PG8_STAGE(PG8_SA(1, 0), a3, voffA);
;             PG8_WAIT_V(8); PG8_WAIT_L(0); PG8_BAR; PG8_MMA(1, 0, At, B0); PG8_MMA(1, 1, At, B1); PG8_BAR; PG8_SCHED;
	ds_read_b128 v[128:131], v169
	ds_read_b128 v[132:135], v170
	ds_read_b128 v[152:155], v171
	ds_read_b128 v[180:183], v172
	ds_read_b128 v[186:189], v173
	ds_read_b128 v[190:193], v174
	ds_read_b128 v[194:197], v175
	ds_read_b128 v[198:201], v176
	s_add_u32 s50, s50, 0x40000
	s_addc_u32 s51, s51, 0
	s_mov_b32 m0, s59
	v_lshl_add_u64 v[240:241], s[50:51], 0, v[136:137]
	ds_read_b128 v[202:205], v159 offset:32768
	ds_read_b128 v[206:209], v159 offset:33792
	ds_read_b128 v[210:213], v159 offset:34816
	ds_read_b128 v[214:217], v159 offset:35840
	ds_read_b128 v[218:221], v159 offset:36864
	ds_read_b128 v[222:225], v159 offset:37888
	ds_read_b128 v[226:229], v159 offset:38912
	ds_read_b128 v[230:233], v159 offset:39936
	global_load_lds_dwordx4 v[240:241], off
	v_lshl_add_u64 v[240:241], s[50:51], 0, v[140:141]
	s_mov_b32 m0, s60
	s_nop 0
	global_load_lds_dwordx4 v[240:241], off
	s_waitcnt vmcnt(8)
	s_waitcnt lgkmcnt(0)
	s_barrier
	s_waitcnt lgkmcnt(0)
	v_mfma_f32_16x16x32_bf16 v[124:127], v[128:131], v[202:205], v[124:127]
	v_mfma_f32_16x16x32_bf16 v[120:123], v[152:155], v[202:205], v[120:123]
	v_mfma_f32_16x16x32_bf16 v[108:111], v[128:131], v[210:213], v[108:111]
	v_mfma_f32_16x16x32_bf16 v[104:107], v[152:155], v[210:213], v[104:107]
	v_mfma_f32_16x16x32_bf16 v[92:95], v[128:131], v[218:221], v[92:95]
	v_mfma_f32_16x16x32_bf16 v[88:91], v[152:155], v[218:221], v[88:91]
	v_mfma_f32_16x16x32_bf16 v[76:79], v[128:131], v[226:229], v[76:79]
	v_mfma_f32_16x16x32_bf16 v[72:75], v[152:155], v[226:229], v[72:75]
	v_mfma_f32_16x16x32_bf16 v[124:127], v[132:135], v[206:209], v[124:127]
	v_mfma_f32_16x16x32_bf16 v[120:123], v[180:183], v[206:209], v[120:123]
	v_mfma_f32_16x16x32_bf16 v[108:111], v[132:135], v[214:217], v[108:111]
	v_mfma_f32_16x16x32_bf16 v[104:107], v[180:183], v[214:217], v[104:107]
	v_mfma_f32_16x16x32_bf16 v[92:95], v[132:135], v[222:225], v[92:95]
	v_mfma_f32_16x16x32_bf16 v[88:91], v[180:183], v[222:225], v[88:91]
	v_mfma_f32_16x16x32_bf16 v[76:79], v[132:135], v[230:233], v[76:79]
	v_mfma_f32_16x16x32_bf16 v[72:75], v[180:183], v[230:233], v[72:75]
	v_mfma_f32_16x16x32_bf16 v[116:119], v[186:189], v[202:205], v[116:119]
	v_mfma_f32_16x16x32_bf16 v[112:115], v[194:197], v[202:205], v[112:115]
	v_mfma_f32_16x16x32_bf16 v[100:103], v[186:189], v[210:213], v[100:103]
	v_mfma_f32_16x16x32_bf16 v[96:99], v[194:197], v[210:213], v[96:99]
	v_mfma_f32_16x16x32_bf16 v[84:87], v[186:189], v[218:221], v[84:87]
	v_mfma_f32_16x16x32_bf16 v[80:83], v[194:197], v[218:221], v[80:83]
	v_mfma_f32_16x16x32_bf16 v[68:71], v[186:189], v[226:229], v[68:71]
	v_mfma_f32_16x16x32_bf16 v[64:67], v[194:197], v[226:229], v[64:67]
	v_mfma_f32_16x16x32_bf16 v[116:119], v[190:193], v[206:209], v[116:119]
	v_mfma_f32_16x16x32_bf16 v[112:115], v[198:201], v[206:209], v[112:115]
	v_mfma_f32_16x16x32_bf16 v[100:103], v[190:193], v[214:217], v[100:103]
	v_mfma_f32_16x16x32_bf16 v[96:99], v[198:201], v[214:217], v[96:99]
	v_mfma_f32_16x16x32_bf16 v[84:87], v[190:193], v[222:225], v[84:87]
	v_mfma_f32_16x16x32_bf16 v[80:83], v[198:201], v[222:225], v[80:83]
	v_mfma_f32_16x16x32_bf16 v[68:71], v[190:193], v[230:233], v[68:71]
	v_mfma_f32_16x16x32_bf16 v[64:67], v[198:201], v[230:233], v[64:67]
	s_barrier
	s_mov_b32 m0, s62
	v_lshl_add_u64 v[156:157], v[156:157], 0, s[28:29]
	s_add_u32 s48, s48, 0x40080
	ds_read_b128 v[202:205], v159 offset:49152
	ds_read_b128 v[206:209], v159 offset:50176
	ds_read_b128 v[210:213], v159 offset:51200
	ds_read_b128 v[214:217], v159 offset:52224
	ds_read_b128 v[218:221], v159 offset:53248
	ds_read_b128 v[222:225], v159 offset:54272
	ds_read_b128 v[226:229], v159 offset:55296
	ds_read_b128 v[230:233], v159 offset:56320
	global_load_lds_dwordx4 v[156:157], off
	v_lshl_add_u64 v[156:157], v[234:235], 0, s[28:29]
	s_mov_b32 m0, s63
	s_addc_u32 s49, s49, 0
	global_load_lds_dwordx4 v[156:157], off
	v_lshl_add_u64 v[156:157], s[48:49], 0, v[138:139]
	s_mov_b32 m0, s66
	s_nop 0
	global_load_lds_dwordx4 v[156:157], off
	v_lshl_add_u64 v[156:157], s[48:49], 0, v[142:143]
	s_mov_b32 m0, s67
	s_nop 0
	global_load_lds_dwordx4 v[156:157], off
	v_lshl_add_u64 v[156:157], v[236:237], 0, s[28:29]
	s_mov_b32 m0, s64
	s_nop 0
	global_load_lds_dwordx4 v[156:157], off
	v_lshl_add_u64 v[156:157], v[238:239], 0, s[28:29]
	s_mov_b32 m0, s65
	s_nop 0
	global_load_lds_dwordx4 v[156:157], off
	s_waitcnt vmcnt(8)
	s_waitcnt lgkmcnt(0)
	s_barrier
	s_waitcnt lgkmcnt(0)
	v_mfma_f32_16x16x32_bf16 v[60:63], v[128:131], v[202:205], v[60:63]
	v_mfma_f32_16x16x32_bf16 v[56:59], v[152:155], v[202:205], v[56:59]
	v_mfma_f32_16x16x32_bf16 v[44:47], v[128:131], v[210:213], v[44:47]
	v_mfma_f32_16x16x32_bf16 v[40:43], v[152:155], v[210:213], v[40:43]
	v_mfma_f32_16x16x32_bf16 v[28:31], v[128:131], v[218:221], v[28:31]
	v_mfma_f32_16x16x32_bf16 v[24:27], v[152:155], v[218:221], v[24:27]
	v_mfma_f32_16x16x32_bf16 v[12:15], v[128:131], v[226:229], v[12:15]
	v_mfma_f32_16x16x32_bf16 v[8:11], v[152:155], v[226:229], v[8:11]
	v_mfma_f32_16x16x32_bf16 v[60:63], v[132:135], v[206:209], v[60:63]
	v_mfma_f32_16x16x32_bf16 v[56:59], v[180:183], v[206:209], v[56:59]
	v_mfma_f32_16x16x32_bf16 v[44:47], v[132:135], v[214:217], v[44:47]
	v_mfma_f32_16x16x32_bf16 v[40:43], v[180:183], v[214:217], v[40:43]
	v_mfma_f32_16x16x32_bf16 v[28:31], v[132:135], v[222:225], v[28:31]
	v_mfma_f32_16x16x32_bf16 v[24:27], v[180:183], v[222:225], v[24:27]
	v_mfma_f32_16x16x32_bf16 v[12:15], v[132:135], v[230:233], v[12:15]
	v_mfma_f32_16x16x32_bf16 v[8:11], v[180:183], v[230:233], v[8:11]
	v_mfma_f32_16x16x32_bf16 v[52:55], v[186:189], v[202:205], v[52:55]
	v_mfma_f32_16x16x32_bf16 v[48:51], v[194:197], v[202:205], v[48:51]
	v_mfma_f32_16x16x32_bf16 v[36:39], v[186:189], v[210:213], v[36:39]
	v_mfma_f32_16x16x32_bf16 v[32:35], v[194:197], v[210:213], v[32:35]
	v_mfma_f32_16x16x32_bf16 v[20:23], v[186:189], v[218:221], v[20:23]
	v_mfma_f32_16x16x32_bf16 v[16:19], v[194:197], v[218:221], v[16:19]
	v_mfma_f32_16x16x32_bf16 v[4:7], v[186:189], v[226:229], v[4:7]
	v_mfma_f32_16x16x32_bf16 v[0:3], v[194:197], v[226:229], v[0:3]
	v_mfma_f32_16x16x32_bf16 v[52:55], v[190:193], v[206:209], v[52:55]
	v_mfma_f32_16x16x32_bf16 v[48:51], v[198:201], v[206:209], v[48:51]
	v_mfma_f32_16x16x32_bf16 v[36:39], v[190:193], v[214:217], v[36:39]
	v_mfma_f32_16x16x32_bf16 v[32:35], v[198:201], v[214:217], v[32:35]
	v_mfma_f32_16x16x32_bf16 v[20:23], v[190:193], v[222:225], v[20:23]
	v_mfma_f32_16x16x32_bf16 v[16:19], v[198:201], v[222:225], v[16:19]
	v_mfma_f32_16x16x32_bf16 v[4:7], v[190:193], v[230:233], v[4:7]
	v_mfma_f32_16x16x32_bf16 v[0:3], v[198:201], v[230:233], v[0:3]
	s_barrier
	s_add_i32 s75, s75, 2
	s_add_u32 s43, s43, 0x100
	s_addc_u32 s74, s74, 0
	s_add_u32 s12, s12, 0x100
	s_addc_u32 s13, s13, 0
	s_cmp_gt_u32 s75, 13
	s_cbranch_scc0 .LBB0_1744
	s_and_b64 vcc, exec, s[30:31]
	s_cbranch_vccz .LBB0_1747
	s_barrier
